# speedup vs baseline: 1.0035x; 1.0035x over previous
; #define STAGE(P, BASE, br, kt) do { const char* _gb = (const char*)((BASE) + ((long)(br) * K + (long)(kt) * BK)); \
;     __builtin_amdgcn_global_load_lds((const unsigned*)(_gb + (size_t)so0), (unsigned*)((char*)(P) + wv1k), 16, 0, 0); \
;     __builtin_amdgcn_global_load_lds((const unsigned*)(_gb + (size_t)so1), (unsigned*)((char*)(P) + wv1k + 8192), 16, 0, 0); } while (0)
; #define LDA(dst, b, h) _Pragma("unroll") for (int m = 0; m < 4; ++m) _Pragma("unroll") for (int k = 0; k < 2; ++k) \
;     dst[m][k] = *reinterpret_cast<const bf16x8*>((char*)SA(b, h) + lds_byte(wr * 64 + m * 16 + fr, k * 32 + fq * 8))
; #define LDB(dst, b, h) _Pragma("unroll") for (int n = 0; n < 2; ++n) _Pragma("unroll") for (int k = 0; k < 2; ++k) \
;     dst[n][k] = *reinterpret_cast<const bf16x8*>((char*)SB(b, h) + lds_byte(wc * 32 + n * 16 + fr, k * 32 + fq * 8))
; #define MMA(ai, bj, At_, Bt_) do { __builtin_amdgcn_s_setprio(1); \
;     _Pragma("unroll") for (int m = 0; m < 4; ++m) _Pragma("unroll") for (int n = 0; n < 2; ++n) _Pragma("unroll") for (int k = 0; k < 2; ++k) \
;       acc[ai][bj][m][n] = __builtin_amdgcn_mfma_f32_16x16x32_bf16(At_[m][k], Bt_[n][k], acc[ai][bj][m][n], 0, 0, 0); \
;     __builtin_amdgcn_s_setprio(0); } while (0)
; #define WAIT_V(n) asm volatile("s_waitcnt vmcnt(" #n ")" ::: "memory")
; #define WAIT_L(n) asm volatile("s_waitcnt lgkmcnt(" #n ")" ::: "memory")
; #define BAR __builtin_amdgcn_s_barrier()
; #define SCHED __builtin_amdgcn_sched_barrier(0)
; template <class Epi> ...
;     ...
;   for (int t = 0; t < nt - 2; t += 2) {
;     LDB(B0, 0, 0); SCHED; LDA(At, 0, 0); STAGE(SA(1, 1), A, brow + HALF, t + 1);
;     WAIT_L(8); BAR; WAIT_L(0); MMA(0, 0, At, B0); BAR; SCHED;
;     LDB(B1, 0, 1); STAGE(SB(0, 0), Bt, bcol, t + 2);
;     BAR; WAIT_L(0); MMA(0, 1, At, B1); BAR;
;     LDA(At, 0, 1); STAGE(SA(0, 0), A, brow, t + 2);
;     BAR; WAIT_L(0); MMA(1, 0, At, B0); BAR; SCHED;
;     STAGE(SB(0, 1), Bt, bcol + HALF, t + 2);
;     WAIT_V(6); BAR; MMA(1, 1, At, B1); BAR;
.LBB0_65:
	ds_read_b128 v[162:165], v154
	ds_read_b128 v[166:169], v154 offset:1024
	ds_read_b128 v[170:173], v154 offset:2048
	ds_read_b128 v[174:177], v154 offset:3072
	v_lshl_add_u64 v[210:211], v[146:147], 0, s[22:23]
	s_add_i32 s46, s31, 0xc000
	v_lshl_add_u64 v[212:213], v[210:211], 0, s[50:51]
	s_mov_b32 m0, s46
	ds_read_b128 v[178:181], v155
	ds_read_b128 v[182:185], v155 offset:1024
	ds_read_b128 v[186:189], v156
	ds_read_b128 v[190:193], v156 offset:1024
	ds_read_b128 v[194:197], v157
	ds_read_b128 v[198:201], v157 offset:1024
	ds_read_b128 v[202:205], v158
	ds_read_b128 v[206:209], v158 offset:1024
	global_load_lds_dwordx4 v[212:213], off
	v_lshl_add_u64 v[212:213], v[144:145], 0, s[22:23]
	s_add_i32 s25, s31, 0xe000
	v_lshl_add_u64 v[214:215], v[212:213], 0, s[50:51]
	s_mov_b32 m0, s25
	s_nop 0
	global_load_lds_dwordx4 v[214:215], off
	s_waitcnt lgkmcnt(8)
	s_barrier
	s_waitcnt lgkmcnt(0)
	v_mfma_f32_16x16x32_bf16 v[126:129], v[178:181], v[162:165], v[126:129]
	v_mfma_f32_16x16x32_bf16 v[122:125], v[178:181], v[170:173], v[122:125]
	v_mfma_f32_16x16x32_bf16 v[118:121], v[186:189], v[162:165], v[118:121]
	v_mfma_f32_16x16x32_bf16 v[114:117], v[186:189], v[170:173], v[114:117]
	v_mfma_f32_16x16x32_bf16 v[110:113], v[194:197], v[162:165], v[110:113]
	v_mfma_f32_16x16x32_bf16 v[106:109], v[194:197], v[170:173], v[106:109]
	v_mfma_f32_16x16x32_bf16 v[102:105], v[202:205], v[162:165], v[102:105]
	v_mfma_f32_16x16x32_bf16 v[98:101], v[202:205], v[170:173], v[98:101]
	v_mfma_f32_16x16x32_bf16 v[126:129], v[182:185], v[166:169], v[126:129]
	v_mfma_f32_16x16x32_bf16 v[122:125], v[182:185], v[174:177], v[122:125]
	v_mfma_f32_16x16x32_bf16 v[118:121], v[190:193], v[166:169], v[118:121]
	v_mfma_f32_16x16x32_bf16 v[114:117], v[190:193], v[174:177], v[114:117]
	v_mfma_f32_16x16x32_bf16 v[110:113], v[198:201], v[166:169], v[110:113]
	v_mfma_f32_16x16x32_bf16 v[106:109], v[198:201], v[174:177], v[106:109]
	v_mfma_f32_16x16x32_bf16 v[102:105], v[206:209], v[166:169], v[102:105]
	v_mfma_f32_16x16x32_bf16 v[98:101], v[206:209], v[174:177], v[98:101]
	s_barrier
	v_lshl_add_u64 v[214:215], v[152:153], 0, s[22:23]
	s_mov_b32 m0, s34
	v_lshl_add_u64 v[216:217], v[214:215], 0, s[0:1]
	ds_read_b128 v[236:239], v159
	ds_read_b128 v[240:243], v159 offset:1024
	ds_read_b128 v[244:247], v159 offset:2048
	ds_read_b128 v[248:251], v159 offset:3072
	global_load_lds_dwordx4 v[216:217], off
	v_lshl_add_u64 v[216:217], v[148:149], 0, s[22:23]
	v_lshl_add_u64 v[218:219], v[216:217], 0, s[0:1]
	s_mov_b32 m0, s35
	s_nop 0
	global_load_lds_dwordx4 v[218:219], off
	s_barrier
	s_waitcnt lgkmcnt(0)
	v_mfma_f32_16x16x32_bf16 v[94:97], v[178:181], v[236:239], v[94:97]
	v_mfma_f32_16x16x32_bf16 v[90:93], v[178:181], v[244:247], v[90:93]
	v_mfma_f32_16x16x32_bf16 v[86:89], v[186:189], v[236:239], v[86:89]
	v_mfma_f32_16x16x32_bf16 v[82:85], v[186:189], v[244:247], v[82:85]
	v_mfma_f32_16x16x32_bf16 v[78:81], v[194:197], v[236:239], v[78:81]
	v_mfma_f32_16x16x32_bf16 v[74:77], v[194:197], v[244:247], v[74:77]
	v_mfma_f32_16x16x32_bf16 v[70:73], v[202:205], v[236:239], v[70:73]
	v_mfma_f32_16x16x32_bf16 v[66:69], v[202:205], v[244:247], v[66:69]
	v_mfma_f32_16x16x32_bf16 v[94:97], v[182:185], v[240:243], v[94:97]
	v_mfma_f32_16x16x32_bf16 v[90:93], v[182:185], v[248:251], v[90:93]
	v_mfma_f32_16x16x32_bf16 v[86:89], v[190:193], v[240:243], v[86:89]
	v_mfma_f32_16x16x32_bf16 v[82:85], v[190:193], v[248:251], v[82:85]
	v_mfma_f32_16x16x32_bf16 v[78:81], v[198:201], v[240:243], v[78:81]
	v_mfma_f32_16x16x32_bf16 v[74:77], v[198:201], v[248:251], v[74:77]
	v_mfma_f32_16x16x32_bf16 v[70:73], v[206:209], v[240:243], v[70:73]
	v_mfma_f32_16x16x32_bf16 v[66:69], v[206:209], v[248:251], v[66:69]
	s_mov_b32 m0, s31
	v_lshl_add_u64 v[218:219], v[210:211], 0, s[0:1]
	s_barrier
	ds_read_b128 v[178:181], v155 offset:16384
	ds_read_b128 v[182:185], v155 offset:17408
	ds_read_b128 v[186:189], v156 offset:16384
	ds_read_b128 v[190:193], v156 offset:17408
	ds_read_b128 v[194:197], v157 offset:16384
	ds_read_b128 v[198:201], v157 offset:17408
	ds_read_b128 v[202:205], v158 offset:16384
	ds_read_b128 v[206:209], v158 offset:17408
	global_load_lds_dwordx4 v[218:219], off
	v_lshl_add_u64 v[218:219], v[212:213], 0, s[0:1]
	s_mov_b32 m0, s21
	s_nop 0
	global_load_lds_dwordx4 v[218:219], off
	s_barrier
	s_waitcnt lgkmcnt(0)
	v_mfma_f32_16x16x32_bf16 v[62:65], v[178:181], v[162:165], v[62:65]
	v_mfma_f32_16x16x32_bf16 v[58:61], v[178:181], v[170:173], v[58:61]
	v_mfma_f32_16x16x32_bf16 v[54:57], v[186:189], v[162:165], v[54:57]
	v_mfma_f32_16x16x32_bf16 v[50:53], v[186:189], v[170:173], v[50:53]
	v_mfma_f32_16x16x32_bf16 v[46:49], v[194:197], v[162:165], v[46:49]
	v_mfma_f32_16x16x32_bf16 v[42:45], v[194:197], v[170:173], v[42:45]
	v_mfma_f32_16x16x32_bf16 v[38:41], v[202:205], v[162:165], v[38:41]
	v_mfma_f32_16x16x32_bf16 v[34:37], v[202:205], v[170:173], v[34:37]
	v_mfma_f32_16x16x32_bf16 v[62:65], v[182:185], v[166:169], v[62:65]
	v_mfma_f32_16x16x32_bf16 v[58:61], v[182:185], v[174:177], v[58:61]
	v_mfma_f32_16x16x32_bf16 v[54:57], v[190:193], v[166:169], v[54:57]
	v_mfma_f32_16x16x32_bf16 v[50:53], v[190:193], v[174:177], v[50:53]
	v_mfma_f32_16x16x32_bf16 v[46:49], v[198:201], v[166:169], v[46:49]
	v_mfma_f32_16x16x32_bf16 v[42:45], v[198:201], v[174:177], v[42:45]
	v_mfma_f32_16x16x32_bf16 v[38:41], v[206:209], v[166:169], v[38:41]
	v_mfma_f32_16x16x32_bf16 v[34:37], v[206:209], v[174:177], v[34:37]
	s_barrier
	s_mov_b32 m0, s38
	v_lshl_add_u64 v[162:163], v[214:215], 0, s[52:53]
	global_load_lds_dwordx4 v[162:163], off
	v_lshl_add_u64 v[162:163], v[216:217], 0, s[52:53]
	s_mov_b32 m0, s39
	s_nop 0
	global_load_lds_dwordx4 v[162:163], off
	s_waitcnt vmcnt(6)
	s_barrier
; #define STAGE(P, BASE, br, kt) do { const char* _gb = (const char*)((BASE) + ((long)(br) * K + (long)(kt) * BK)); \
;     __builtin_amdgcn_global_load_lds((const unsigned*)(_gb + (size_t)so0), (unsigned*)((char*)(P) + wv1k), 16, 0, 0); \
;     __builtin_amdgcn_global_load_lds((const unsigned*)(_gb + (size_t)so1), (unsigned*)((char*)(P) + wv1k + 8192), 16, 0, 0); } while (0)
; #define LDA(dst, b, h) _Pragma("unroll") for (int m = 0; m < 4; ++m) _Pragma("unroll") for (int k = 0; k < 2; ++k) \
;     dst[m][k] = *reinterpret_cast<const bf16x8*>((char*)SA(b, h) + lds_byte(wr * 64 + m * 16 + fr, k * 32 + fq * 8))
; #define LDB(dst, b, h) _Pragma("unroll") for (int n = 0; n < 2; ++n) _Pragma("unroll") for (int k = 0; k < 2; ++k) \
;     dst[n][k] = *reinterpret_cast<const bf16x8*>((char*)SB(b, h) + lds_byte(wc * 32 + n * 16 + fr, k * 32 + fq * 8))
; #define MMA(ai, bj, At_, Bt_) do { __builtin_amdgcn_s_setprio(1); \
;     _Pragma("unroll") for (int m = 0; m < 4; ++m) _Pragma("unroll") for (int n = 0; n < 2; ++n) _Pragma("unroll") for (int k = 0; k < 2; ++k) \
;       acc[ai][bj][m][n] = __builtin_amdgcn_mfma_f32_16x16x32_bf16(At_[m][k], Bt_[n][k], acc[ai][bj][m][n], 0, 0, 0); \
;     __builtin_amdgcn_s_setprio(0); } while (0)
; #define WAIT_V(n) asm volatile("s_waitcnt vmcnt(" #n ")" ::: "memory")
; #define WAIT_L(n) asm volatile("s_waitcnt lgkmcnt(" #n ")" ::: "memory")
; #define BAR __builtin_amdgcn_s_barrier()
; #define SCHED __builtin_amdgcn_sched_barrier(0)
; template <class Epi> ...
;     ...
;     WAIT_V(6); BAR; MMA(1, 1, At, B1); BAR;
;     LDB(B0, 1, 0); SCHED; LDA(At, 1, 0); STAGE(SA(0, 1), A, brow + HALF, t + 2);
;     WAIT_L(8); BAR; WAIT_L(0); MMA(0, 0, At, B0); BAR; SCHED;
;     LDB(B1, 1, 1); STAGE(SB(1, 0), Bt, bcol, t + 3);
;     BAR; WAIT_L(0); MMA(0, 1, At, B1); BAR;
;     LDA(At, 1, 1); STAGE(SA(1, 0), A, brow, t + 3);
;     BAR; WAIT_L(0); MMA(1, 0, At, B0); BAR; SCHED;
	v_mfma_f32_16x16x32_bf16 v[30:33], v[178:181], v[236:239], v[30:33]
	v_mfma_f32_16x16x32_bf16 v[26:29], v[178:181], v[244:247], v[26:29]
	v_mfma_f32_16x16x32_bf16 v[22:25], v[186:189], v[236:239], v[22:25]
	v_mfma_f32_16x16x32_bf16 v[18:21], v[186:189], v[244:247], v[18:21]
	v_mfma_f32_16x16x32_bf16 v[14:17], v[194:197], v[236:239], v[14:17]
	v_mfma_f32_16x16x32_bf16 v[10:13], v[194:197], v[244:247], v[10:13]
	v_mfma_f32_16x16x32_bf16 v[6:9], v[202:205], v[236:239], v[6:9]
	v_mfma_f32_16x16x32_bf16 v[2:5], v[202:205], v[244:247], v[2:5]
	v_mfma_f32_16x16x32_bf16 v[30:33], v[182:185], v[240:243], v[30:33]
	v_mfma_f32_16x16x32_bf16 v[26:29], v[182:185], v[248:251], v[26:29]
	v_mfma_f32_16x16x32_bf16 v[22:25], v[190:193], v[240:243], v[22:25]
	v_mfma_f32_16x16x32_bf16 v[18:21], v[190:193], v[248:251], v[18:21]
	v_mfma_f32_16x16x32_bf16 v[14:17], v[198:201], v[240:243], v[14:17]
	v_mfma_f32_16x16x32_bf16 v[10:13], v[198:201], v[248:251], v[10:13]
	v_mfma_f32_16x16x32_bf16 v[6:9], v[206:209], v[240:243], v[6:9]
	v_mfma_f32_16x16x32_bf16 v[2:5], v[206:209], v[248:251], v[2:5]
	s_barrier
	ds_read_b128 v[162:165], v160
	ds_read_b128 v[166:169], v160 offset:1024
	ds_read_b128 v[170:173], v160 offset:2048
	ds_read_b128 v[174:177], v160 offset:3072
	s_mov_b32 m0, s40
	v_lshl_add_u64 v[218:219], v[210:211], 0, s[52:53]
	ds_read_b128 v[178:181], v155 offset:32768
	ds_read_b128 v[182:185], v155 offset:33792
	ds_read_b128 v[186:189], v156 offset:32768
	ds_read_b128 v[190:193], v156 offset:33792
	ds_read_b128 v[194:197], v157 offset:32768
	ds_read_b128 v[198:201], v157 offset:33792
	ds_read_b128 v[202:205], v158 offset:32768
	ds_read_b128 v[206:209], v158 offset:33792
	global_load_lds_dwordx4 v[218:219], off
	v_lshl_add_u64 v[218:219], v[212:213], 0, s[52:53]
	s_mov_b32 m0, s41
	s_nop 0
	global_load_lds_dwordx4 v[218:219], off
	s_waitcnt lgkmcnt(8)
	s_barrier
	s_waitcnt lgkmcnt(0)
	v_mfma_f32_16x16x32_bf16 v[126:129], v[178:181], v[162:165], v[126:129]
	v_mfma_f32_16x16x32_bf16 v[122:125], v[178:181], v[170:173], v[122:125]
	v_mfma_f32_16x16x32_bf16 v[118:121], v[186:189], v[162:165], v[118:121]
	v_mfma_f32_16x16x32_bf16 v[114:117], v[186:189], v[170:173], v[114:117]
	v_mfma_f32_16x16x32_bf16 v[110:113], v[194:197], v[162:165], v[110:113]
	v_mfma_f32_16x16x32_bf16 v[106:109], v[194:197], v[170:173], v[106:109]
	v_mfma_f32_16x16x32_bf16 v[102:105], v[202:205], v[162:165], v[102:105]
	v_mfma_f32_16x16x32_bf16 v[98:101], v[202:205], v[170:173], v[98:101]
	v_mfma_f32_16x16x32_bf16 v[126:129], v[182:185], v[166:169], v[126:129]
	v_mfma_f32_16x16x32_bf16 v[122:125], v[182:185], v[174:177], v[122:125]
	v_mfma_f32_16x16x32_bf16 v[118:121], v[190:193], v[166:169], v[118:121]
	v_mfma_f32_16x16x32_bf16 v[114:117], v[190:193], v[174:177], v[114:117]
	v_mfma_f32_16x16x32_bf16 v[110:113], v[198:201], v[166:169], v[110:113]
	v_mfma_f32_16x16x32_bf16 v[106:109], v[198:201], v[174:177], v[106:109]
	v_mfma_f32_16x16x32_bf16 v[102:105], v[206:209], v[166:169], v[102:105]
	v_mfma_f32_16x16x32_bf16 v[98:101], v[206:209], v[174:177], v[98:101]
	s_barrier
	s_mov_b32 m0, s26
	v_lshl_add_u64 v[218:219], v[214:215], 0, s[90:91]
	ds_read_b128 v[236:239], v161
	ds_read_b128 v[240:243], v161 offset:1024
	ds_read_b128 v[244:247], v161 offset:2048
	ds_read_b128 v[248:251], v161 offset:3072
	global_load_lds_dwordx4 v[218:219], off
	v_lshl_add_u64 v[218:219], v[216:217], 0, s[90:91]
	s_mov_b32 m0, s27
	s_nop 0
	global_load_lds_dwordx4 v[218:219], off
	s_barrier
	s_waitcnt lgkmcnt(0)
	v_mfma_f32_16x16x32_bf16 v[94:97], v[178:181], v[236:239], v[94:97]
	v_mfma_f32_16x16x32_bf16 v[90:93], v[178:181], v[244:247], v[90:93]
	v_mfma_f32_16x16x32_bf16 v[86:89], v[186:189], v[236:239], v[86:89]
	v_mfma_f32_16x16x32_bf16 v[82:85], v[186:189], v[244:247], v[82:85]
	v_mfma_f32_16x16x32_bf16 v[78:81], v[194:197], v[236:239], v[78:81]
	v_mfma_f32_16x16x32_bf16 v[74:77], v[194:197], v[244:247], v[74:77]
	v_mfma_f32_16x16x32_bf16 v[70:73], v[202:205], v[236:239], v[70:73]
	v_mfma_f32_16x16x32_bf16 v[66:69], v[202:205], v[244:247], v[66:69]
	v_mfma_f32_16x16x32_bf16 v[94:97], v[182:185], v[240:243], v[94:97]
	v_mfma_f32_16x16x32_bf16 v[90:93], v[182:185], v[248:251], v[90:93]
	v_mfma_f32_16x16x32_bf16 v[86:89], v[190:193], v[240:243], v[86:89]
	v_mfma_f32_16x16x32_bf16 v[82:85], v[190:193], v[248:251], v[82:85]
	v_mfma_f32_16x16x32_bf16 v[78:81], v[198:201], v[240:243], v[78:81]
	v_mfma_f32_16x16x32_bf16 v[74:77], v[198:201], v[248:251], v[74:77]
	v_mfma_f32_16x16x32_bf16 v[70:73], v[206:209], v[240:243], v[70:73]
	v_mfma_f32_16x16x32_bf16 v[66:69], v[206:209], v[248:251], v[66:69]
	s_mov_b32 m0, s42
	v_lshl_add_u64 v[210:211], v[210:211], 0, s[90:91]
	s_barrier
	ds_read_b128 v[178:181], v155 offset:49152
	ds_read_b128 v[182:185], v155 offset:50176
	ds_read_b128 v[186:189], v156 offset:49152
	ds_read_b128 v[190:193], v156 offset:50176
	ds_read_b128 v[194:197], v157 offset:49152
	ds_read_b128 v[198:201], v157 offset:50176
	ds_read_b128 v[202:205], v158 offset:49152
	ds_read_b128 v[206:209], v158 offset:50176
	global_load_lds_dwordx4 v[210:211], off
	v_lshl_add_u64 v[210:211], v[212:213], 0, s[90:91]
	s_mov_b32 m0, s43
	s_nop 0
	global_load_lds_dwordx4 v[210:211], off
	s_barrier
; #define STAGE(P, BASE, br, kt) do { const char* _gb = (const char*)((BASE) + ((long)(br) * K + (long)(kt) * BK)); \
;     __builtin_amdgcn_global_load_lds((const unsigned*)(_gb + (size_t)so0), (unsigned*)((char*)(P) + wv1k), 16, 0, 0); \
;     __builtin_amdgcn_global_load_lds((const unsigned*)(_gb + (size_t)so1), (unsigned*)((char*)(P) + wv1k + 8192), 16, 0, 0); } while (0)
; #define LDA(dst, b, h) _Pragma("unroll") for (int m = 0; m < 4; ++m) _Pragma("unroll") for (int k = 0; k < 2; ++k) \
;     dst[m][k] = *reinterpret_cast<const bf16x8*>((char*)SA(b, h) + lds_byte(wr * 64 + m * 16 + fr, k * 32 + fq * 8))
; #define LDB(dst, b, h) _Pragma("unroll") for (int n = 0; n < 2; ++n) _Pragma("unroll") for (int k = 0; k < 2; ++k) \
;     dst[n][k] = *reinterpret_cast<const bf16x8*>((char*)SB(b, h) + lds_byte(wc * 32 + n * 16 + fr, k * 32 + fq * 8))
; #define MMA(ai, bj, At_, Bt_) do { __builtin_amdgcn_s_setprio(1); \
;     _Pragma("unroll") for (int m = 0; m < 4; ++m) _Pragma("unroll") for (int n = 0; n < 2; ++n) _Pragma("unroll") for (int k = 0; k < 2; ++k) \
;       acc[ai][bj][m][n] = __builtin_amdgcn_mfma_f32_16x16x32_bf16(At_[m][k], Bt_[n][k], acc[ai][bj][m][n], 0, 0, 0); \
;     __builtin_amdgcn_s_setprio(0); } while (0)
; #define WAIT_V(n) asm volatile("s_waitcnt vmcnt(" #n ")" ::: "memory")
; #define WAIT_L(n) asm volatile("s_waitcnt lgkmcnt(" #n ")" ::: "memory")
; #define BAR __builtin_amdgcn_s_barrier()
; #define SCHED __builtin_amdgcn_sched_barrier(0)
; template <class Epi> ...
;     ...
;     BAR; WAIT_L(0); MMA(1, 0, At, B0); BAR; SCHED;
;     STAGE(SB(1, 1), Bt, bcol + HALF, t + 3);
;     WAIT_V(6); BAR; MMA(1, 1, At, B1); BAR;
;   }
;   { LDB(B0, 0, 0); LDA(At, 0, 0); STAGE(SA(1, 1), A, brow + HALF, nt - 1);
;     BAR; WAIT_L(0); MMA(0, 0, At, B0); BAR;
;     LDB(B1, 0, 1); BAR; WAIT_L(0); MMA(0, 1, At, B1); BAR;
	s_waitcnt lgkmcnt(0)
	v_mfma_f32_16x16x32_bf16 v[62:65], v[178:181], v[162:165], v[62:65]
	v_mfma_f32_16x16x32_bf16 v[58:61], v[178:181], v[170:173], v[58:61]
	v_mfma_f32_16x16x32_bf16 v[54:57], v[186:189], v[162:165], v[54:57]
	v_mfma_f32_16x16x32_bf16 v[50:53], v[186:189], v[170:173], v[50:53]
	v_mfma_f32_16x16x32_bf16 v[46:49], v[194:197], v[162:165], v[46:49]
	v_mfma_f32_16x16x32_bf16 v[42:45], v[194:197], v[170:173], v[42:45]
	v_mfma_f32_16x16x32_bf16 v[38:41], v[202:205], v[162:165], v[38:41]
	v_mfma_f32_16x16x32_bf16 v[34:37], v[202:205], v[170:173], v[34:37]
	v_mfma_f32_16x16x32_bf16 v[62:65], v[182:185], v[166:169], v[62:65]
	v_mfma_f32_16x16x32_bf16 v[58:61], v[182:185], v[174:177], v[58:61]
	v_mfma_f32_16x16x32_bf16 v[54:57], v[190:193], v[166:169], v[54:57]
	v_mfma_f32_16x16x32_bf16 v[50:53], v[190:193], v[174:177], v[50:53]
	v_mfma_f32_16x16x32_bf16 v[46:49], v[198:201], v[166:169], v[46:49]
	v_mfma_f32_16x16x32_bf16 v[42:45], v[198:201], v[174:177], v[42:45]
	v_mfma_f32_16x16x32_bf16 v[38:41], v[206:209], v[166:169], v[38:41]
	v_mfma_f32_16x16x32_bf16 v[34:37], v[206:209], v[174:177], v[34:37]
	s_barrier
	s_mov_b32 m0, s44
	v_lshl_add_u64 v[162:163], v[214:215], 0, s[54:55]
	global_load_lds_dwordx4 v[162:163], off
	v_lshl_add_u64 v[162:163], v[216:217], 0, s[54:55]
	s_mov_b32 m0, s45
	s_nop 0
	global_load_lds_dwordx4 v[162:163], off
	s_waitcnt vmcnt(6)
	s_barrier
	v_mfma_f32_16x16x32_bf16 v[30:33], v[178:181], v[236:239], v[30:33]
	v_mfma_f32_16x16x32_bf16 v[26:29], v[178:181], v[244:247], v[26:29]
	v_mfma_f32_16x16x32_bf16 v[22:25], v[186:189], v[236:239], v[22:25]
	v_mfma_f32_16x16x32_bf16 v[18:21], v[186:189], v[244:247], v[18:21]
	v_mfma_f32_16x16x32_bf16 v[14:17], v[194:197], v[236:239], v[14:17]
	v_mfma_f32_16x16x32_bf16 v[10:13], v[194:197], v[244:247], v[10:13]
	v_mfma_f32_16x16x32_bf16 v[6:9], v[202:205], v[236:239], v[6:9]
	v_mfma_f32_16x16x32_bf16 v[2:5], v[202:205], v[244:247], v[2:5]
	v_mfma_f32_16x16x32_bf16 v[30:33], v[182:185], v[240:243], v[30:33]
	v_mfma_f32_16x16x32_bf16 v[26:29], v[182:185], v[248:251], v[26:29]
	v_mfma_f32_16x16x32_bf16 v[22:25], v[190:193], v[240:243], v[22:25]
	v_mfma_f32_16x16x32_bf16 v[18:21], v[190:193], v[248:251], v[18:21]
	v_mfma_f32_16x16x32_bf16 v[14:17], v[198:201], v[240:243], v[14:17]
	v_mfma_f32_16x16x32_bf16 v[10:13], v[198:201], v[248:251], v[10:13]
	v_mfma_f32_16x16x32_bf16 v[6:9], v[206:209], v[240:243], v[6:9]
	v_mfma_f32_16x16x32_bf16 v[2:5], v[206:209], v[248:251], v[2:5]
	s_add_i32 s24, s24, 2
	s_add_u32 s22, s22, 0x100
	s_addc_u32 s23, s23, 0
	s_cmp_lt_u32 s24, 12
	s_barrier
	s_cbranch_scc1 .LBB0_65
	s_mov_b64 s[22:23], 0x780
	s_mov_b32 m0, s46
	v_lshl_add_u64 v[140:141], v[140:141], 0, s[22:23]
	ds_read_b128 v[144:147], v154
	ds_read_b128 v[162:165], v154 offset:1024
	ds_read_b128 v[166:169], v154 offset:2048
	ds_read_b128 v[170:173], v154 offset:3072
	ds_read_b128 v[174:177], v155
	ds_read_b128 v[178:181], v155 offset:1024
	ds_read_b128 v[182:185], v156
	ds_read_b128 v[186:189], v156 offset:1024
	ds_read_b128 v[190:193], v157
	ds_read_b128 v[194:197], v157 offset:1024
	ds_read_b128 v[198:201], v158
	ds_read_b128 v[202:205], v158 offset:1024
	global_load_lds_dwordx4 v[140:141], off
	v_lshl_add_u64 v[140:141], v[142:143], 0, s[22:23]
	s_mov_b32 m0, s25
	s_nop 0
	global_load_lds_dwordx4 v[140:141], off
	s_barrier
	s_waitcnt lgkmcnt(0)
	v_mfma_f32_16x16x32_bf16 v[126:129], v[174:177], v[144:147], v[126:129]
	v_mfma_f32_16x16x32_bf16 v[122:125], v[174:177], v[166:169], v[122:125]
	v_mfma_f32_16x16x32_bf16 v[118:121], v[182:185], v[144:147], v[118:121]
	v_mfma_f32_16x16x32_bf16 v[106:109], v[190:193], v[166:169], v[106:109]
	v_mfma_f32_16x16x32_bf16 v[102:105], v[198:201], v[144:147], v[102:105]
	v_mfma_f32_16x16x32_bf16 v[126:129], v[178:181], v[162:165], v[126:129]
	v_mfma_f32_16x16x32_bf16 v[122:125], v[178:181], v[170:173], v[122:125]
	v_mfma_f32_16x16x32_bf16 v[118:121], v[186:189], v[162:165], v[118:121]
	v_mfma_f32_16x16x32_bf16 v[114:117], v[182:185], v[166:169], v[114:117]
	v_mfma_f32_16x16x32_bf16 v[110:113], v[190:193], v[144:147], v[110:113]
	v_mfma_f32_16x16x32_bf16 v[106:109], v[194:197], v[170:173], v[106:109]
	v_mfma_f32_16x16x32_bf16 v[102:105], v[202:205], v[162:165], v[102:105]
	v_mfma_f32_16x16x32_bf16 v[98:101], v[198:201], v[166:169], v[98:101]
	v_mfma_f32_16x16x32_bf16 v[140:143], v[186:189], v[170:173], v[114:117]
	v_mfma_f32_16x16x32_bf16 v[206:209], v[194:197], v[162:165], v[110:113]
	v_mfma_f32_16x16x32_bf16 v[236:239], v[202:205], v[170:173], v[98:101]
	s_barrier
	s_nop 2
	ds_read_b128 v[98:101], v159
	ds_read_b128 v[110:113], v159 offset:1024
	ds_read_b128 v[114:117], v159 offset:2048
	ds_read_b128 v[240:243], v159 offset:3072
	s_barrier
	s_waitcnt lgkmcnt(0)
	v_mfma_f32_16x16x32_bf16 v[90:93], v[174:177], v[114:117], v[90:93]
	v_mfma_f32_16x16x32_bf16 v[86:89], v[182:185], v[98:101], v[86:89]
	v_mfma_f32_16x16x32_bf16 v[74:77], v[190:193], v[114:117], v[74:77]
	v_mfma_f32_16x16x32_bf16 v[70:73], v[198:201], v[98:101], v[70:73]
	v_mfma_f32_16x16x32_bf16 v[94:97], v[174:177], v[98:101], v[94:97]
	v_mfma_f32_16x16x32_bf16 v[90:93], v[178:181], v[240:243], v[90:93]
	v_mfma_f32_16x16x32_bf16 v[86:89], v[186:189], v[110:113], v[86:89]
	v_mfma_f32_16x16x32_bf16 v[82:85], v[182:185], v[114:117], v[82:85]
	v_mfma_f32_16x16x32_bf16 v[78:81], v[190:193], v[98:101], v[78:81]
	v_mfma_f32_16x16x32_bf16 v[74:77], v[194:197], v[240:243], v[74:77]
	v_mfma_f32_16x16x32_bf16 v[70:73], v[202:205], v[110:113], v[70:73]
	v_mfma_f32_16x16x32_bf16 v[66:69], v[198:201], v[114:117], v[66:69]
	v_mfma_f32_16x16x32_bf16 v[244:247], v[178:181], v[110:113], v[94:97]
	v_mfma_f32_16x16x32_bf16 v[174:177], v[186:189], v[240:243], v[82:85]
	v_mfma_f32_16x16x32_bf16 v[178:181], v[194:197], v[110:113], v[78:81]
	v_mfma_f32_16x16x32_bf16 v[182:185], v[202:205], v[240:243], v[66:69]
	s_barrier
; #define LDA(dst, b, h) _Pragma("unroll") for (int m = 0; m < 4; ++m) _Pragma("unroll") for (int k = 0; k < 2; ++k) \
;     dst[m][k] = *reinterpret_cast<const bf16x8*>((char*)SA(b, h) + lds_byte(wr * 64 + m * 16 + fr, k * 32 + fq * 8))
; #define LDB(dst, b, h) _Pragma("unroll") for (int n = 0; n < 2; ++n) _Pragma("unroll") for (int k = 0; k < 2; ++k) \
;     dst[n][k] = *reinterpret_cast<const bf16x8*>((char*)SB(b, h) + lds_byte(wc * 32 + n * 16 + fr, k * 32 + fq * 8))
; #define MMA(ai, bj, At_, Bt_) do { __builtin_amdgcn_s_setprio(1); \
;     _Pragma("unroll") for (int m = 0; m < 4; ++m) _Pragma("unroll") for (int n = 0; n < 2; ++n) _Pragma("unroll") for (int k = 0; k < 2; ++k) \
;       acc[ai][bj][m][n] = __builtin_amdgcn_mfma_f32_16x16x32_bf16(At_[m][k], Bt_[n][k], acc[ai][bj][m][n], 0, 0, 0); \
;     __builtin_amdgcn_s_setprio(0); } while (0)
; #define WAIT_V(n) asm volatile("s_waitcnt vmcnt(" #n ")" ::: "memory")
; #define WAIT_L(n) asm volatile("s_waitcnt lgkmcnt(" #n ")" ::: "memory")
; #define BAR __builtin_amdgcn_s_barrier()
; template <class Epi> ...
;     ...
;     LDA(At, 0, 1); WAIT_V(4); BAR; WAIT_L(0); MMA(1, 0, At, B0); MMA(1, 1, At, B1); BAR; }
;   { LDB(B0, 1, 0); LDA(At, 1, 0); WAIT_V(2); BAR; WAIT_L(0); MMA(0, 0, At, B0); BAR;
	s_nop 1
	ds_read_b128 v[66:69], v155 offset:16384
	ds_read_b128 v[78:81], v155 offset:17408
	ds_read_b128 v[82:85], v156 offset:16384
	ds_read_b128 v[94:97], v156 offset:17408
	ds_read_b128 v[186:189], v157 offset:16384
	ds_read_b128 v[190:193], v157 offset:17408
	ds_read_b128 v[194:197], v158 offset:16384
	ds_read_b128 v[198:201], v158 offset:17408
	s_waitcnt vmcnt(4)
	s_barrier
	s_waitcnt lgkmcnt(0)
	v_mfma_f32_16x16x32_bf16 v[62:65], v[66:69], v[144:147], v[62:65]
	v_mfma_f32_16x16x32_bf16 v[58:61], v[66:69], v[166:169], v[58:61]
	v_mfma_f32_16x16x32_bf16 v[54:57], v[82:85], v[144:147], v[54:57]
	v_mfma_f32_16x16x32_bf16 v[42:45], v[186:189], v[166:169], v[42:45]
	v_mfma_f32_16x16x32_bf16 v[38:41], v[194:197], v[144:147], v[38:41]
	v_mfma_f32_16x16x32_bf16 v[62:65], v[78:81], v[162:165], v[62:65]
	v_mfma_f32_16x16x32_bf16 v[58:61], v[78:81], v[170:173], v[58:61]
	v_mfma_f32_16x16x32_bf16 v[54:57], v[94:97], v[162:165], v[54:57]
	v_mfma_f32_16x16x32_bf16 v[50:53], v[82:85], v[166:169], v[50:53]
	v_mfma_f32_16x16x32_bf16 v[46:49], v[186:189], v[144:147], v[46:49]
	v_mfma_f32_16x16x32_bf16 v[42:45], v[190:193], v[170:173], v[42:45]
	v_mfma_f32_16x16x32_bf16 v[38:41], v[198:201], v[162:165], v[38:41]
	v_mfma_f32_16x16x32_bf16 v[34:37], v[194:197], v[166:169], v[34:37]
	v_mfma_f32_16x16x32_bf16 v[202:205], v[94:97], v[170:173], v[50:53]
	v_mfma_f32_16x16x32_bf16 v[248:251], v[190:193], v[162:165], v[46:49]
	v_mfma_f32_16x16x32_bf16 v[144:147], v[198:201], v[170:173], v[34:37]
	v_mfma_f32_16x16x32_bf16 v[26:29], v[66:69], v[114:117], v[26:29]
	v_mfma_f32_16x16x32_bf16 v[22:25], v[82:85], v[98:101], v[22:25]
	v_mfma_f32_16x16x32_bf16 v[10:13], v[186:189], v[114:117], v[10:13]
	v_mfma_f32_16x16x32_bf16 v[6:9], v[194:197], v[98:101], v[6:9]
	v_mfma_f32_16x16x32_bf16 v[30:33], v[66:69], v[98:101], v[30:33]
	v_mfma_f32_16x16x32_bf16 v[26:29], v[78:81], v[240:243], v[26:29]
	v_mfma_f32_16x16x32_bf16 v[22:25], v[94:97], v[110:113], v[22:25]
	v_mfma_f32_16x16x32_bf16 v[18:21], v[82:85], v[114:117], v[18:21]
	v_mfma_f32_16x16x32_bf16 v[14:17], v[186:189], v[98:101], v[14:17]
	v_mfma_f32_16x16x32_bf16 v[10:13], v[190:193], v[240:243], v[10:13]
	v_mfma_f32_16x16x32_bf16 v[6:9], v[198:201], v[110:113], v[6:9]
	v_mfma_f32_16x16x32_bf16 v[2:5], v[194:197], v[114:117], v[2:5]
	v_mfma_f32_16x16x32_bf16 v[162:165], v[78:81], v[110:113], v[30:33]
	v_mfma_f32_16x16x32_bf16 v[166:169], v[94:97], v[240:243], v[18:21]
	v_mfma_f32_16x16x32_bf16 v[170:173], v[190:193], v[110:113], v[14:17]
	v_mfma_f32_16x16x32_bf16 v[186:189], v[198:201], v[240:243], v[2:5]
	s_barrier
	s_nop 1
	ds_read_b128 v[2:5], v160
	ds_read_b128 v[14:17], v160 offset:1024
	ds_read_b128 v[190:193], v160 offset:2048
	ds_read_b128 v[194:197], v160 offset:3072
	ds_read_b128 v[18:21], v155 offset:32768
	ds_read_b128 v[30:33], v155 offset:33792
	ds_read_b128 v[34:37], v156 offset:32768
	ds_read_b128 v[46:49], v156 offset:33792
	ds_read_b128 v[50:53], v157 offset:32768
	ds_read_b128 v[198:201], v157 offset:33792
	ds_read_b128 v[240:243], v158 offset:32768
	ds_read_b128 v[222:225], v158 offset:33792
	s_waitcnt vmcnt(2)
	s_barrier
	s_waitcnt lgkmcnt(0)
	v_mfma_f32_16x16x32_bf16 v[66:69], v[18:21], v[2:5], v[126:129]
	v_mfma_f32_16x16x32_bf16 v[114:117], v[30:33], v[14:17], v[66:69]
	v_mfma_f32_16x16x32_bf16 v[66:69], v[18:21], v[190:193], v[122:125]
	v_mfma_f32_16x16x32_bf16 v[126:129], v[30:33], v[194:197], v[66:69]
	v_mfma_f32_16x16x32_bf16 v[66:69], v[34:37], v[2:5], v[118:121]
	v_mfma_f32_16x16x32_bf16 v[98:101], v[46:49], v[14:17], v[66:69]
	v_mfma_f32_16x16x32_bf16 v[66:69], v[34:37], v[190:193], v[140:143]
	v_mfma_f32_16x16x32_bf16 v[110:113], v[46:49], v[194:197], v[66:69]
	v_mfma_f32_16x16x32_bf16 v[66:69], v[50:53], v[2:5], v[206:209]
	v_mfma_f32_16x16x32_bf16 v[82:85], v[198:201], v[14:17], v[66:69]
	v_mfma_f32_16x16x32_bf16 v[66:69], v[50:53], v[190:193], v[106:109]
	v_mfma_f32_16x16x32_bf16 v[94:97], v[198:201], v[194:197], v[66:69]
	v_mfma_f32_16x16x32_bf16 v[66:69], v[240:243], v[2:5], v[102:105]
	v_mfma_f32_16x16x32_bf16 v[78:81], v[240:243], v[190:193], v[236:239]
	v_mfma_f32_16x16x32_bf16 v[66:69], v[222:225], v[14:17], v[66:69]
	v_mfma_f32_16x16x32_bf16 v[78:81], v[222:225], v[194:197], v[78:81]
	s_barrier
; #define LDA(dst, b, h) _Pragma("unroll") for (int m = 0; m < 4; ++m) _Pragma("unroll") for (int k = 0; k < 2; ++k) \
;     dst[m][k] = *reinterpret_cast<const bf16x8*>((char*)SA(b, h) + lds_byte(wr * 64 + m * 16 + fr, k * 32 + fq * 8))
; #define LDB(dst, b, h) _Pragma("unroll") for (int n = 0; n < 2; ++n) _Pragma("unroll") for (int k = 0; k < 2; ++k) \
;     dst[n][k] = *reinterpret_cast<const bf16x8*>((char*)SB(b, h) + lds_byte(wc * 32 + n * 16 + fr, k * 32 + fq * 8))
; #define MMA(ai, bj, At_, Bt_) do { __builtin_amdgcn_s_setprio(1); \
;     _Pragma("unroll") for (int m = 0; m < 4; ++m) _Pragma("unroll") for (int n = 0; n < 2; ++n) _Pragma("unroll") for (int k = 0; k < 2; ++k) \
;       acc[ai][bj][m][n] = __builtin_amdgcn_mfma_f32_16x16x32_bf16(At_[m][k], Bt_[n][k], acc[ai][bj][m][n], 0, 0, 0); \
;     __builtin_amdgcn_s_setprio(0); } while (0)
; #define WAIT_V(n) asm volatile("s_waitcnt vmcnt(" #n ")" ::: "memory")
; #define WAIT_L(n) asm volatile("s_waitcnt lgkmcnt(" #n ")" ::: "memory")
; #define BAR __builtin_amdgcn_s_barrier()
; template <class Epi> ...
;     ...
;     LDB(B1, 1, 1); WAIT_V(0); BAR; WAIT_L(0); MMA(0, 1, At, B1); BAR;
;     LDA(At, 1, 1); BAR; WAIT_L(0); MMA(1, 0, At, B0); MMA(1, 1, At, B1); BAR; }
;   if (wr == 0) BAR;
	ds_read_b128 v[140:143], v161
	ds_read_b128 v[206:209], v161 offset:1024
	ds_read_b128 v[236:239], v161 offset:2048
	ds_read_b128 v[226:229], v161 offset:3072
	s_waitcnt vmcnt(0)
	s_barrier
	s_waitcnt lgkmcnt(0)
	v_mfma_f32_16x16x32_bf16 v[102:105], v[18:21], v[140:143], v[244:247]
	v_mfma_f32_16x16x32_bf16 v[18:21], v[18:21], v[236:239], v[90:93]
	v_mfma_f32_16x16x32_bf16 v[122:125], v[30:33], v[226:229], v[18:21]
	v_mfma_f32_16x16x32_bf16 v[18:21], v[34:37], v[140:143], v[86:89]
	v_mfma_f32_16x16x32_bf16 v[118:121], v[30:33], v[206:209], v[102:105]
	v_mfma_f32_16x16x32_bf16 v[102:105], v[46:49], v[206:209], v[18:21]
	v_mfma_f32_16x16x32_bf16 v[18:21], v[34:37], v[236:239], v[174:177]
	v_mfma_f32_16x16x32_bf16 v[106:109], v[46:49], v[226:229], v[18:21]
	v_mfma_f32_16x16x32_bf16 v[18:21], v[50:53], v[140:143], v[178:181]
	v_mfma_f32_16x16x32_bf16 v[86:89], v[198:201], v[206:209], v[18:21]
	v_mfma_f32_16x16x32_bf16 v[18:21], v[50:53], v[236:239], v[74:77]
	v_mfma_f32_16x16x32_bf16 v[90:93], v[198:201], v[226:229], v[18:21]
	v_mfma_f32_16x16x32_bf16 v[18:21], v[240:243], v[140:143], v[70:73]
	v_mfma_f32_16x16x32_bf16 v[70:73], v[222:225], v[206:209], v[18:21]
	v_mfma_f32_16x16x32_bf16 v[18:21], v[240:243], v[236:239], v[182:185]
	v_mfma_f32_16x16x32_bf16 v[74:77], v[222:225], v[226:229], v[18:21]
	s_barrier
	ds_read_b128 v[174:177], v155 offset:49152
	ds_read_b128 v[178:181], v155 offset:50176
	ds_read_b128 v[182:185], v156 offset:49152
	ds_read_b128 v[198:201], v156 offset:50176
	ds_read_b128 v[222:225], v157 offset:49152
	ds_read_b128 v[240:243], v157 offset:50176
	ds_read_b128 v[244:247], v158 offset:49152
	ds_read_b128 v[230:233], v158 offset:50176
	s_barrier
	s_waitcnt lgkmcnt(0)
	v_mfma_f32_16x16x32_bf16 v[18:21], v[174:177], v[2:5], v[62:65]
	v_mfma_f32_16x16x32_bf16 v[50:53], v[178:181], v[14:17], v[18:21]
	v_mfma_f32_16x16x32_bf16 v[18:21], v[174:177], v[190:193], v[58:61]
	v_mfma_f32_16x16x32_bf16 v[62:65], v[178:181], v[194:197], v[18:21]
	v_mfma_f32_16x16x32_bf16 v[18:21], v[182:185], v[2:5], v[54:57]
	v_mfma_f32_16x16x32_bf16 v[34:37], v[198:201], v[14:17], v[18:21]
	v_mfma_f32_16x16x32_bf16 v[18:21], v[182:185], v[190:193], v[202:205]
	v_mfma_f32_16x16x32_bf16 v[46:49], v[198:201], v[194:197], v[18:21]
	v_mfma_f32_16x16x32_bf16 v[18:21], v[222:225], v[2:5], v[248:251]
	v_mfma_f32_16x16x32_bf16 v[2:5], v[244:247], v[2:5], v[38:41]
	v_mfma_f32_16x16x32_bf16 v[18:21], v[240:243], v[14:17], v[18:21]
	v_mfma_f32_16x16x32_bf16 v[30:33], v[222:225], v[190:193], v[42:45]
	v_mfma_f32_16x16x32_bf16 v[2:5], v[230:233], v[14:17], v[2:5]
	v_mfma_f32_16x16x32_bf16 v[14:17], v[244:247], v[190:193], v[144:147]
	v_mfma_f32_16x16x32_bf16 v[30:33], v[240:243], v[194:197], v[30:33]
	v_mfma_f32_16x16x32_bf16 v[14:17], v[230:233], v[194:197], v[14:17]
	v_mfma_f32_16x16x32_bf16 v[38:41], v[174:177], v[140:143], v[162:165]
	v_mfma_f32_16x16x32_bf16 v[22:25], v[182:185], v[140:143], v[22:25]
	v_mfma_f32_16x16x32_bf16 v[54:57], v[178:181], v[206:209], v[38:41]
	v_mfma_f32_16x16x32_bf16 v[26:29], v[174:177], v[236:239], v[26:29]
	v_mfma_f32_16x16x32_bf16 v[38:41], v[198:201], v[206:209], v[22:25]
	v_mfma_f32_16x16x32_bf16 v[22:25], v[182:185], v[236:239], v[166:169]
	v_mfma_f32_16x16x32_bf16 v[10:13], v[222:225], v[236:239], v[10:13]
	v_mfma_f32_16x16x32_bf16 v[58:61], v[178:181], v[226:229], v[26:29]
	v_mfma_f32_16x16x32_bf16 v[42:45], v[198:201], v[226:229], v[22:25]
	v_mfma_f32_16x16x32_bf16 v[22:25], v[222:225], v[140:143], v[170:173]
	v_mfma_f32_16x16x32_bf16 v[26:29], v[240:243], v[226:229], v[10:13]
	v_mfma_f32_16x16x32_bf16 v[6:9], v[244:247], v[140:143], v[6:9]
	v_mfma_f32_16x16x32_bf16 v[10:13], v[244:247], v[236:239], v[186:189]
	v_mfma_f32_16x16x32_bf16 v[22:25], v[240:243], v[206:209], v[22:25]
	v_mfma_f32_16x16x32_bf16 v[6:9], v[230:233], v[206:209], v[6:9]
	v_mfma_f32_16x16x32_bf16 v[10:13], v[230:233], v[226:229], v[10:13]
	s_barrier
	s_and_saveexec_b64 s[22:23], s[6:7]
	s_cbranch_execz .LBB0_61
	s_barrier
	s_branch .LBB0_61

; #define STAGE(P, BASE, br, kt) do { const char* _gb = (const char*)((BASE) + ((long)(br) * K + (long)(kt) * BK)); \
;     __builtin_amdgcn_global_load_lds((const unsigned*)(_gb + (size_t)so0), (unsigned*)((char*)(P) + wv1k), 16, 0, 0); \
;     __builtin_amdgcn_global_load_lds((const unsigned*)(_gb + (size_t)so1), (unsigned*)((char*)(P) + wv1k + 8192), 16, 0, 0); } while (0)
; #define LDA(dst, b, h) _Pragma("unroll") for (int m = 0; m < 4; ++m) _Pragma("unroll") for (int k = 0; k < 2; ++k) \
;     dst[m][k] = *reinterpret_cast<const bf16x8*>((char*)SA(b, h) + lds_byte(wr * 64 + m * 16 + fr, k * 32 + fq * 8))
; #define LDB(dst, b, h) _Pragma("unroll") for (int n = 0; n < 2; ++n) _Pragma("unroll") for (int k = 0; k < 2; ++k) \
;     dst[n][k] = *reinterpret_cast<const bf16x8*>((char*)SB(b, h) + lds_byte(wc * 32 + n * 16 + fr, k * 32 + fq * 8))
; #define MMA(ai, bj, At_, Bt_) do { __builtin_amdgcn_s_setprio(1); \
;     _Pragma("unroll") for (int m = 0; m < 4; ++m) _Pragma("unroll") for (int n = 0; n < 2; ++n) _Pragma("unroll") for (int k = 0; k < 2; ++k) \
;       acc[ai][bj][m][n] = __builtin_amdgcn_mfma_f32_16x16x32_bf16(At_[m][k], Bt_[n][k], acc[ai][bj][m][n], 0, 0, 0); \
;     __builtin_amdgcn_s_setprio(0); } while (0)
; #define WAIT_L(n) asm volatile("s_waitcnt lgkmcnt(" #n ")" ::: "memory")
; #define BAR __builtin_amdgcn_s_barrier()
; #define SCHED __builtin_amdgcn_sched_barrier(0)
; template <class Epi> ...
;     ...
;   for (int t = 0; t < nt - 2; t += 2) {
;     LDB(B0, 0, 0); SCHED; LDA(At, 0, 0); STAGE(SA(1, 1), A, brow + HALF, t + 1);
;     WAIT_L(8); BAR; WAIT_L(0); MMA(0, 0, At, B0); BAR; SCHED;
;     LDB(B1, 0, 1); STAGE(SB(0, 0), Bt, bcol, t + 2);
;     BAR; WAIT_L(0); MMA(0, 1, At, B1); BAR;
;     LDA(At, 0, 1); STAGE(SA(0, 0), A, brow, t + 2);
;     BAR; WAIT_L(0); MMA(1, 0, At, B0); BAR; SCHED;
.LBB0_82:
	ds_read_b128 v[106:109], v235
	ds_read_b128 v[110:113], v235 offset:1024
	ds_read_b128 v[162:165], v235 offset:2048
	ds_read_b128 v[166:169], v235 offset:3072
	v_lshl_add_u64 v[210:211], v[96:97], 0, s[24:25]
	s_add_i32 s28, s42, 0xc000
	v_lshl_add_u64 v[202:203], v[210:211], 0, s[54:55]
	s_mov_b32 m0, s28
	v_lshl_add_u64 v[212:213], v[90:91], 0, s[24:25]
	s_add_i32 s27, s42, 0xe000
	ds_read_b128 v[170:173], v236
	ds_read_b128 v[174:177], v236 offset:1024
	ds_read_b128 v[178:181], v237
	ds_read_b128 v[182:185], v237 offset:1024
	ds_read_b128 v[186:189], v238
	ds_read_b128 v[190:193], v238 offset:1024
	ds_read_b128 v[194:197], v239
	ds_read_b128 v[198:201], v239 offset:1024
	global_load_lds_dwordx4 v[202:203], off
	v_lshl_add_u64 v[202:203], v[212:213], 0, s[54:55]
	s_mov_b32 m0, s27
	s_nop 0
	global_load_lds_dwordx4 v[202:203], off
	s_waitcnt lgkmcnt(8)
	s_barrier
	s_waitcnt lgkmcnt(0)
	v_mfma_f32_16x16x32_bf16 v[2:5], v[170:173], v[106:109], v[2:5]
	v_mfma_f32_16x16x32_bf16 v[10:13], v[170:173], v[162:165], v[10:13]
	v_mfma_f32_16x16x32_bf16 v[22:25], v[178:181], v[106:109], v[22:25]
	v_mfma_f32_16x16x32_bf16 v[30:33], v[178:181], v[162:165], v[30:33]
	v_mfma_f32_16x16x32_bf16 v[62:65], v[186:189], v[106:109], v[62:65]
	v_mfma_f32_16x16x32_bf16 v[86:89], v[186:189], v[162:165], v[86:89]
	v_mfma_f32_16x16x32_bf16 v[118:121], v[194:197], v[106:109], v[118:121]
	v_mfma_f32_16x16x32_bf16 v[130:133], v[194:197], v[162:165], v[130:133]
	v_mfma_f32_16x16x32_bf16 v[2:5], v[174:177], v[110:113], v[2:5]
	v_mfma_f32_16x16x32_bf16 v[10:13], v[174:177], v[166:169], v[10:13]
	v_mfma_f32_16x16x32_bf16 v[22:25], v[182:185], v[110:113], v[22:25]
	v_mfma_f32_16x16x32_bf16 v[30:33], v[182:185], v[166:169], v[30:33]
	v_mfma_f32_16x16x32_bf16 v[62:65], v[190:193], v[110:113], v[62:65]
	v_mfma_f32_16x16x32_bf16 v[86:89], v[190:193], v[166:169], v[86:89]
	v_mfma_f32_16x16x32_bf16 v[118:121], v[198:201], v[110:113], v[118:121]
	v_mfma_f32_16x16x32_bf16 v[130:133], v[198:201], v[166:169], v[130:133]
	s_barrier
	v_lshl_add_u64 v[214:215], v[48:49], 0, s[24:25]
	s_mov_b32 m0, s43
	v_lshl_add_u64 v[216:217], v[214:215], 0, s[0:1]
	ds_read_b128 v[202:205], v240
	ds_read_b128 v[206:209], v240 offset:1024
	ds_read_b128 v[222:225], v240 offset:2048
	ds_read_b128 v[226:229], v240 offset:3072
	global_load_lds_dwordx4 v[216:217], off
	v_lshl_add_u64 v[216:217], v[34:35], 0, s[24:25]
	v_lshl_add_u64 v[218:219], v[216:217], 0, s[0:1]
	s_mov_b32 m0, s44
	s_nop 0
	global_load_lds_dwordx4 v[218:219], off
	s_barrier
	s_waitcnt lgkmcnt(0)
	v_mfma_f32_16x16x32_bf16 v[6:9], v[170:173], v[202:205], v[6:9]
	v_mfma_f32_16x16x32_bf16 v[14:17], v[170:173], v[222:225], v[14:17]
	v_mfma_f32_16x16x32_bf16 v[18:21], v[178:181], v[202:205], v[18:21]
	v_mfma_f32_16x16x32_bf16 v[26:29], v[178:181], v[222:225], v[26:29]
	v_mfma_f32_16x16x32_bf16 v[58:61], v[186:189], v[202:205], v[58:61]
	v_mfma_f32_16x16x32_bf16 v[82:85], v[186:189], v[222:225], v[82:85]
	v_mfma_f32_16x16x32_bf16 v[114:117], v[194:197], v[202:205], v[114:117]
	v_mfma_f32_16x16x32_bf16 v[126:129], v[194:197], v[222:225], v[126:129]
	v_mfma_f32_16x16x32_bf16 v[6:9], v[174:177], v[206:209], v[6:9]
	v_mfma_f32_16x16x32_bf16 v[14:17], v[174:177], v[226:229], v[14:17]
	v_mfma_f32_16x16x32_bf16 v[18:21], v[182:185], v[206:209], v[18:21]
	v_mfma_f32_16x16x32_bf16 v[26:29], v[182:185], v[226:229], v[26:29]
	v_mfma_f32_16x16x32_bf16 v[58:61], v[190:193], v[206:209], v[58:61]
	v_mfma_f32_16x16x32_bf16 v[82:85], v[190:193], v[226:229], v[82:85]
	v_mfma_f32_16x16x32_bf16 v[114:117], v[198:201], v[206:209], v[114:117]
	v_mfma_f32_16x16x32_bf16 v[126:129], v[198:201], v[226:229], v[126:129]
	v_lshl_add_u64 v[218:219], v[72:73], 0, s[24:25]
	s_mov_b32 m0, s42
	v_lshl_add_u64 v[220:221], v[218:219], 0, s[0:1]
	s_barrier
	ds_read_b128 v[170:173], v236 offset:16384
	ds_read_b128 v[174:177], v236 offset:17408
	ds_read_b128 v[178:181], v237 offset:16384
	ds_read_b128 v[182:185], v237 offset:17408
	ds_read_b128 v[186:189], v238 offset:16384
	ds_read_b128 v[190:193], v238 offset:17408
	ds_read_b128 v[194:197], v239 offset:16384
	ds_read_b128 v[198:201], v239 offset:17408
	global_load_lds_dwordx4 v[220:221], off
	v_lshl_add_u64 v[220:221], v[66:67], 0, s[24:25]
	v_lshl_add_u64 v[230:231], v[220:221], 0, s[0:1]
	s_mov_b32 m0, s19
	s_nop 0
	global_load_lds_dwordx4 v[230:231], off
	s_barrier
	s_waitcnt lgkmcnt(0)
	v_mfma_f32_16x16x32_bf16 v[122:125], v[170:173], v[106:109], v[122:125]
	v_mfma_f32_16x16x32_bf16 v[138:141], v[170:173], v[162:165], v[138:141]
	v_mfma_f32_16x16x32_bf16 v[50:53], v[178:181], v[106:109], v[50:53]
	v_mfma_f32_16x16x32_bf16 v[54:57], v[178:181], v[162:165], v[54:57]
	v_mfma_f32_16x16x32_bf16 v[78:81], v[186:189], v[106:109], v[78:81]
	v_mfma_f32_16x16x32_bf16 v[142:145], v[186:189], v[162:165], v[142:145]
	v_mfma_f32_16x16x32_bf16 v[102:105], v[194:197], v[106:109], v[102:105]
	v_mfma_f32_16x16x32_bf16 v[122:125], v[174:177], v[110:113], v[122:125]
	v_mfma_f32_16x16x32_bf16 v[138:141], v[174:177], v[166:169], v[138:141]
	v_mfma_f32_16x16x32_bf16 v[50:53], v[182:185], v[110:113], v[50:53]
	v_mfma_f32_16x16x32_bf16 v[54:57], v[182:185], v[166:169], v[54:57]
	v_mfma_f32_16x16x32_bf16 v[78:81], v[190:193], v[110:113], v[78:81]
	v_mfma_f32_16x16x32_bf16 v[142:145], v[190:193], v[166:169], v[142:145]
	v_mfma_f32_16x16x32_bf16 v[102:105], v[198:201], v[110:113], v[102:105]
	v_mfma_f32_16x16x32_bf16 v[106:109], v[194:197], v[162:165], v[146:149]
	v_mfma_f32_16x16x32_bf16 v[106:109], v[198:201], v[166:169], v[106:109]
	s_barrier
; #define STAGE(P, BASE, br, kt) do { const char* _gb = (const char*)((BASE) + ((long)(br) * K + (long)(kt) * BK)); \
;     __builtin_amdgcn_global_load_lds((const unsigned*)(_gb + (size_t)so0), (unsigned*)((char*)(P) + wv1k), 16, 0, 0); \
;     __builtin_amdgcn_global_load_lds((const unsigned*)(_gb + (size_t)so1), (unsigned*)((char*)(P) + wv1k + 8192), 16, 0, 0); } while (0)
; #define LDA(dst, b, h) _Pragma("unroll") for (int m = 0; m < 4; ++m) _Pragma("unroll") for (int k = 0; k < 2; ++k) \
;     dst[m][k] = *reinterpret_cast<const bf16x8*>((char*)SA(b, h) + lds_byte(wr * 64 + m * 16 + fr, k * 32 + fq * 8))
; #define LDB(dst, b, h) _Pragma("unroll") for (int n = 0; n < 2; ++n) _Pragma("unroll") for (int k = 0; k < 2; ++k) \
;     dst[n][k] = *reinterpret_cast<const bf16x8*>((char*)SB(b, h) + lds_byte(wc * 32 + n * 16 + fr, k * 32 + fq * 8))
; #define MMA(ai, bj, At_, Bt_) do { __builtin_amdgcn_s_setprio(1); \
;     _Pragma("unroll") for (int m = 0; m < 4; ++m) _Pragma("unroll") for (int n = 0; n < 2; ++n) _Pragma("unroll") for (int k = 0; k < 2; ++k) \
;       acc[ai][bj][m][n] = __builtin_amdgcn_mfma_f32_16x16x32_bf16(At_[m][k], Bt_[n][k], acc[ai][bj][m][n], 0, 0, 0); \
;     __builtin_amdgcn_s_setprio(0); } while (0)
; #define WAIT_V(n) asm volatile("s_waitcnt vmcnt(" #n ")" ::: "memory")
; #define WAIT_L(n) asm volatile("s_waitcnt lgkmcnt(" #n ")" ::: "memory")
; #define BAR __builtin_amdgcn_s_barrier()
; #define SCHED __builtin_amdgcn_sched_barrier(0)
; template <class Epi> ...
;     ...
;     BAR; WAIT_L(0); MMA(1, 0, At, B0); BAR; SCHED;
;     STAGE(SB(0, 1), Bt, bcol + HALF, t + 2);
;     WAIT_V(6); BAR; MMA(1, 1, At, B1); BAR;
;     LDB(B0, 1, 0); SCHED; LDA(At, 1, 0); STAGE(SA(0, 1), A, brow + HALF, t + 2);
;     WAIT_L(8); BAR; WAIT_L(0); MMA(0, 0, At, B0); BAR; SCHED;
;     LDB(B1, 1, 1); STAGE(SB(1, 0), Bt, bcol, t + 3);
;     BAR; WAIT_L(0); MMA(0, 1, At, B1); BAR;
;     LDA(At, 1, 1); STAGE(SA(1, 0), A, brow, t + 3);
;     BAR; WAIT_L(0); MMA(1, 0, At, B0); BAR; SCHED;
	s_mov_b32 m0, s45
	v_lshl_add_u64 v[110:111], v[214:215], 0, s[2:3]
	global_load_lds_dwordx4 v[110:111], off
	v_lshl_add_u64 v[110:111], v[216:217], 0, s[2:3]
	s_mov_b32 m0, s46
	s_nop 0
	global_load_lds_dwordx4 v[110:111], off
	s_waitcnt vmcnt(6)
	s_barrier
	v_mfma_f32_16x16x32_bf16 v[36:39], v[170:173], v[222:225], v[36:39]
	v_mfma_f32_16x16x32_bf16 v[40:43], v[178:181], v[202:205], v[40:43]
	v_mfma_f32_16x16x32_bf16 v[44:47], v[178:181], v[222:225], v[44:47]
	v_mfma_f32_16x16x32_bf16 v[74:77], v[186:189], v[202:205], v[74:77]
	v_mfma_f32_16x16x32_bf16 v[68:71], v[186:189], v[222:225], v[68:71]
	v_mfma_f32_16x16x32_bf16 v[98:101], v[194:197], v[202:205], v[98:101]
	v_mfma_f32_16x16x32_bf16 v[92:95], v[194:197], v[222:225], v[92:95]
	v_mfma_f32_16x16x32_bf16 v[110:113], v[170:173], v[202:205], v[134:137]
	v_mfma_f32_16x16x32_bf16 v[36:39], v[174:177], v[226:229], v[36:39]
	v_mfma_f32_16x16x32_bf16 v[40:43], v[182:185], v[206:209], v[40:43]
	v_mfma_f32_16x16x32_bf16 v[44:47], v[182:185], v[226:229], v[44:47]
	v_mfma_f32_16x16x32_bf16 v[74:77], v[190:193], v[206:209], v[74:77]
	v_mfma_f32_16x16x32_bf16 v[68:71], v[190:193], v[226:229], v[68:71]
	v_mfma_f32_16x16x32_bf16 v[98:101], v[198:201], v[206:209], v[98:101]
	v_mfma_f32_16x16x32_bf16 v[92:95], v[198:201], v[226:229], v[92:95]
	v_mfma_f32_16x16x32_bf16 v[110:113], v[174:177], v[206:209], v[110:113]
	s_barrier
	ds_read_b128 v[134:137], v241
	ds_read_b128 v[146:149], v241 offset:1024
	ds_read_b128 v[162:165], v241 offset:2048
	ds_read_b128 v[166:169], v241 offset:3072
	s_mov_b32 m0, s47
	v_lshl_add_u64 v[202:203], v[210:211], 0, s[2:3]
	ds_read_b128 v[170:173], v236 offset:32768
	ds_read_b128 v[174:177], v236 offset:33792
	ds_read_b128 v[178:181], v237 offset:32768
	ds_read_b128 v[182:185], v237 offset:33792
	ds_read_b128 v[186:189], v238 offset:32768
	ds_read_b128 v[190:193], v238 offset:33792
	ds_read_b128 v[194:197], v239 offset:32768
	ds_read_b128 v[198:201], v239 offset:33792
	global_load_lds_dwordx4 v[202:203], off
	v_lshl_add_u64 v[202:203], v[212:213], 0, s[2:3]
	s_mov_b32 m0, s50
	s_nop 0
	global_load_lds_dwordx4 v[202:203], off
	s_waitcnt lgkmcnt(8)
	s_barrier
	s_waitcnt lgkmcnt(0)
	v_mfma_f32_16x16x32_bf16 v[2:5], v[170:173], v[134:137], v[2:5]
	v_mfma_f32_16x16x32_bf16 v[10:13], v[170:173], v[162:165], v[10:13]
	v_mfma_f32_16x16x32_bf16 v[22:25], v[178:181], v[134:137], v[22:25]
	v_mfma_f32_16x16x32_bf16 v[30:33], v[178:181], v[162:165], v[30:33]
	v_mfma_f32_16x16x32_bf16 v[62:65], v[186:189], v[134:137], v[62:65]
	v_mfma_f32_16x16x32_bf16 v[86:89], v[186:189], v[162:165], v[86:89]
	v_mfma_f32_16x16x32_bf16 v[118:121], v[194:197], v[134:137], v[118:121]
	v_mfma_f32_16x16x32_bf16 v[130:133], v[194:197], v[162:165], v[130:133]
	v_mfma_f32_16x16x32_bf16 v[2:5], v[174:177], v[146:149], v[2:5]
	v_mfma_f32_16x16x32_bf16 v[10:13], v[174:177], v[166:169], v[10:13]
	v_mfma_f32_16x16x32_bf16 v[22:25], v[182:185], v[146:149], v[22:25]
	v_mfma_f32_16x16x32_bf16 v[30:33], v[182:185], v[166:169], v[30:33]
	v_mfma_f32_16x16x32_bf16 v[62:65], v[190:193], v[146:149], v[62:65]
	v_mfma_f32_16x16x32_bf16 v[86:89], v[190:193], v[166:169], v[86:89]
	v_mfma_f32_16x16x32_bf16 v[118:121], v[198:201], v[146:149], v[118:121]
	v_mfma_f32_16x16x32_bf16 v[130:133], v[198:201], v[166:169], v[130:133]
	s_barrier
	s_mov_b32 m0, s34
	v_lshl_add_u64 v[210:211], v[214:215], 0, s[90:91]
	ds_read_b128 v[202:205], v242
	ds_read_b128 v[206:209], v242 offset:1024
	ds_read_b128 v[222:225], v242 offset:2048
	ds_read_b128 v[226:229], v242 offset:3072
	global_load_lds_dwordx4 v[210:211], off
	v_lshl_add_u64 v[210:211], v[216:217], 0, s[90:91]
	s_mov_b32 m0, s35
	s_nop 0
	global_load_lds_dwordx4 v[210:211], off
	s_barrier
	s_waitcnt lgkmcnt(0)
	v_mfma_f32_16x16x32_bf16 v[6:9], v[170:173], v[202:205], v[6:9]
	v_mfma_f32_16x16x32_bf16 v[14:17], v[170:173], v[222:225], v[14:17]
	v_mfma_f32_16x16x32_bf16 v[18:21], v[178:181], v[202:205], v[18:21]
	v_mfma_f32_16x16x32_bf16 v[26:29], v[178:181], v[222:225], v[26:29]
	v_mfma_f32_16x16x32_bf16 v[58:61], v[186:189], v[202:205], v[58:61]
	v_mfma_f32_16x16x32_bf16 v[82:85], v[186:189], v[222:225], v[82:85]
	v_mfma_f32_16x16x32_bf16 v[114:117], v[194:197], v[202:205], v[114:117]
	v_mfma_f32_16x16x32_bf16 v[126:129], v[194:197], v[222:225], v[126:129]
	v_mfma_f32_16x16x32_bf16 v[6:9], v[174:177], v[206:209], v[6:9]
	v_mfma_f32_16x16x32_bf16 v[14:17], v[174:177], v[226:229], v[14:17]
	v_mfma_f32_16x16x32_bf16 v[18:21], v[182:185], v[206:209], v[18:21]
	v_mfma_f32_16x16x32_bf16 v[26:29], v[182:185], v[226:229], v[26:29]
	v_mfma_f32_16x16x32_bf16 v[58:61], v[190:193], v[206:209], v[58:61]
	v_mfma_f32_16x16x32_bf16 v[82:85], v[190:193], v[226:229], v[82:85]
	v_mfma_f32_16x16x32_bf16 v[114:117], v[198:201], v[206:209], v[114:117]
	v_mfma_f32_16x16x32_bf16 v[126:129], v[198:201], v[226:229], v[126:129]
	s_mov_b32 m0, s51
	v_lshl_add_u64 v[210:211], v[218:219], 0, s[90:91]
	s_barrier
	ds_read_b128 v[170:173], v236 offset:49152
	ds_read_b128 v[174:177], v236 offset:50176
	ds_read_b128 v[178:181], v237 offset:49152
	ds_read_b128 v[182:185], v237 offset:50176
	ds_read_b128 v[186:189], v238 offset:49152
	ds_read_b128 v[190:193], v238 offset:50176
	ds_read_b128 v[194:197], v239 offset:49152
	ds_read_b128 v[198:201], v239 offset:50176
	global_load_lds_dwordx4 v[210:211], off
	v_lshl_add_u64 v[210:211], v[220:221], 0, s[90:91]
	s_mov_b32 m0, s52
	s_nop 0
	global_load_lds_dwordx4 v[210:211], off
	s_barrier
; #define STAGE(P, BASE, br, kt) do { const char* _gb = (const char*)((BASE) + ((long)(br) * K + (long)(kt) * BK)); \
;     __builtin_amdgcn_global_load_lds((const unsigned*)(_gb + (size_t)so0), (unsigned*)((char*)(P) + wv1k), 16, 0, 0); \
;     __builtin_amdgcn_global_load_lds((const unsigned*)(_gb + (size_t)so1), (unsigned*)((char*)(P) + wv1k + 8192), 16, 0, 0); } while (0)
; #define LDA(dst, b, h) _Pragma("unroll") for (int m = 0; m < 4; ++m) _Pragma("unroll") for (int k = 0; k < 2; ++k) \
;     dst[m][k] = *reinterpret_cast<const bf16x8*>((char*)SA(b, h) + lds_byte(wr * 64 + m * 16 + fr, k * 32 + fq * 8))
; #define LDB(dst, b, h) _Pragma("unroll") for (int n = 0; n < 2; ++n) _Pragma("unroll") for (int k = 0; k < 2; ++k) \
;     dst[n][k] = *reinterpret_cast<const bf16x8*>((char*)SB(b, h) + lds_byte(wc * 32 + n * 16 + fr, k * 32 + fq * 8))
; #define MMA(ai, bj, At_, Bt_) do { __builtin_amdgcn_s_setprio(1); \
;     _Pragma("unroll") for (int m = 0; m < 4; ++m) _Pragma("unroll") for (int n = 0; n < 2; ++n) _Pragma("unroll") for (int k = 0; k < 2; ++k) \
;       acc[ai][bj][m][n] = __builtin_amdgcn_mfma_f32_16x16x32_bf16(At_[m][k], Bt_[n][k], acc[ai][bj][m][n], 0, 0, 0); \
;     __builtin_amdgcn_s_setprio(0); } while (0)
; #define WAIT_V(n) asm volatile("s_waitcnt vmcnt(" #n ")" ::: "memory")
; #define WAIT_L(n) asm volatile("s_waitcnt lgkmcnt(" #n ")" ::: "memory")
; #define BAR __builtin_amdgcn_s_barrier()
; #define SCHED __builtin_amdgcn_sched_barrier(0)
; template <class Epi> ...
;     ...
;     BAR; WAIT_L(0); MMA(1, 0, At, B0); BAR; SCHED;
;     STAGE(SB(1, 1), Bt, bcol + HALF, t + 3);
;     WAIT_V(6); BAR; MMA(1, 1, At, B1); BAR;
;   }
;   { LDB(B0, 0, 0); LDA(At, 0, 0); STAGE(SA(1, 1), A, brow + HALF, nt - 1);
;     BAR; WAIT_L(0); MMA(0, 0, At, B0); BAR;
;     LDB(B1, 0, 1); BAR; WAIT_L(0); MMA(0, 1, At, B1); BAR;
	s_waitcnt lgkmcnt(0)
	v_mfma_f32_16x16x32_bf16 v[122:125], v[170:173], v[134:137], v[122:125]
	v_mfma_f32_16x16x32_bf16 v[138:141], v[170:173], v[162:165], v[138:141]
	v_mfma_f32_16x16x32_bf16 v[50:53], v[178:181], v[134:137], v[50:53]
	v_mfma_f32_16x16x32_bf16 v[54:57], v[178:181], v[162:165], v[54:57]
	v_mfma_f32_16x16x32_bf16 v[78:81], v[186:189], v[134:137], v[78:81]
	v_mfma_f32_16x16x32_bf16 v[142:145], v[186:189], v[162:165], v[142:145]
	v_mfma_f32_16x16x32_bf16 v[102:105], v[194:197], v[134:137], v[102:105]
	v_mfma_f32_16x16x32_bf16 v[106:109], v[194:197], v[162:165], v[106:109]
	v_mfma_f32_16x16x32_bf16 v[122:125], v[174:177], v[146:149], v[122:125]
	v_mfma_f32_16x16x32_bf16 v[138:141], v[174:177], v[166:169], v[138:141]
	v_mfma_f32_16x16x32_bf16 v[50:53], v[182:185], v[146:149], v[50:53]
	v_mfma_f32_16x16x32_bf16 v[54:57], v[182:185], v[166:169], v[54:57]
	v_mfma_f32_16x16x32_bf16 v[78:81], v[190:193], v[146:149], v[78:81]
	v_mfma_f32_16x16x32_bf16 v[142:145], v[190:193], v[166:169], v[142:145]
	v_mfma_f32_16x16x32_bf16 v[102:105], v[198:201], v[146:149], v[102:105]
	v_mfma_f32_16x16x32_bf16 v[146:149], v[198:201], v[166:169], v[106:109]
	s_barrier
	s_mov_b32 m0, s30
	v_lshl_add_u64 v[106:107], v[214:215], 0, s[60:61]
	global_load_lds_dwordx4 v[106:107], off
	v_lshl_add_u64 v[106:107], v[216:217], 0, s[60:61]
	s_mov_b32 m0, s31
	s_nop 0
	global_load_lds_dwordx4 v[106:107], off
	s_waitcnt vmcnt(6)
	s_barrier
	v_mfma_f32_16x16x32_bf16 v[106:109], v[170:173], v[202:205], v[110:113]
	v_mfma_f32_16x16x32_bf16 v[36:39], v[170:173], v[222:225], v[36:39]
	v_mfma_f32_16x16x32_bf16 v[40:43], v[178:181], v[202:205], v[40:43]
	v_mfma_f32_16x16x32_bf16 v[44:47], v[178:181], v[222:225], v[44:47]
	v_mfma_f32_16x16x32_bf16 v[74:77], v[186:189], v[202:205], v[74:77]
	v_mfma_f32_16x16x32_bf16 v[68:71], v[186:189], v[222:225], v[68:71]
	v_mfma_f32_16x16x32_bf16 v[98:101], v[194:197], v[202:205], v[98:101]
	v_mfma_f32_16x16x32_bf16 v[92:95], v[194:197], v[222:225], v[92:95]
	v_mfma_f32_16x16x32_bf16 v[134:137], v[174:177], v[206:209], v[106:109]
	v_mfma_f32_16x16x32_bf16 v[36:39], v[174:177], v[226:229], v[36:39]
	v_mfma_f32_16x16x32_bf16 v[40:43], v[182:185], v[206:209], v[40:43]
	v_mfma_f32_16x16x32_bf16 v[44:47], v[182:185], v[226:229], v[44:47]
	v_mfma_f32_16x16x32_bf16 v[74:77], v[190:193], v[206:209], v[74:77]
	v_mfma_f32_16x16x32_bf16 v[68:71], v[190:193], v[226:229], v[68:71]
	v_mfma_f32_16x16x32_bf16 v[98:101], v[198:201], v[206:209], v[98:101]
	v_mfma_f32_16x16x32_bf16 v[92:95], v[198:201], v[226:229], v[92:95]
	s_add_i32 s26, s26, 2
	s_add_u32 s24, s24, 0x100
	s_addc_u32 s25, s25, 0
	s_cmp_lt_u32 s26, 40
	s_barrier
	s_cbranch_scc1 .LBB0_82
	s_add_u32 s22, s22, 0x1580
	s_addc_u32 s23, s23, 0
	s_mov_b32 m0, s28
	v_lshl_add_u64 v[34:35], s[22:23], 0, v[0:1]
	ds_read_b128 v[106:109], v235
	ds_read_b128 v[110:113], v235 offset:1024
	ds_read_b128 v[162:165], v235 offset:2048
	ds_read_b128 v[166:169], v235 offset:3072
	ds_read_b128 v[170:173], v236
	ds_read_b128 v[174:177], v236 offset:1024
	ds_read_b128 v[178:181], v237
	ds_read_b128 v[182:185], v237 offset:1024
	ds_read_b128 v[186:189], v238
	ds_read_b128 v[190:193], v238 offset:1024
	ds_read_b128 v[194:197], v239
	ds_read_b128 v[198:201], v239 offset:1024
	global_load_lds_dwordx4 v[34:35], off
	v_lshl_add_u64 v[34:35], s[22:23], 0, v[152:153]
	s_mov_b32 m0, s27
	s_nop 0
	global_load_lds_dwordx4 v[34:35], off
	s_barrier
	s_waitcnt lgkmcnt(0)
	v_mfma_f32_16x16x32_bf16 v[2:5], v[170:173], v[106:109], v[2:5]
	v_mfma_f32_16x16x32_bf16 v[10:13], v[170:173], v[162:165], v[10:13]
	v_mfma_f32_16x16x32_bf16 v[22:25], v[178:181], v[106:109], v[22:25]
	v_mfma_f32_16x16x32_bf16 v[30:33], v[178:181], v[162:165], v[30:33]
	v_mfma_f32_16x16x32_bf16 v[62:65], v[186:189], v[106:109], v[62:65]
	v_mfma_f32_16x16x32_bf16 v[86:89], v[186:189], v[162:165], v[86:89]
	v_mfma_f32_16x16x32_bf16 v[118:121], v[194:197], v[106:109], v[118:121]
	v_mfma_f32_16x16x32_bf16 v[2:5], v[174:177], v[110:113], v[2:5]
	v_mfma_f32_16x16x32_bf16 v[10:13], v[174:177], v[166:169], v[10:13]
	v_mfma_f32_16x16x32_bf16 v[22:25], v[182:185], v[110:113], v[22:25]
	v_mfma_f32_16x16x32_bf16 v[30:33], v[182:185], v[166:169], v[30:33]
	v_mfma_f32_16x16x32_bf16 v[62:65], v[190:193], v[110:113], v[62:65]
	v_mfma_f32_16x16x32_bf16 v[86:89], v[190:193], v[166:169], v[86:89]
	v_mfma_f32_16x16x32_bf16 v[202:205], v[198:201], v[110:113], v[118:121]
	v_mfma_f32_16x16x32_bf16 v[118:121], v[194:197], v[162:165], v[130:133]
	v_mfma_f32_16x16x32_bf16 v[130:133], v[198:201], v[166:169], v[118:121]
	s_barrier
	s_nop 4
	ds_read_b128 v[118:121], v240
	ds_read_b128 v[206:209], v240 offset:1024
	ds_read_b128 v[222:225], v240 offset:2048
	ds_read_b128 v[226:229], v240 offset:3072
	s_barrier
	s_waitcnt lgkmcnt(0)
	v_mfma_f32_16x16x32_bf16 v[58:61], v[186:189], v[118:121], v[58:61]
	v_mfma_f32_16x16x32_bf16 v[6:9], v[170:173], v[118:121], v[6:9]
	v_mfma_f32_16x16x32_bf16 v[14:17], v[170:173], v[222:225], v[14:17]
	v_mfma_f32_16x16x32_bf16 v[170:173], v[190:193], v[206:209], v[58:61]
	v_mfma_f32_16x16x32_bf16 v[58:61], v[186:189], v[222:225], v[82:85]
	v_mfma_f32_16x16x32_bf16 v[6:9], v[174:177], v[206:209], v[6:9]
	v_mfma_f32_16x16x32_bf16 v[14:17], v[174:177], v[226:229], v[14:17]
	v_mfma_f32_16x16x32_bf16 v[18:21], v[178:181], v[118:121], v[18:21]
	v_mfma_f32_16x16x32_bf16 v[26:29], v[178:181], v[222:225], v[26:29]
	v_mfma_f32_16x16x32_bf16 v[174:177], v[190:193], v[226:229], v[58:61]
	v_mfma_f32_16x16x32_bf16 v[58:61], v[194:197], v[118:121], v[114:117]
	v_mfma_f32_16x16x32_bf16 v[18:21], v[182:185], v[206:209], v[18:21]
	v_mfma_f32_16x16x32_bf16 v[26:29], v[182:185], v[226:229], v[26:29]
	v_mfma_f32_16x16x32_bf16 v[178:181], v[198:201], v[206:209], v[58:61]
	v_mfma_f32_16x16x32_bf16 v[58:61], v[194:197], v[222:225], v[126:129]
	v_mfma_f32_16x16x32_bf16 v[182:185], v[198:201], v[226:229], v[58:61]
	s_barrier
; #define LDA(dst, b, h) _Pragma("unroll") for (int m = 0; m < 4; ++m) _Pragma("unroll") for (int k = 0; k < 2; ++k) \
;     dst[m][k] = *reinterpret_cast<const bf16x8*>((char*)SA(b, h) + lds_byte(wr * 64 + m * 16 + fr, k * 32 + fq * 8))
; #define LDB(dst, b, h) _Pragma("unroll") for (int n = 0; n < 2; ++n) _Pragma("unroll") for (int k = 0; k < 2; ++k) \
;     dst[n][k] = *reinterpret_cast<const bf16x8*>((char*)SB(b, h) + lds_byte(wc * 32 + n * 16 + fr, k * 32 + fq * 8))
; #define MMA(ai, bj, At_, Bt_) do { __builtin_amdgcn_s_setprio(1); \
;     _Pragma("unroll") for (int m = 0; m < 4; ++m) _Pragma("unroll") for (int n = 0; n < 2; ++n) _Pragma("unroll") for (int k = 0; k < 2; ++k) \
;       acc[ai][bj][m][n] = __builtin_amdgcn_mfma_f32_16x16x32_bf16(At_[m][k], Bt_[n][k], acc[ai][bj][m][n], 0, 0, 0); \
;     __builtin_amdgcn_s_setprio(0); } while (0)
; #define WAIT_V(n) asm volatile("s_waitcnt vmcnt(" #n ")" ::: "memory")
; #define WAIT_L(n) asm volatile("s_waitcnt lgkmcnt(" #n ")" ::: "memory")
; #define BAR __builtin_amdgcn_s_barrier()
; template <class Epi> ...
;     ...
;     LDA(At, 0, 1); WAIT_V(4); BAR; WAIT_L(0); MMA(1, 0, At, B0); MMA(1, 1, At, B1); BAR; }
;   { LDB(B0, 1, 0); LDA(At, 1, 0); WAIT_V(2); BAR; WAIT_L(0); MMA(0, 0, At, B0); BAR;
	s_nop 4
	ds_read_b128 v[58:61], v236 offset:16384
	ds_read_b128 v[82:85], v236 offset:17408
	ds_read_b128 v[114:117], v237 offset:16384
	ds_read_b128 v[126:129], v237 offset:17408
	ds_read_b128 v[186:189], v238 offset:16384
	ds_read_b128 v[190:193], v238 offset:17408
	ds_read_b128 v[194:197], v239 offset:16384
	ds_read_b128 v[198:201], v239 offset:17408
	s_waitcnt vmcnt(4)
	s_barrier
	s_waitcnt lgkmcnt(0)
	v_mfma_f32_16x16x32_bf16 v[48:51], v[114:117], v[106:109], v[50:53]
	v_mfma_f32_16x16x32_bf16 v[244:247], v[126:129], v[110:113], v[48:51]
	v_mfma_f32_16x16x32_bf16 v[48:51], v[114:117], v[162:165], v[54:57]
	v_mfma_f32_16x16x32_bf16 v[248:251], v[126:129], v[166:169], v[48:51]
	v_mfma_f32_16x16x32_bf16 v[48:51], v[186:189], v[106:109], v[78:81]
	v_mfma_f32_16x16x32_bf16 v[214:217], v[190:193], v[110:113], v[48:51]
	v_mfma_f32_16x16x32_bf16 v[48:51], v[186:189], v[162:165], v[142:145]
	v_mfma_f32_16x16x32_bf16 v[122:125], v[58:61], v[106:109], v[122:125]
	v_mfma_f32_16x16x32_bf16 v[142:145], v[190:193], v[166:169], v[48:51]
	v_mfma_f32_16x16x32_bf16 v[48:51], v[194:197], v[106:109], v[102:105]
	v_mfma_f32_16x16x32_bf16 v[230:233], v[82:85], v[110:113], v[122:125]
	v_mfma_f32_16x16x32_bf16 v[122:125], v[58:61], v[162:165], v[138:141]
	v_mfma_f32_16x16x32_bf16 v[210:213], v[198:201], v[110:113], v[48:51]
	v_mfma_f32_16x16x32_bf16 v[48:51], v[194:197], v[162:165], v[146:149]
	v_mfma_f32_16x16x32_bf16 v[138:141], v[82:85], v[166:169], v[122:125]
	v_mfma_f32_16x16x32_bf16 v[146:149], v[198:201], v[166:169], v[48:51]
	v_mfma_f32_16x16x32_bf16 v[34:37], v[58:61], v[222:225], v[36:39]
	v_mfma_f32_16x16x32_bf16 v[162:165], v[82:85], v[226:229], v[34:37]
	v_mfma_f32_16x16x32_bf16 v[34:37], v[114:117], v[118:121], v[40:43]
	v_mfma_f32_16x16x32_bf16 v[48:51], v[58:61], v[118:121], v[134:137]
	v_mfma_f32_16x16x32_bf16 v[166:169], v[126:129], v[206:209], v[34:37]
	v_mfma_f32_16x16x32_bf16 v[34:37], v[114:117], v[222:225], v[44:47]
	v_mfma_f32_16x16x32_bf16 v[134:137], v[82:85], v[206:209], v[48:51]
	v_mfma_f32_16x16x32_bf16 v[46:49], v[126:129], v[226:229], v[34:37]
	v_mfma_f32_16x16x32_bf16 v[34:37], v[186:189], v[118:121], v[74:77]
	v_mfma_f32_16x16x32_bf16 v[218:221], v[190:193], v[206:209], v[34:37]
	v_mfma_f32_16x16x32_bf16 v[34:37], v[186:189], v[222:225], v[68:71]
	v_mfma_f32_16x16x32_bf16 v[186:189], v[190:193], v[226:229], v[34:37]
	v_mfma_f32_16x16x32_bf16 v[34:37], v[194:197], v[118:121], v[98:101]
	v_mfma_f32_16x16x32_bf16 v[190:193], v[198:201], v[206:209], v[34:37]
	v_mfma_f32_16x16x32_bf16 v[34:37], v[194:197], v[222:225], v[92:95]
	v_mfma_f32_16x16x32_bf16 v[194:197], v[198:201], v[226:229], v[34:37]
	s_barrier
	ds_read_b128 v[42:45], v241
	ds_read_b128 v[66:69], v241 offset:1024
	ds_read_b128 v[70:73], v241 offset:2048
	ds_read_b128 v[198:201], v241 offset:3072
	s_nop 0
	ds_read_b128 v[34:37], v236 offset:32768
	ds_read_b128 v[38:41], v236 offset:33792
	ds_read_b128 v[50:53], v237 offset:32768
	ds_read_b128 v[54:57], v237 offset:33792
	ds_read_b128 v[74:77], v238 offset:32768
	ds_read_b128 v[78:81], v238 offset:33792
	ds_read_b128 v[206:209], v239 offset:32768
	ds_read_b128 v[222:225], v239 offset:33792
	s_waitcnt vmcnt(2)
	s_barrier
	s_waitcnt lgkmcnt(0)
	v_mfma_f32_16x16x32_bf16 v[2:5], v[34:37], v[42:45], v[2:5]
	v_mfma_f32_16x16x32_bf16 v[114:117], v[38:41], v[66:69], v[2:5]
	v_mfma_f32_16x16x32_bf16 v[2:5], v[34:37], v[70:73], v[10:13]
	v_mfma_f32_16x16x32_bf16 v[118:121], v[38:41], v[198:201], v[2:5]
	v_mfma_f32_16x16x32_bf16 v[2:5], v[50:53], v[42:45], v[22:25]
	v_mfma_f32_16x16x32_bf16 v[98:101], v[54:57], v[66:69], v[2:5]
	v_mfma_f32_16x16x32_bf16 v[2:5], v[50:53], v[70:73], v[30:33]
	v_mfma_f32_16x16x32_bf16 v[102:105], v[54:57], v[198:201], v[2:5]
	v_mfma_f32_16x16x32_bf16 v[2:5], v[74:77], v[42:45], v[62:65]
	v_mfma_f32_16x16x32_bf16 v[82:85], v[78:81], v[66:69], v[2:5]
	v_mfma_f32_16x16x32_bf16 v[2:5], v[74:77], v[70:73], v[86:89]
	v_mfma_f32_16x16x32_bf16 v[86:89], v[78:81], v[198:201], v[2:5]
	v_mfma_f32_16x16x32_bf16 v[2:5], v[206:209], v[42:45], v[202:205]
	v_mfma_f32_16x16x32_bf16 v[58:61], v[222:225], v[66:69], v[2:5]
	v_mfma_f32_16x16x32_bf16 v[2:5], v[206:209], v[70:73], v[130:133]
	v_mfma_f32_16x16x32_bf16 v[62:65], v[222:225], v[198:201], v[2:5]
	s_barrier
; #define LDA(dst, b, h) _Pragma("unroll") for (int m = 0; m < 4; ++m) _Pragma("unroll") for (int k = 0; k < 2; ++k) \
;     dst[m][k] = *reinterpret_cast<const bf16x8*>((char*)SA(b, h) + lds_byte(wr * 64 + m * 16 + fr, k * 32 + fq * 8))
; #define LDB(dst, b, h) _Pragma("unroll") for (int n = 0; n < 2; ++n) _Pragma("unroll") for (int k = 0; k < 2; ++k) \
;     dst[n][k] = *reinterpret_cast<const bf16x8*>((char*)SB(b, h) + lds_byte(wc * 32 + n * 16 + fr, k * 32 + fq * 8))
; #define MMA(ai, bj, At_, Bt_) do { __builtin_amdgcn_s_setprio(1); \
;     _Pragma("unroll") for (int m = 0; m < 4; ++m) _Pragma("unroll") for (int n = 0; n < 2; ++n) _Pragma("unroll") for (int k = 0; k < 2; ++k) \
;       acc[ai][bj][m][n] = __builtin_amdgcn_mfma_f32_16x16x32_bf16(At_[m][k], Bt_[n][k], acc[ai][bj][m][n], 0, 0, 0); \
;     __builtin_amdgcn_s_setprio(0); } while (0)
; #define WAIT_V(n) asm volatile("s_waitcnt vmcnt(" #n ")" ::: "memory")
; #define WAIT_L(n) asm volatile("s_waitcnt lgkmcnt(" #n ")" ::: "memory")
; #define BAR __builtin_amdgcn_s_barrier()
; template <class Epi> ...
;     ...
;     LDB(B1, 1, 1); WAIT_V(0); BAR; WAIT_L(0); MMA(0, 1, At, B1); BAR;
;     LDA(At, 1, 1); BAR; WAIT_L(0); MMA(1, 0, At, B0); MMA(1, 1, At, B1); BAR; }
;   if (wr == 0) BAR;
	ds_read_b128 v[10:13], v242
	ds_read_b128 v[130:133], v242 offset:1024
	ds_read_b128 v[202:205], v242 offset:2048
	ds_read_b128 v[226:229], v242 offset:3072
	s_waitcnt vmcnt(0)
	s_barrier
	s_waitcnt lgkmcnt(0)
	v_mfma_f32_16x16x32_bf16 v[2:5], v[34:37], v[10:13], v[6:9]
	v_mfma_f32_16x16x32_bf16 v[122:125], v[38:41], v[130:133], v[2:5]
	v_mfma_f32_16x16x32_bf16 v[2:5], v[34:37], v[202:205], v[14:17]
	v_mfma_f32_16x16x32_bf16 v[126:129], v[38:41], v[226:229], v[2:5]
	v_mfma_f32_16x16x32_bf16 v[2:5], v[50:53], v[10:13], v[18:21]
	v_mfma_f32_16x16x32_bf16 v[106:109], v[54:57], v[130:133], v[2:5]
	v_mfma_f32_16x16x32_bf16 v[2:5], v[50:53], v[202:205], v[26:29]
	v_mfma_f32_16x16x32_bf16 v[110:113], v[54:57], v[226:229], v[2:5]
	v_mfma_f32_16x16x32_bf16 v[2:5], v[74:77], v[10:13], v[170:173]
	v_mfma_f32_16x16x32_bf16 v[90:93], v[78:81], v[130:133], v[2:5]
	v_mfma_f32_16x16x32_bf16 v[2:5], v[74:77], v[202:205], v[174:177]
	v_mfma_f32_16x16x32_bf16 v[94:97], v[78:81], v[226:229], v[2:5]
	v_mfma_f32_16x16x32_bf16 v[2:5], v[206:209], v[10:13], v[178:181]
	v_mfma_f32_16x16x32_bf16 v[74:77], v[222:225], v[130:133], v[2:5]
	v_mfma_f32_16x16x32_bf16 v[2:5], v[206:209], v[202:205], v[182:185]
	v_mfma_f32_16x16x32_bf16 v[78:81], v[222:225], v[226:229], v[2:5]
	s_barrier
	ds_read_b128 v[14:17], v236 offset:49152
	ds_read_b128 v[26:29], v236 offset:50176
	ds_read_b128 v[30:33], v237 offset:49152
	ds_read_b128 v[170:173], v237 offset:50176
	ds_read_b128 v[174:177], v238 offset:49152
	ds_read_b128 v[178:181], v238 offset:50176
	ds_read_b128 v[182:185], v239 offset:49152
	ds_read_b128 v[206:209], v239 offset:50176
	s_barrier
	s_waitcnt lgkmcnt(0)
	v_mfma_f32_16x16x32_bf16 v[2:5], v[14:17], v[42:45], v[230:233]
	v_mfma_f32_16x16x32_bf16 v[50:53], v[26:29], v[66:69], v[2:5]
	v_mfma_f32_16x16x32_bf16 v[2:5], v[14:17], v[70:73], v[138:141]
	v_mfma_f32_16x16x32_bf16 v[54:57], v[26:29], v[198:201], v[2:5]
	v_mfma_f32_16x16x32_bf16 v[2:5], v[30:33], v[42:45], v[244:247]
	v_mfma_f32_16x16x32_bf16 v[34:37], v[170:173], v[66:69], v[2:5]
	v_mfma_f32_16x16x32_bf16 v[2:5], v[30:33], v[70:73], v[248:251]
	v_mfma_f32_16x16x32_bf16 v[38:41], v[170:173], v[198:201], v[2:5]
	v_mfma_f32_16x16x32_bf16 v[2:5], v[174:177], v[42:45], v[214:217]
	v_mfma_f32_16x16x32_bf16 v[18:21], v[178:181], v[66:69], v[2:5]
	v_mfma_f32_16x16x32_bf16 v[2:5], v[174:177], v[70:73], v[142:145]
	v_mfma_f32_16x16x32_bf16 v[22:25], v[178:181], v[198:201], v[2:5]
	v_mfma_f32_16x16x32_bf16 v[2:5], v[182:185], v[42:45], v[210:213]
	v_mfma_f32_16x16x32_bf16 v[6:9], v[182:185], v[70:73], v[146:149]
	v_mfma_f32_16x16x32_bf16 v[2:5], v[206:209], v[66:69], v[2:5]
	v_mfma_f32_16x16x32_bf16 v[6:9], v[206:209], v[198:201], v[6:9]
	v_mfma_f32_16x16x32_bf16 v[42:45], v[14:17], v[10:13], v[134:137]
	v_mfma_f32_16x16x32_bf16 v[14:17], v[14:17], v[202:205], v[162:165]
	v_mfma_f32_16x16x32_bf16 v[70:73], v[26:29], v[226:229], v[14:17]
	v_mfma_f32_16x16x32_bf16 v[14:17], v[30:33], v[10:13], v[166:169]
	v_mfma_f32_16x16x32_bf16 v[66:69], v[26:29], v[130:133], v[42:45]
	v_mfma_f32_16x16x32_bf16 v[42:45], v[170:173], v[130:133], v[14:17]
	v_mfma_f32_16x16x32_bf16 v[14:17], v[30:33], v[202:205], v[46:49]
	v_mfma_f32_16x16x32_bf16 v[46:49], v[170:173], v[226:229], v[14:17]
	v_mfma_f32_16x16x32_bf16 v[14:17], v[174:177], v[10:13], v[218:221]
	v_mfma_f32_16x16x32_bf16 v[26:29], v[178:181], v[130:133], v[14:17]
	v_mfma_f32_16x16x32_bf16 v[14:17], v[174:177], v[202:205], v[186:189]
	v_mfma_f32_16x16x32_bf16 v[30:33], v[178:181], v[226:229], v[14:17]
	v_mfma_f32_16x16x32_bf16 v[10:13], v[182:185], v[10:13], v[190:193]
	v_mfma_f32_16x16x32_bf16 v[14:17], v[182:185], v[202:205], v[194:197]
	v_mfma_f32_16x16x32_bf16 v[10:13], v[206:209], v[130:133], v[10:13]
	v_mfma_f32_16x16x32_bf16 v[14:17], v[206:209], v[226:229], v[14:17]
	s_barrier
	s_and_saveexec_b64 s[22:23], s[6:7]
	s_cbranch_execz .LBB0_73
	s_barrier
	s_branch .LBB0_73

; #define STAGE(P, BASE, br, kt) do { const char* _gb = (const char*)((BASE) + ((long)(br) * K + (long)(kt) * BK)); \
;     __builtin_amdgcn_global_load_lds((const unsigned*)(_gb + (size_t)so0), (unsigned*)((char*)(P) + wv1k), 16, 0, 0); \
;     __builtin_amdgcn_global_load_lds((const unsigned*)(_gb + (size_t)so1), (unsigned*)((char*)(P) + wv1k + 8192), 16, 0, 0); } while (0)
; #define LDA(dst, b, h) _Pragma("unroll") for (int m = 0; m < 4; ++m) _Pragma("unroll") for (int k = 0; k < 2; ++k) \
;     dst[m][k] = *reinterpret_cast<const bf16x8*>((char*)SA(b, h) + lds_byte(wr * 64 + m * 16 + fr, k * 32 + fq * 8))
; #define LDB(dst, b, h) _Pragma("unroll") for (int n = 0; n < 2; ++n) _Pragma("unroll") for (int k = 0; k < 2; ++k) \
;     dst[n][k] = *reinterpret_cast<const bf16x8*>((char*)SB(b, h) + lds_byte(wc * 32 + n * 16 + fr, k * 32 + fq * 8))
; #define MMA(ai, bj, At_, Bt_) do { __builtin_amdgcn_s_setprio(1); \
;     _Pragma("unroll") for (int m = 0; m < 4; ++m) _Pragma("unroll") for (int n = 0; n < 2; ++n) _Pragma("unroll") for (int k = 0; k < 2; ++k) \
;       acc[ai][bj][m][n] = __builtin_amdgcn_mfma_f32_16x16x32_bf16(At_[m][k], Bt_[n][k], acc[ai][bj][m][n], 0, 0, 0); \
;     __builtin_amdgcn_s_setprio(0); } while (0)
; #define WAIT_L(n) asm volatile("s_waitcnt lgkmcnt(" #n ")" ::: "memory")
; #define BAR __builtin_amdgcn_s_barrier()
; #define SCHED __builtin_amdgcn_sched_barrier(0)
; template <class Epi> ...
;     ...
;   for (int t = 0; t < nt - 2; t += 2) {
;     LDB(B0, 0, 0); SCHED; LDA(At, 0, 0); STAGE(SA(1, 1), A, brow + HALF, t + 1);
;     WAIT_L(8); BAR; WAIT_L(0); MMA(0, 0, At, B0); BAR; SCHED;
;     LDB(B1, 0, 1); STAGE(SB(0, 0), Bt, bcol, t + 2);
;     BAR; WAIT_L(0); MMA(0, 1, At, B1); BAR;
;     LDA(At, 0, 1); STAGE(SA(0, 0), A, brow, t + 2);
;     BAR; WAIT_L(0); MMA(1, 0, At, B0); BAR; SCHED;
.LBB0_115:
	ds_read_b128 v[106:109], v208
	ds_read_b128 v[110:113], v208 offset:1024
	ds_read_b128 v[162:165], v208 offset:2048
	ds_read_b128 v[166:169], v208 offset:3072
	v_lshl_add_u64 v[206:207], v[72:73], 0, s[22:23]
	s_add_i32 s26, s21, 0xc000
	v_lshl_add_u64 v[90:91], v[206:207], 0, s[28:29]
	s_mov_b32 m0, s26
	v_lshl_add_u64 v[224:225], v[66:67], 0, s[22:23]
	s_add_i32 s25, s21, 0xe000
	ds_read_b128 v[170:173], v209
	ds_read_b128 v[174:177], v209 offset:1024
	ds_read_b128 v[178:181], v210
	ds_read_b128 v[182:185], v210 offset:1024
	ds_read_b128 v[186:189], v211
	ds_read_b128 v[190:193], v211 offset:1024
	ds_read_b128 v[194:197], v235
	ds_read_b128 v[198:201], v235 offset:1024
	global_load_lds_dwordx4 v[90:91], off
	v_lshl_add_u64 v[90:91], v[224:225], 0, s[28:29]
	s_mov_b32 m0, s25
	s_nop 0
	global_load_lds_dwordx4 v[90:91], off
	s_waitcnt lgkmcnt(8)
	s_barrier
	s_waitcnt lgkmcnt(0)
	v_mfma_f32_16x16x32_bf16 v[2:5], v[170:173], v[106:109], v[2:5]
	v_mfma_f32_16x16x32_bf16 v[10:13], v[170:173], v[162:165], v[10:13]
	v_mfma_f32_16x16x32_bf16 v[22:25], v[178:181], v[106:109], v[22:25]
	v_mfma_f32_16x16x32_bf16 v[30:33], v[178:181], v[162:165], v[30:33]
	v_mfma_f32_16x16x32_bf16 v[62:65], v[186:189], v[106:109], v[62:65]
	v_mfma_f32_16x16x32_bf16 v[86:89], v[186:189], v[162:165], v[86:89]
	v_mfma_f32_16x16x32_bf16 v[118:121], v[194:197], v[106:109], v[118:121]
	v_mfma_f32_16x16x32_bf16 v[130:133], v[194:197], v[162:165], v[130:133]
	v_mfma_f32_16x16x32_bf16 v[2:5], v[174:177], v[110:113], v[2:5]
	v_mfma_f32_16x16x32_bf16 v[10:13], v[174:177], v[166:169], v[10:13]
	v_mfma_f32_16x16x32_bf16 v[22:25], v[182:185], v[110:113], v[22:25]
	v_mfma_f32_16x16x32_bf16 v[30:33], v[182:185], v[166:169], v[30:33]
	v_mfma_f32_16x16x32_bf16 v[62:65], v[190:193], v[110:113], v[62:65]
	v_mfma_f32_16x16x32_bf16 v[86:89], v[190:193], v[166:169], v[86:89]
	v_mfma_f32_16x16x32_bf16 v[118:121], v[198:201], v[110:113], v[118:121]
	v_mfma_f32_16x16x32_bf16 v[130:133], v[198:201], v[166:169], v[130:133]
	s_barrier
	v_lshl_add_u64 v[226:227], v[48:49], 0, s[22:23]
	s_mov_b32 m0, s42
	v_lshl_add_u64 v[90:91], v[226:227], 0, s[0:1]
	v_lshl_add_u64 v[228:229], v[34:35], 0, s[22:23]
	ds_read_b128 v[202:205], v236
	ds_read_b128 v[212:215], v236 offset:1024
	ds_read_b128 v[216:219], v236 offset:2048
	ds_read_b128 v[220:223], v236 offset:3072
	global_load_lds_dwordx4 v[90:91], off
	v_lshl_add_u64 v[90:91], v[228:229], 0, s[0:1]
	s_mov_b32 m0, s43
	s_nop 0
	global_load_lds_dwordx4 v[90:91], off
	s_barrier
	s_waitcnt lgkmcnt(0)
	v_mfma_f32_16x16x32_bf16 v[6:9], v[170:173], v[202:205], v[6:9]
	v_mfma_f32_16x16x32_bf16 v[14:17], v[170:173], v[216:219], v[14:17]
	v_mfma_f32_16x16x32_bf16 v[18:21], v[178:181], v[202:205], v[18:21]
	v_mfma_f32_16x16x32_bf16 v[26:29], v[178:181], v[216:219], v[26:29]
	v_mfma_f32_16x16x32_bf16 v[58:61], v[186:189], v[202:205], v[58:61]
	v_mfma_f32_16x16x32_bf16 v[82:85], v[186:189], v[216:219], v[82:85]
	v_mfma_f32_16x16x32_bf16 v[114:117], v[194:197], v[202:205], v[114:117]
	v_mfma_f32_16x16x32_bf16 v[126:129], v[194:197], v[216:219], v[126:129]
	v_mfma_f32_16x16x32_bf16 v[6:9], v[174:177], v[212:215], v[6:9]
	v_mfma_f32_16x16x32_bf16 v[14:17], v[174:177], v[220:223], v[14:17]
	v_mfma_f32_16x16x32_bf16 v[18:21], v[182:185], v[212:215], v[18:21]
	v_mfma_f32_16x16x32_bf16 v[26:29], v[182:185], v[220:223], v[26:29]
	v_mfma_f32_16x16x32_bf16 v[58:61], v[190:193], v[212:215], v[58:61]
	v_mfma_f32_16x16x32_bf16 v[82:85], v[190:193], v[220:223], v[82:85]
	v_mfma_f32_16x16x32_bf16 v[114:117], v[198:201], v[212:215], v[114:117]
	v_mfma_f32_16x16x32_bf16 v[126:129], v[198:201], v[220:223], v[126:129]
	s_mov_b32 m0, s21
	v_lshl_add_u64 v[90:91], v[206:207], 0, s[0:1]
	s_barrier
	ds_read_b128 v[170:173], v209 offset:16384
	ds_read_b128 v[174:177], v209 offset:17408
	ds_read_b128 v[178:181], v210 offset:16384
	ds_read_b128 v[182:185], v210 offset:17408
	ds_read_b128 v[186:189], v211 offset:16384
	ds_read_b128 v[190:193], v211 offset:17408
	ds_read_b128 v[194:197], v235 offset:16384
	ds_read_b128 v[198:201], v235 offset:17408
	global_load_lds_dwordx4 v[90:91], off
	v_lshl_add_u64 v[90:91], v[224:225], 0, s[0:1]
	s_mov_b32 m0, s17
	s_nop 0
	global_load_lds_dwordx4 v[90:91], off
	s_barrier
	s_waitcnt lgkmcnt(0)
	v_mfma_f32_16x16x32_bf16 v[122:125], v[170:173], v[106:109], v[122:125]
	v_mfma_f32_16x16x32_bf16 v[138:141], v[170:173], v[162:165], v[138:141]
	v_mfma_f32_16x16x32_bf16 v[50:53], v[178:181], v[106:109], v[50:53]
	v_mfma_f32_16x16x32_bf16 v[54:57], v[178:181], v[162:165], v[54:57]
	v_mfma_f32_16x16x32_bf16 v[78:81], v[186:189], v[106:109], v[78:81]
	v_mfma_f32_16x16x32_bf16 v[142:145], v[186:189], v[162:165], v[142:145]
	v_mfma_f32_16x16x32_bf16 v[102:105], v[194:197], v[106:109], v[102:105]
	v_mfma_f32_16x16x32_bf16 v[122:125], v[174:177], v[110:113], v[122:125]
	v_mfma_f32_16x16x32_bf16 v[138:141], v[174:177], v[166:169], v[138:141]
	v_mfma_f32_16x16x32_bf16 v[50:53], v[182:185], v[110:113], v[50:53]
	v_mfma_f32_16x16x32_bf16 v[54:57], v[182:185], v[166:169], v[54:57]
	v_mfma_f32_16x16x32_bf16 v[78:81], v[190:193], v[110:113], v[78:81]
	v_mfma_f32_16x16x32_bf16 v[142:145], v[190:193], v[166:169], v[142:145]
	v_mfma_f32_16x16x32_bf16 v[102:105], v[198:201], v[110:113], v[102:105]
	v_mfma_f32_16x16x32_bf16 v[106:109], v[194:197], v[162:165], v[146:149]
	v_mfma_f32_16x16x32_bf16 v[106:109], v[198:201], v[166:169], v[106:109]
	s_barrier
	s_mov_b32 m0, s44
	v_lshl_add_u64 v[90:91], v[226:227], 0, s[56:57]
	global_load_lds_dwordx4 v[90:91], off
	v_lshl_add_u64 v[90:91], v[228:229], 0, s[56:57]
	s_mov_b32 m0, s45
	s_nop 0
	global_load_lds_dwordx4 v[90:91], off
	s_waitcnt vmcnt(6)
	s_barrier
; #define STAGE(P, BASE, br, kt) do { const char* _gb = (const char*)((BASE) + ((long)(br) * K + (long)(kt) * BK)); \
;     __builtin_amdgcn_global_load_lds((const unsigned*)(_gb + (size_t)so0), (unsigned*)((char*)(P) + wv1k), 16, 0, 0); \
;     __builtin_amdgcn_global_load_lds((const unsigned*)(_gb + (size_t)so1), (unsigned*)((char*)(P) + wv1k + 8192), 16, 0, 0); } while (0)
; #define LDA(dst, b, h) _Pragma("unroll") for (int m = 0; m < 4; ++m) _Pragma("unroll") for (int k = 0; k < 2; ++k) \
;     dst[m][k] = *reinterpret_cast<const bf16x8*>((char*)SA(b, h) + lds_byte(wr * 64 + m * 16 + fr, k * 32 + fq * 8))
; #define LDB(dst, b, h) _Pragma("unroll") for (int n = 0; n < 2; ++n) _Pragma("unroll") for (int k = 0; k < 2; ++k) \
;     dst[n][k] = *reinterpret_cast<const bf16x8*>((char*)SB(b, h) + lds_byte(wc * 32 + n * 16 + fr, k * 32 + fq * 8))
; #define MMA(ai, bj, At_, Bt_) do { __builtin_amdgcn_s_setprio(1); \
;     _Pragma("unroll") for (int m = 0; m < 4; ++m) _Pragma("unroll") for (int n = 0; n < 2; ++n) _Pragma("unroll") for (int k = 0; k < 2; ++k) \
;       acc[ai][bj][m][n] = __builtin_amdgcn_mfma_f32_16x16x32_bf16(At_[m][k], Bt_[n][k], acc[ai][bj][m][n], 0, 0, 0); \
;     __builtin_amdgcn_s_setprio(0); } while (0)
; #define WAIT_V(n) asm volatile("s_waitcnt vmcnt(" #n ")" ::: "memory")
; #define WAIT_L(n) asm volatile("s_waitcnt lgkmcnt(" #n ")" ::: "memory")
; #define BAR __builtin_amdgcn_s_barrier()
; #define SCHED __builtin_amdgcn_sched_barrier(0)
; template <class Epi> ...
;     ...
;     WAIT_V(6); BAR; MMA(1, 1, At, B1); BAR;
;     LDB(B0, 1, 0); SCHED; LDA(At, 1, 0); STAGE(SA(0, 1), A, brow + HALF, t + 2);
;     WAIT_L(8); BAR; WAIT_L(0); MMA(0, 0, At, B0); BAR; SCHED;
;     LDB(B1, 1, 1); STAGE(SB(1, 0), Bt, bcol, t + 3);
;     BAR; WAIT_L(0); MMA(0, 1, At, B1); BAR;
;     LDA(At, 1, 1); STAGE(SA(1, 0), A, brow, t + 3);
;     BAR; WAIT_L(0); MMA(1, 0, At, B0); BAR; SCHED;
	v_mfma_f32_16x16x32_bf16 v[36:39], v[170:173], v[216:219], v[36:39]
	v_mfma_f32_16x16x32_bf16 v[40:43], v[178:181], v[202:205], v[40:43]
	v_mfma_f32_16x16x32_bf16 v[44:47], v[178:181], v[216:219], v[44:47]
	v_mfma_f32_16x16x32_bf16 v[74:77], v[186:189], v[202:205], v[74:77]
	v_mfma_f32_16x16x32_bf16 v[68:71], v[186:189], v[216:219], v[68:71]
	v_mfma_f32_16x16x32_bf16 v[96:99], v[194:197], v[202:205], v[98:101]
	v_mfma_f32_16x16x32_bf16 v[90:93], v[194:197], v[216:219], v[92:95]
	v_mfma_f32_16x16x32_bf16 v[110:113], v[170:173], v[202:205], v[134:137]
	v_mfma_f32_16x16x32_bf16 v[36:39], v[174:177], v[220:223], v[36:39]
	v_mfma_f32_16x16x32_bf16 v[40:43], v[182:185], v[212:215], v[40:43]
	v_mfma_f32_16x16x32_bf16 v[44:47], v[182:185], v[220:223], v[44:47]
	v_mfma_f32_16x16x32_bf16 v[74:77], v[190:193], v[212:215], v[74:77]
	v_mfma_f32_16x16x32_bf16 v[68:71], v[190:193], v[220:223], v[68:71]
	v_mfma_f32_16x16x32_bf16 v[96:99], v[198:201], v[212:215], v[96:99]
	v_mfma_f32_16x16x32_bf16 v[90:93], v[198:201], v[220:223], v[90:93]
	v_mfma_f32_16x16x32_bf16 v[110:113], v[174:177], v[212:215], v[110:113]
	s_barrier
	ds_read_b128 v[134:137], v237
	ds_read_b128 v[146:149], v237 offset:1024
	ds_read_b128 v[162:165], v237 offset:2048
	ds_read_b128 v[166:169], v237 offset:3072
	s_mov_b32 m0, s46
	v_lshl_add_u64 v[94:95], v[206:207], 0, s[56:57]
	ds_read_b128 v[170:173], v209 offset:32768
	ds_read_b128 v[174:177], v209 offset:33792
	ds_read_b128 v[178:181], v210 offset:32768
	ds_read_b128 v[182:185], v210 offset:33792
	ds_read_b128 v[186:189], v211 offset:32768
	ds_read_b128 v[190:193], v211 offset:33792
	ds_read_b128 v[194:197], v235 offset:32768
	ds_read_b128 v[198:201], v235 offset:33792
	global_load_lds_dwordx4 v[94:95], off
	v_lshl_add_u64 v[94:95], v[224:225], 0, s[56:57]
	s_mov_b32 m0, s47
	s_nop 0
	global_load_lds_dwordx4 v[94:95], off
	s_waitcnt lgkmcnt(8)
	s_barrier
	s_waitcnt lgkmcnt(0)
	v_mfma_f32_16x16x32_bf16 v[2:5], v[170:173], v[134:137], v[2:5]
	v_mfma_f32_16x16x32_bf16 v[10:13], v[170:173], v[162:165], v[10:13]
	v_mfma_f32_16x16x32_bf16 v[22:25], v[178:181], v[134:137], v[22:25]
	v_mfma_f32_16x16x32_bf16 v[30:33], v[178:181], v[162:165], v[30:33]
	v_mfma_f32_16x16x32_bf16 v[62:65], v[186:189], v[134:137], v[62:65]
	v_mfma_f32_16x16x32_bf16 v[86:89], v[186:189], v[162:165], v[86:89]
	v_mfma_f32_16x16x32_bf16 v[118:121], v[194:197], v[134:137], v[118:121]
	v_mfma_f32_16x16x32_bf16 v[130:133], v[194:197], v[162:165], v[130:133]
	v_mfma_f32_16x16x32_bf16 v[2:5], v[174:177], v[146:149], v[2:5]
	v_mfma_f32_16x16x32_bf16 v[10:13], v[174:177], v[166:169], v[10:13]
	v_mfma_f32_16x16x32_bf16 v[22:25], v[182:185], v[146:149], v[22:25]
	v_mfma_f32_16x16x32_bf16 v[30:33], v[182:185], v[166:169], v[30:33]
	v_mfma_f32_16x16x32_bf16 v[62:65], v[190:193], v[146:149], v[62:65]
	v_mfma_f32_16x16x32_bf16 v[86:89], v[190:193], v[166:169], v[86:89]
	v_mfma_f32_16x16x32_bf16 v[118:121], v[198:201], v[146:149], v[118:121]
	v_mfma_f32_16x16x32_bf16 v[130:133], v[198:201], v[166:169], v[130:133]
	s_barrier
	s_mov_b32 m0, s30
	v_lshl_add_u64 v[94:95], v[226:227], 0, s[90:91]
	ds_read_b128 v[202:205], v238
	ds_read_b128 v[212:215], v238 offset:1024
	ds_read_b128 v[216:219], v238 offset:2048
	ds_read_b128 v[220:223], v238 offset:3072
	global_load_lds_dwordx4 v[94:95], off
	v_lshl_add_u64 v[94:95], v[228:229], 0, s[90:91]
	s_mov_b32 m0, s31
	s_nop 0
	global_load_lds_dwordx4 v[94:95], off
	s_barrier
	s_waitcnt lgkmcnt(0)
	v_mfma_f32_16x16x32_bf16 v[6:9], v[170:173], v[202:205], v[6:9]
	v_mfma_f32_16x16x32_bf16 v[14:17], v[170:173], v[216:219], v[14:17]
	v_mfma_f32_16x16x32_bf16 v[18:21], v[178:181], v[202:205], v[18:21]
	v_mfma_f32_16x16x32_bf16 v[26:29], v[178:181], v[216:219], v[26:29]
	v_mfma_f32_16x16x32_bf16 v[58:61], v[186:189], v[202:205], v[58:61]
	v_mfma_f32_16x16x32_bf16 v[82:85], v[186:189], v[216:219], v[82:85]
	v_mfma_f32_16x16x32_bf16 v[114:117], v[194:197], v[202:205], v[114:117]
	v_mfma_f32_16x16x32_bf16 v[126:129], v[194:197], v[216:219], v[126:129]
	v_mfma_f32_16x16x32_bf16 v[6:9], v[174:177], v[212:215], v[6:9]
	v_mfma_f32_16x16x32_bf16 v[14:17], v[174:177], v[220:223], v[14:17]
	v_mfma_f32_16x16x32_bf16 v[18:21], v[182:185], v[212:215], v[18:21]
	v_mfma_f32_16x16x32_bf16 v[26:29], v[182:185], v[220:223], v[26:29]
	v_mfma_f32_16x16x32_bf16 v[58:61], v[190:193], v[212:215], v[58:61]
	v_mfma_f32_16x16x32_bf16 v[82:85], v[190:193], v[220:223], v[82:85]
	v_mfma_f32_16x16x32_bf16 v[114:117], v[198:201], v[212:215], v[114:117]
	v_mfma_f32_16x16x32_bf16 v[126:129], v[198:201], v[220:223], v[126:129]
	s_mov_b32 m0, s51
	v_lshl_add_u64 v[94:95], v[206:207], 0, s[90:91]
	s_barrier
	ds_read_b128 v[170:173], v209 offset:49152
	ds_read_b128 v[174:177], v209 offset:50176
	ds_read_b128 v[178:181], v210 offset:49152
	ds_read_b128 v[182:185], v210 offset:50176
	ds_read_b128 v[186:189], v211 offset:49152
	ds_read_b128 v[190:193], v211 offset:50176
	ds_read_b128 v[194:197], v235 offset:49152
	ds_read_b128 v[198:201], v235 offset:50176
	global_load_lds_dwordx4 v[94:95], off
	v_lshl_add_u64 v[94:95], v[224:225], 0, s[90:91]
	s_mov_b32 m0, s52
	s_nop 0
	global_load_lds_dwordx4 v[94:95], off
	s_barrier
; #define STAGE(P, BASE, br, kt) do { const char* _gb = (const char*)((BASE) + ((long)(br) * K + (long)(kt) * BK)); \
;     __builtin_amdgcn_global_load_lds((const unsigned*)(_gb + (size_t)so0), (unsigned*)((char*)(P) + wv1k), 16, 0, 0); \
;     __builtin_amdgcn_global_load_lds((const unsigned*)(_gb + (size_t)so1), (unsigned*)((char*)(P) + wv1k + 8192), 16, 0, 0); } while (0)
; #define LDA(dst, b, h) _Pragma("unroll") for (int m = 0; m < 4; ++m) _Pragma("unroll") for (int k = 0; k < 2; ++k) \
;     dst[m][k] = *reinterpret_cast<const bf16x8*>((char*)SA(b, h) + lds_byte(wr * 64 + m * 16 + fr, k * 32 + fq * 8))
; #define LDB(dst, b, h) _Pragma("unroll") for (int n = 0; n < 2; ++n) _Pragma("unroll") for (int k = 0; k < 2; ++k) \
;     dst[n][k] = *reinterpret_cast<const bf16x8*>((char*)SB(b, h) + lds_byte(wc * 32 + n * 16 + fr, k * 32 + fq * 8))
; #define MMA(ai, bj, At_, Bt_) do { __builtin_amdgcn_s_setprio(1); \
;     _Pragma("unroll") for (int m = 0; m < 4; ++m) _Pragma("unroll") for (int n = 0; n < 2; ++n) _Pragma("unroll") for (int k = 0; k < 2; ++k) \
;       acc[ai][bj][m][n] = __builtin_amdgcn_mfma_f32_16x16x32_bf16(At_[m][k], Bt_[n][k], acc[ai][bj][m][n], 0, 0, 0); \
;     __builtin_amdgcn_s_setprio(0); } while (0)
; #define WAIT_V(n) asm volatile("s_waitcnt vmcnt(" #n ")" ::: "memory")
; #define WAIT_L(n) asm volatile("s_waitcnt lgkmcnt(" #n ")" ::: "memory")
; #define BAR __builtin_amdgcn_s_barrier()
; #define SCHED __builtin_amdgcn_sched_barrier(0)
; template <class Epi> ...
;     ...
;     BAR; WAIT_L(0); MMA(1, 0, At, B0); BAR; SCHED;
;     STAGE(SB(1, 1), Bt, bcol + HALF, t + 3);
;     WAIT_V(6); BAR; MMA(1, 1, At, B1); BAR;
;   }
;   { LDB(B0, 0, 0); LDA(At, 0, 0); STAGE(SA(1, 1), A, brow + HALF, nt - 1);
;     BAR; WAIT_L(0); MMA(0, 0, At, B0); BAR;
;     LDB(B1, 0, 1); BAR; WAIT_L(0); MMA(0, 1, At, B1); BAR;
	s_waitcnt lgkmcnt(0)
	v_mfma_f32_16x16x32_bf16 v[122:125], v[170:173], v[134:137], v[122:125]
	v_mfma_f32_16x16x32_bf16 v[138:141], v[170:173], v[162:165], v[138:141]
	v_mfma_f32_16x16x32_bf16 v[50:53], v[178:181], v[134:137], v[50:53]
	v_mfma_f32_16x16x32_bf16 v[54:57], v[178:181], v[162:165], v[54:57]
	v_mfma_f32_16x16x32_bf16 v[78:81], v[186:189], v[134:137], v[78:81]
	v_mfma_f32_16x16x32_bf16 v[142:145], v[186:189], v[162:165], v[142:145]
	v_mfma_f32_16x16x32_bf16 v[100:103], v[194:197], v[134:137], v[102:105]
	v_mfma_f32_16x16x32_bf16 v[106:109], v[194:197], v[162:165], v[106:109]
	v_mfma_f32_16x16x32_bf16 v[122:125], v[174:177], v[146:149], v[122:125]
	v_mfma_f32_16x16x32_bf16 v[138:141], v[174:177], v[166:169], v[138:141]
	v_mfma_f32_16x16x32_bf16 v[50:53], v[182:185], v[146:149], v[50:53]
	v_mfma_f32_16x16x32_bf16 v[54:57], v[182:185], v[166:169], v[54:57]
	v_mfma_f32_16x16x32_bf16 v[78:81], v[190:193], v[146:149], v[78:81]
	v_mfma_f32_16x16x32_bf16 v[142:145], v[190:193], v[166:169], v[142:145]
	v_mfma_f32_16x16x32_bf16 v[102:105], v[198:201], v[146:149], v[100:103]
	v_mfma_f32_16x16x32_bf16 v[146:149], v[198:201], v[166:169], v[106:109]
	s_barrier
	s_mov_b32 m0, s53
	v_lshl_add_u64 v[94:95], v[226:227], 0, s[60:61]
	global_load_lds_dwordx4 v[94:95], off
	v_lshl_add_u64 v[94:95], v[228:229], 0, s[60:61]
	s_mov_b32 m0, s54
	s_nop 0
	global_load_lds_dwordx4 v[94:95], off
	s_waitcnt vmcnt(6)
	s_barrier
	v_mfma_f32_16x16x32_bf16 v[106:109], v[170:173], v[202:205], v[110:113]
	v_mfma_f32_16x16x32_bf16 v[36:39], v[170:173], v[216:219], v[36:39]
	v_mfma_f32_16x16x32_bf16 v[40:43], v[178:181], v[202:205], v[40:43]
	v_mfma_f32_16x16x32_bf16 v[44:47], v[178:181], v[216:219], v[44:47]
	v_mfma_f32_16x16x32_bf16 v[74:77], v[186:189], v[202:205], v[74:77]
	v_mfma_f32_16x16x32_bf16 v[68:71], v[186:189], v[216:219], v[68:71]
	v_mfma_f32_16x16x32_bf16 v[94:97], v[194:197], v[202:205], v[96:99]
	v_mfma_f32_16x16x32_bf16 v[90:93], v[194:197], v[216:219], v[90:93]
	v_mfma_f32_16x16x32_bf16 v[134:137], v[174:177], v[212:215], v[106:109]
	v_mfma_f32_16x16x32_bf16 v[36:39], v[174:177], v[220:223], v[36:39]
	v_mfma_f32_16x16x32_bf16 v[40:43], v[182:185], v[212:215], v[40:43]
	v_mfma_f32_16x16x32_bf16 v[44:47], v[182:185], v[220:223], v[44:47]
	v_mfma_f32_16x16x32_bf16 v[74:77], v[190:193], v[212:215], v[74:77]
	v_mfma_f32_16x16x32_bf16 v[68:71], v[190:193], v[220:223], v[68:71]
	v_mfma_f32_16x16x32_bf16 v[98:101], v[198:201], v[212:215], v[94:97]
	v_mfma_f32_16x16x32_bf16 v[92:95], v[198:201], v[220:223], v[90:93]
	s_add_i32 s24, s24, 2
	s_add_u32 s22, s22, 0x100
	s_addc_u32 s23, s23, 0
	s_cmp_lt_u32 s24, 12
	s_barrier
	s_cbranch_scc1 .LBB0_115
	s_mov_b64 s[22:23], 0x780
	s_mov_b32 m0, s26
	v_lshl_add_u64 v[34:35], v[158:159], 0, s[22:23]
	ds_read_b128 v[106:109], v208
	ds_read_b128 v[110:113], v208 offset:1024
	ds_read_b128 v[162:165], v208 offset:2048
	ds_read_b128 v[166:169], v208 offset:3072
	ds_read_b128 v[170:173], v209
	ds_read_b128 v[174:177], v209 offset:1024
	ds_read_b128 v[178:181], v210
	ds_read_b128 v[182:185], v210 offset:1024
	ds_read_b128 v[186:189], v211
	ds_read_b128 v[190:193], v211 offset:1024
	ds_read_b128 v[194:197], v235
	ds_read_b128 v[198:201], v235 offset:1024
	global_load_lds_dwordx4 v[34:35], off
	v_lshl_add_u64 v[34:35], v[160:161], 0, s[22:23]
	s_mov_b32 m0, s25
	s_nop 0
	global_load_lds_dwordx4 v[34:35], off
	s_barrier
	s_waitcnt lgkmcnt(0)
	v_mfma_f32_16x16x32_bf16 v[2:5], v[170:173], v[106:109], v[2:5]
	v_mfma_f32_16x16x32_bf16 v[10:13], v[170:173], v[162:165], v[10:13]
	v_mfma_f32_16x16x32_bf16 v[22:25], v[178:181], v[106:109], v[22:25]
	v_mfma_f32_16x16x32_bf16 v[30:33], v[178:181], v[162:165], v[30:33]
	v_mfma_f32_16x16x32_bf16 v[62:65], v[186:189], v[106:109], v[62:65]
	v_mfma_f32_16x16x32_bf16 v[86:89], v[186:189], v[162:165], v[86:89]
	v_mfma_f32_16x16x32_bf16 v[118:121], v[194:197], v[106:109], v[118:121]
	v_mfma_f32_16x16x32_bf16 v[2:5], v[174:177], v[110:113], v[2:5]
	v_mfma_f32_16x16x32_bf16 v[10:13], v[174:177], v[166:169], v[10:13]
	v_mfma_f32_16x16x32_bf16 v[22:25], v[182:185], v[110:113], v[22:25]
	v_mfma_f32_16x16x32_bf16 v[30:33], v[182:185], v[166:169], v[30:33]
	v_mfma_f32_16x16x32_bf16 v[62:65], v[190:193], v[110:113], v[62:65]
	v_mfma_f32_16x16x32_bf16 v[86:89], v[190:193], v[166:169], v[86:89]
	v_mfma_f32_16x16x32_bf16 v[158:161], v[198:201], v[110:113], v[118:121]
	v_mfma_f32_16x16x32_bf16 v[118:121], v[194:197], v[162:165], v[130:133]
	v_mfma_f32_16x16x32_bf16 v[130:133], v[198:201], v[166:169], v[118:121]
	s_barrier
	s_nop 4
	ds_read_b128 v[118:121], v236
	ds_read_b128 v[202:205], v236 offset:1024
	ds_read_b128 v[212:215], v236 offset:2048
	ds_read_b128 v[216:219], v236 offset:3072
	s_barrier
	s_waitcnt lgkmcnt(0)
	v_mfma_f32_16x16x32_bf16 v[58:61], v[186:189], v[118:121], v[58:61]
	v_mfma_f32_16x16x32_bf16 v[6:9], v[170:173], v[118:121], v[6:9]
	v_mfma_f32_16x16x32_bf16 v[14:17], v[170:173], v[212:215], v[14:17]
	v_mfma_f32_16x16x32_bf16 v[170:173], v[190:193], v[202:205], v[58:61]
	v_mfma_f32_16x16x32_bf16 v[58:61], v[186:189], v[212:215], v[82:85]
	v_mfma_f32_16x16x32_bf16 v[6:9], v[174:177], v[202:205], v[6:9]
	v_mfma_f32_16x16x32_bf16 v[14:17], v[174:177], v[216:219], v[14:17]
	v_mfma_f32_16x16x32_bf16 v[18:21], v[178:181], v[118:121], v[18:21]
	v_mfma_f32_16x16x32_bf16 v[26:29], v[178:181], v[212:215], v[26:29]
	v_mfma_f32_16x16x32_bf16 v[174:177], v[190:193], v[216:219], v[58:61]
	v_mfma_f32_16x16x32_bf16 v[58:61], v[194:197], v[118:121], v[114:117]
	v_mfma_f32_16x16x32_bf16 v[18:21], v[182:185], v[202:205], v[18:21]
	v_mfma_f32_16x16x32_bf16 v[26:29], v[182:185], v[216:219], v[26:29]
	v_mfma_f32_16x16x32_bf16 v[178:181], v[198:201], v[202:205], v[58:61]
	v_mfma_f32_16x16x32_bf16 v[58:61], v[194:197], v[212:215], v[126:129]
	v_mfma_f32_16x16x32_bf16 v[182:185], v[198:201], v[216:219], v[58:61]
	s_barrier
; #define LDA(dst, b, h) _Pragma("unroll") for (int m = 0; m < 4; ++m) _Pragma("unroll") for (int k = 0; k < 2; ++k) \
;     dst[m][k] = *reinterpret_cast<const bf16x8*>((char*)SA(b, h) + lds_byte(wr * 64 + m * 16 + fr, k * 32 + fq * 8))
; #define LDB(dst, b, h) _Pragma("unroll") for (int n = 0; n < 2; ++n) _Pragma("unroll") for (int k = 0; k < 2; ++k) \
;     dst[n][k] = *reinterpret_cast<const bf16x8*>((char*)SB(b, h) + lds_byte(wc * 32 + n * 16 + fr, k * 32 + fq * 8))
; #define MMA(ai, bj, At_, Bt_) do { __builtin_amdgcn_s_setprio(1); \
;     _Pragma("unroll") for (int m = 0; m < 4; ++m) _Pragma("unroll") for (int n = 0; n < 2; ++n) _Pragma("unroll") for (int k = 0; k < 2; ++k) \
;       acc[ai][bj][m][n] = __builtin_amdgcn_mfma_f32_16x16x32_bf16(At_[m][k], Bt_[n][k], acc[ai][bj][m][n], 0, 0, 0); \
;     __builtin_amdgcn_s_setprio(0); } while (0)
; #define WAIT_V(n) asm volatile("s_waitcnt vmcnt(" #n ")" ::: "memory")
; #define WAIT_L(n) asm volatile("s_waitcnt lgkmcnt(" #n ")" ::: "memory")
; #define BAR __builtin_amdgcn_s_barrier()
; template <class Epi> ...
;     ...
;     LDA(At, 0, 1); WAIT_V(4); BAR; WAIT_L(0); MMA(1, 0, At, B0); MMA(1, 1, At, B1); BAR; }
;   { LDB(B0, 1, 0); LDA(At, 1, 0); WAIT_V(2); BAR; WAIT_L(0); MMA(0, 0, At, B0); BAR;
	s_nop 4
	ds_read_b128 v[58:61], v209 offset:16384
	ds_read_b128 v[82:85], v209 offset:17408
	ds_read_b128 v[114:117], v210 offset:16384
	ds_read_b128 v[126:129], v210 offset:17408
	ds_read_b128 v[186:189], v211 offset:16384
	ds_read_b128 v[190:193], v211 offset:17408
	ds_read_b128 v[194:197], v235 offset:16384
	ds_read_b128 v[198:201], v235 offset:17408
	s_waitcnt vmcnt(4)
	s_barrier
	s_waitcnt lgkmcnt(0)
	v_mfma_f32_16x16x32_bf16 v[48:51], v[114:117], v[106:109], v[50:53]
	v_mfma_f32_16x16x32_bf16 v[224:227], v[126:129], v[110:113], v[48:51]
	v_mfma_f32_16x16x32_bf16 v[48:51], v[114:117], v[162:165], v[54:57]
	v_mfma_f32_16x16x32_bf16 v[228:231], v[126:129], v[166:169], v[48:51]
	v_mfma_f32_16x16x32_bf16 v[48:51], v[186:189], v[106:109], v[78:81]
	v_mfma_f32_16x16x32_bf16 v[240:243], v[190:193], v[110:113], v[48:51]
	v_mfma_f32_16x16x32_bf16 v[48:51], v[186:189], v[162:165], v[142:145]
	v_mfma_f32_16x16x32_bf16 v[122:125], v[58:61], v[106:109], v[122:125]
	v_mfma_f32_16x16x32_bf16 v[142:145], v[190:193], v[166:169], v[48:51]
	v_mfma_f32_16x16x32_bf16 v[48:51], v[194:197], v[106:109], v[102:105]
	v_mfma_f32_16x16x32_bf16 v[220:223], v[82:85], v[110:113], v[122:125]
	v_mfma_f32_16x16x32_bf16 v[122:125], v[58:61], v[162:165], v[138:141]
	v_mfma_f32_16x16x32_bf16 v[244:247], v[198:201], v[110:113], v[48:51]
	v_mfma_f32_16x16x32_bf16 v[48:51], v[194:197], v[162:165], v[146:149]
	v_mfma_f32_16x16x32_bf16 v[138:141], v[82:85], v[166:169], v[122:125]
	v_mfma_f32_16x16x32_bf16 v[146:149], v[198:201], v[166:169], v[48:51]
	v_mfma_f32_16x16x32_bf16 v[34:37], v[58:61], v[212:215], v[36:39]
	v_mfma_f32_16x16x32_bf16 v[162:165], v[82:85], v[216:219], v[34:37]
	v_mfma_f32_16x16x32_bf16 v[34:37], v[114:117], v[118:121], v[40:43]
	v_mfma_f32_16x16x32_bf16 v[48:51], v[58:61], v[118:121], v[134:137]
	v_mfma_f32_16x16x32_bf16 v[166:169], v[126:129], v[202:205], v[34:37]
	v_mfma_f32_16x16x32_bf16 v[34:37], v[114:117], v[212:215], v[44:47]
	v_mfma_f32_16x16x32_bf16 v[134:137], v[82:85], v[202:205], v[48:51]
	v_mfma_f32_16x16x32_bf16 v[46:49], v[126:129], v[216:219], v[34:37]
	v_mfma_f32_16x16x32_bf16 v[34:37], v[186:189], v[118:121], v[74:77]
	v_mfma_f32_16x16x32_bf16 v[248:251], v[190:193], v[202:205], v[34:37]
	v_mfma_f32_16x16x32_bf16 v[34:37], v[186:189], v[212:215], v[68:71]
	v_mfma_f32_16x16x32_bf16 v[186:189], v[190:193], v[216:219], v[34:37]
	v_mfma_f32_16x16x32_bf16 v[34:37], v[194:197], v[118:121], v[98:101]
	v_mfma_f32_16x16x32_bf16 v[190:193], v[198:201], v[202:205], v[34:37]
	v_mfma_f32_16x16x32_bf16 v[34:37], v[194:197], v[212:215], v[92:95]
	v_mfma_f32_16x16x32_bf16 v[194:197], v[198:201], v[216:219], v[34:37]
	s_barrier
	ds_read_b128 v[42:45], v237
	ds_read_b128 v[66:69], v237 offset:1024
	ds_read_b128 v[70:73], v237 offset:2048
	ds_read_b128 v[198:201], v237 offset:3072
	s_nop 0
	ds_read_b128 v[34:37], v209 offset:32768
	ds_read_b128 v[38:41], v209 offset:33792
	ds_read_b128 v[50:53], v210 offset:32768
	ds_read_b128 v[54:57], v210 offset:33792
	ds_read_b128 v[74:77], v211 offset:32768
	ds_read_b128 v[78:81], v211 offset:33792
	ds_read_b128 v[202:205], v235 offset:32768
	ds_read_b128 v[212:215], v235 offset:33792
	s_waitcnt vmcnt(2)
	s_barrier
	s_waitcnt lgkmcnt(0)
	v_mfma_f32_16x16x32_bf16 v[2:5], v[34:37], v[42:45], v[2:5]
	v_mfma_f32_16x16x32_bf16 v[114:117], v[38:41], v[66:69], v[2:5]
	v_mfma_f32_16x16x32_bf16 v[2:5], v[34:37], v[70:73], v[10:13]
	v_mfma_f32_16x16x32_bf16 v[118:121], v[38:41], v[198:201], v[2:5]
	v_mfma_f32_16x16x32_bf16 v[2:5], v[50:53], v[42:45], v[22:25]
	v_mfma_f32_16x16x32_bf16 v[98:101], v[54:57], v[66:69], v[2:5]
	v_mfma_f32_16x16x32_bf16 v[2:5], v[50:53], v[70:73], v[30:33]
	v_mfma_f32_16x16x32_bf16 v[102:105], v[54:57], v[198:201], v[2:5]
	v_mfma_f32_16x16x32_bf16 v[2:5], v[74:77], v[42:45], v[62:65]
	v_mfma_f32_16x16x32_bf16 v[82:85], v[78:81], v[66:69], v[2:5]
	v_mfma_f32_16x16x32_bf16 v[2:5], v[74:77], v[70:73], v[86:89]
	v_mfma_f32_16x16x32_bf16 v[86:89], v[78:81], v[198:201], v[2:5]
	v_mfma_f32_16x16x32_bf16 v[2:5], v[202:205], v[42:45], v[158:161]
	v_mfma_f32_16x16x32_bf16 v[58:61], v[212:215], v[66:69], v[2:5]
	v_mfma_f32_16x16x32_bf16 v[2:5], v[202:205], v[70:73], v[130:133]
	v_mfma_f32_16x16x32_bf16 v[62:65], v[212:215], v[198:201], v[2:5]
	s_barrier
; #define LDA(dst, b, h) _Pragma("unroll") for (int m = 0; m < 4; ++m) _Pragma("unroll") for (int k = 0; k < 2; ++k) \
;     dst[m][k] = *reinterpret_cast<const bf16x8*>((char*)SA(b, h) + lds_byte(wr * 64 + m * 16 + fr, k * 32 + fq * 8))
; #define LDB(dst, b, h) _Pragma("unroll") for (int n = 0; n < 2; ++n) _Pragma("unroll") for (int k = 0; k < 2; ++k) \
;     dst[n][k] = *reinterpret_cast<const bf16x8*>((char*)SB(b, h) + lds_byte(wc * 32 + n * 16 + fr, k * 32 + fq * 8))
; #define MMA(ai, bj, At_, Bt_) do { __builtin_amdgcn_s_setprio(1); \
;     _Pragma("unroll") for (int m = 0; m < 4; ++m) _Pragma("unroll") for (int n = 0; n < 2; ++n) _Pragma("unroll") for (int k = 0; k < 2; ++k) \
;       acc[ai][bj][m][n] = __builtin_amdgcn_mfma_f32_16x16x32_bf16(At_[m][k], Bt_[n][k], acc[ai][bj][m][n], 0, 0, 0); \
;     __builtin_amdgcn_s_setprio(0); } while (0)
; #define WAIT_V(n) asm volatile("s_waitcnt vmcnt(" #n ")" ::: "memory")
; #define WAIT_L(n) asm volatile("s_waitcnt lgkmcnt(" #n ")" ::: "memory")
; #define BAR __builtin_amdgcn_s_barrier()
; template <class Epi> ...
;     ...
;     LDB(B1, 1, 1); WAIT_V(0); BAR; WAIT_L(0); MMA(0, 1, At, B1); BAR;
;     LDA(At, 1, 1); BAR; WAIT_L(0); MMA(1, 0, At, B0); MMA(1, 1, At, B1); BAR; }
;   if (wr == 0) BAR;
	ds_read_b128 v[10:13], v238
	ds_read_b128 v[130:133], v238 offset:1024
	ds_read_b128 v[158:161], v238 offset:2048
	ds_read_b128 v[216:219], v238 offset:3072
	s_waitcnt vmcnt(0)
	s_barrier
	s_waitcnt lgkmcnt(0)
	v_mfma_f32_16x16x32_bf16 v[2:5], v[34:37], v[10:13], v[6:9]
	v_mfma_f32_16x16x32_bf16 v[122:125], v[38:41], v[130:133], v[2:5]
	v_mfma_f32_16x16x32_bf16 v[2:5], v[34:37], v[158:161], v[14:17]
	v_mfma_f32_16x16x32_bf16 v[126:129], v[38:41], v[216:219], v[2:5]
	v_mfma_f32_16x16x32_bf16 v[2:5], v[50:53], v[10:13], v[18:21]
	v_mfma_f32_16x16x32_bf16 v[106:109], v[54:57], v[130:133], v[2:5]
	v_mfma_f32_16x16x32_bf16 v[2:5], v[50:53], v[158:161], v[26:29]
	v_mfma_f32_16x16x32_bf16 v[110:113], v[54:57], v[216:219], v[2:5]
	v_mfma_f32_16x16x32_bf16 v[2:5], v[74:77], v[10:13], v[170:173]
	v_mfma_f32_16x16x32_bf16 v[90:93], v[78:81], v[130:133], v[2:5]
	v_mfma_f32_16x16x32_bf16 v[2:5], v[74:77], v[158:161], v[174:177]
	v_mfma_f32_16x16x32_bf16 v[94:97], v[78:81], v[216:219], v[2:5]
	v_mfma_f32_16x16x32_bf16 v[2:5], v[202:205], v[10:13], v[178:181]
	v_mfma_f32_16x16x32_bf16 v[74:77], v[212:215], v[130:133], v[2:5]
	v_mfma_f32_16x16x32_bf16 v[2:5], v[202:205], v[158:161], v[182:185]
	v_mfma_f32_16x16x32_bf16 v[78:81], v[212:215], v[216:219], v[2:5]
	s_barrier
	ds_read_b128 v[14:17], v209 offset:49152
	ds_read_b128 v[26:29], v209 offset:50176
	ds_read_b128 v[30:33], v210 offset:49152
	ds_read_b128 v[170:173], v210 offset:50176
	ds_read_b128 v[174:177], v211 offset:49152
	ds_read_b128 v[178:181], v211 offset:50176
	ds_read_b128 v[182:185], v235 offset:49152
	ds_read_b128 v[202:205], v235 offset:50176
	s_barrier
	s_waitcnt lgkmcnt(0)
	v_mfma_f32_16x16x32_bf16 v[2:5], v[14:17], v[42:45], v[220:223]
	v_mfma_f32_16x16x32_bf16 v[50:53], v[26:29], v[66:69], v[2:5]
	v_mfma_f32_16x16x32_bf16 v[2:5], v[14:17], v[70:73], v[138:141]
	v_mfma_f32_16x16x32_bf16 v[54:57], v[26:29], v[198:201], v[2:5]
	v_mfma_f32_16x16x32_bf16 v[2:5], v[30:33], v[42:45], v[224:227]
	v_mfma_f32_16x16x32_bf16 v[34:37], v[170:173], v[66:69], v[2:5]
	v_mfma_f32_16x16x32_bf16 v[2:5], v[30:33], v[70:73], v[228:231]
	v_mfma_f32_16x16x32_bf16 v[38:41], v[170:173], v[198:201], v[2:5]
	v_mfma_f32_16x16x32_bf16 v[2:5], v[174:177], v[42:45], v[240:243]
	v_mfma_f32_16x16x32_bf16 v[18:21], v[178:181], v[66:69], v[2:5]
	v_mfma_f32_16x16x32_bf16 v[2:5], v[174:177], v[70:73], v[142:145]
	v_mfma_f32_16x16x32_bf16 v[22:25], v[178:181], v[198:201], v[2:5]
	v_mfma_f32_16x16x32_bf16 v[2:5], v[182:185], v[42:45], v[244:247]
	v_mfma_f32_16x16x32_bf16 v[6:9], v[182:185], v[70:73], v[146:149]
	v_mfma_f32_16x16x32_bf16 v[2:5], v[202:205], v[66:69], v[2:5]
	v_mfma_f32_16x16x32_bf16 v[6:9], v[202:205], v[198:201], v[6:9]
	v_mfma_f32_16x16x32_bf16 v[42:45], v[14:17], v[10:13], v[134:137]
	v_mfma_f32_16x16x32_bf16 v[14:17], v[14:17], v[158:161], v[162:165]
	v_mfma_f32_16x16x32_bf16 v[70:73], v[26:29], v[216:219], v[14:17]
	v_mfma_f32_16x16x32_bf16 v[14:17], v[30:33], v[10:13], v[166:169]
	v_mfma_f32_16x16x32_bf16 v[66:69], v[26:29], v[130:133], v[42:45]
	v_mfma_f32_16x16x32_bf16 v[42:45], v[170:173], v[130:133], v[14:17]
	v_mfma_f32_16x16x32_bf16 v[14:17], v[30:33], v[158:161], v[46:49]
	v_mfma_f32_16x16x32_bf16 v[46:49], v[170:173], v[216:219], v[14:17]
	v_mfma_f32_16x16x32_bf16 v[14:17], v[174:177], v[10:13], v[248:251]
	v_mfma_f32_16x16x32_bf16 v[26:29], v[178:181], v[130:133], v[14:17]
	v_mfma_f32_16x16x32_bf16 v[14:17], v[174:177], v[158:161], v[186:189]
	v_mfma_f32_16x16x32_bf16 v[30:33], v[178:181], v[216:219], v[14:17]
	v_mfma_f32_16x16x32_bf16 v[10:13], v[182:185], v[10:13], v[190:193]
	v_mfma_f32_16x16x32_bf16 v[14:17], v[182:185], v[158:161], v[194:197]
	v_mfma_f32_16x16x32_bf16 v[10:13], v[202:205], v[130:133], v[10:13]
	v_mfma_f32_16x16x32_bf16 v[14:17], v[202:205], v[216:219], v[14:17]
	s_barrier
	s_and_saveexec_b64 s[22:23], s[6:7]
	s_cbranch_execz .LBB0_111
	s_barrier
	s_branch .LBB0_111

; #define STAGE(P, BASE, br, kt) do { const char* _gb = (const char*)((BASE) + ((long)(br) * K + (long)(kt) * BK)); \
;     __builtin_amdgcn_global_load_lds((const unsigned*)(_gb + (size_t)so0), (unsigned*)((char*)(P) + wv1k), 16, 0, 0); \
;     __builtin_amdgcn_global_load_lds((const unsigned*)(_gb + (size_t)so1), (unsigned*)((char*)(P) + wv1k + 8192), 16, 0, 0); } while (0)
; #define LDA(dst, b, h) _Pragma("unroll") for (int m = 0; m < 4; ++m) _Pragma("unroll") for (int k = 0; k < 2; ++k) \
;     dst[m][k] = *reinterpret_cast<const bf16x8*>((char*)SA(b, h) + lds_byte(wr * 64 + m * 16 + fr, k * 32 + fq * 8))
; #define LDB(dst, b, h) _Pragma("unroll") for (int n = 0; n < 2; ++n) _Pragma("unroll") for (int k = 0; k < 2; ++k) \
;     dst[n][k] = *reinterpret_cast<const bf16x8*>((char*)SB(b, h) + lds_byte(wc * 32 + n * 16 + fr, k * 32 + fq * 8))
; #define MMA(ai, bj, At_, Bt_) do { __builtin_amdgcn_s_setprio(1); \
;     _Pragma("unroll") for (int m = 0; m < 4; ++m) _Pragma("unroll") for (int n = 0; n < 2; ++n) _Pragma("unroll") for (int k = 0; k < 2; ++k) \
;       acc[ai][bj][m][n] = __builtin_amdgcn_mfma_f32_16x16x32_bf16(At_[m][k], Bt_[n][k], acc[ai][bj][m][n], 0, 0, 0); \
;     __builtin_amdgcn_s_setprio(0); } while (0)
; #define WAIT_L(n) asm volatile("s_waitcnt lgkmcnt(" #n ")" ::: "memory")
; #define BAR __builtin_amdgcn_s_barrier()
; #define SCHED __builtin_amdgcn_sched_barrier(0)
; template <class Epi> ...
;     ...
;   for (int t = 0; t < nt - 2; t += 2) {
;     LDB(B0, 0, 0); SCHED; LDA(At, 0, 0); STAGE(SA(1, 1), A, brow + HALF, t + 1);
;     WAIT_L(8); BAR; WAIT_L(0); MMA(0, 0, At, B0); BAR; SCHED;
;     LDB(B1, 0, 1); STAGE(SB(0, 0), Bt, bcol, t + 2);
;     BAR; WAIT_L(0); MMA(0, 1, At, B1); BAR;
;     LDA(At, 0, 1); STAGE(SA(0, 0), A, brow, t + 2);
;     BAR; WAIT_L(0); MMA(1, 0, At, B0); BAR; SCHED;
;     STAGE(SB(0, 1), Bt, bcol + HALF, t + 2);
.LBB0_133:
	ds_read_b128 v[162:165], v154
	ds_read_b128 v[166:169], v154 offset:1024
	ds_read_b128 v[170:173], v154 offset:2048
	ds_read_b128 v[174:177], v154 offset:3072
	v_lshl_add_u64 v[226:227], v[146:147], 0, s[24:25]
	s_add_i32 s30, s21, 0xc000
	v_lshl_add_u64 v[210:211], v[226:227], 0, s[34:35]
	s_mov_b32 m0, s30
	v_lshl_add_u64 v[228:229], v[144:145], 0, s[24:25]
	s_add_i32 s27, s21, 0xe000
	ds_read_b128 v[178:181], v155
	ds_read_b128 v[182:185], v155 offset:1024
	ds_read_b128 v[186:189], v156
	ds_read_b128 v[190:193], v156 offset:1024
	ds_read_b128 v[194:197], v157
	ds_read_b128 v[198:201], v157 offset:1024
	ds_read_b128 v[202:205], v158
	ds_read_b128 v[206:209], v158 offset:1024
	global_load_lds_dwordx4 v[210:211], off
	v_lshl_add_u64 v[210:211], v[228:229], 0, s[34:35]
	s_mov_b32 m0, s27
	s_nop 0
	global_load_lds_dwordx4 v[210:211], off
	s_waitcnt lgkmcnt(8)
	s_barrier
	s_waitcnt lgkmcnt(0)
	v_mfma_f32_16x16x32_bf16 v[104:107], v[178:181], v[162:165], v[104:107]
	v_mfma_f32_16x16x32_bf16 v[100:103], v[178:181], v[170:173], v[100:103]
	v_mfma_f32_16x16x32_bf16 v[112:115], v[186:189], v[162:165], v[112:115]
	v_mfma_f32_16x16x32_bf16 v[108:111], v[186:189], v[170:173], v[108:111]
	v_mfma_f32_16x16x32_bf16 v[120:123], v[194:197], v[162:165], v[120:123]
	v_mfma_f32_16x16x32_bf16 v[116:119], v[194:197], v[170:173], v[116:119]
	v_mfma_f32_16x16x32_bf16 v[128:131], v[202:205], v[162:165], v[128:131]
	v_mfma_f32_16x16x32_bf16 v[124:127], v[202:205], v[170:173], v[124:127]
	v_mfma_f32_16x16x32_bf16 v[104:107], v[182:185], v[166:169], v[104:107]
	v_mfma_f32_16x16x32_bf16 v[100:103], v[182:185], v[174:177], v[100:103]
	v_mfma_f32_16x16x32_bf16 v[112:115], v[190:193], v[166:169], v[112:115]
	v_mfma_f32_16x16x32_bf16 v[108:111], v[190:193], v[174:177], v[108:111]
	v_mfma_f32_16x16x32_bf16 v[120:123], v[198:201], v[166:169], v[120:123]
	v_mfma_f32_16x16x32_bf16 v[116:119], v[198:201], v[174:177], v[116:119]
	v_mfma_f32_16x16x32_bf16 v[128:131], v[206:209], v[166:169], v[128:131]
	v_mfma_f32_16x16x32_bf16 v[124:127], v[206:209], v[174:177], v[124:127]
	s_barrier
	v_lshl_add_u64 v[230:231], v[142:143], 0, s[24:25]
	s_mov_b32 m0, s55
	v_lshl_add_u64 v[232:233], v[230:231], 0, s[0:1]
	ds_read_b128 v[210:213], v159
	ds_read_b128 v[214:217], v159 offset:1024
	ds_read_b128 v[218:221], v159 offset:2048
	ds_read_b128 v[222:225], v159 offset:3072
	global_load_lds_dwordx4 v[232:233], off
	v_lshl_add_u64 v[232:233], v[140:141], 0, s[24:25]
	v_lshl_add_u64 v[236:237], v[232:233], 0, s[0:1]
	s_mov_b32 m0, s56
	s_add_i32 s26, s26, 2
	global_load_lds_dwordx4 v[236:237], off
	s_barrier
	s_waitcnt lgkmcnt(0)
	v_mfma_f32_16x16x32_bf16 v[72:75], v[178:181], v[210:213], v[72:75]
	v_mfma_f32_16x16x32_bf16 v[68:71], v[178:181], v[218:221], v[68:71]
	v_mfma_f32_16x16x32_bf16 v[80:83], v[186:189], v[210:213], v[80:83]
	v_mfma_f32_16x16x32_bf16 v[76:79], v[186:189], v[218:221], v[76:79]
	v_mfma_f32_16x16x32_bf16 v[88:91], v[194:197], v[210:213], v[88:91]
	v_mfma_f32_16x16x32_bf16 v[84:87], v[194:197], v[218:221], v[84:87]
	v_mfma_f32_16x16x32_bf16 v[96:99], v[202:205], v[210:213], v[96:99]
	v_mfma_f32_16x16x32_bf16 v[92:95], v[202:205], v[218:221], v[92:95]
	v_mfma_f32_16x16x32_bf16 v[72:75], v[182:185], v[214:217], v[72:75]
	v_mfma_f32_16x16x32_bf16 v[68:71], v[182:185], v[222:225], v[68:71]
	v_mfma_f32_16x16x32_bf16 v[80:83], v[190:193], v[214:217], v[80:83]
	v_mfma_f32_16x16x32_bf16 v[76:79], v[190:193], v[222:225], v[76:79]
	v_mfma_f32_16x16x32_bf16 v[88:91], v[198:201], v[214:217], v[88:91]
	v_mfma_f32_16x16x32_bf16 v[84:87], v[198:201], v[222:225], v[84:87]
	v_mfma_f32_16x16x32_bf16 v[96:99], v[206:209], v[214:217], v[96:99]
	v_mfma_f32_16x16x32_bf16 v[92:95], v[206:209], v[222:225], v[92:95]
	v_lshl_add_u64 v[236:237], v[138:139], 0, s[24:25]
	s_mov_b32 m0, s21
	v_lshl_add_u64 v[238:239], v[236:237], 0, s[0:1]
	s_barrier
	ds_read_b128 v[178:181], v155 offset:16384
	ds_read_b128 v[182:185], v155 offset:17408
	ds_read_b128 v[186:189], v156 offset:16384
	ds_read_b128 v[190:193], v156 offset:17408
	ds_read_b128 v[194:197], v157 offset:16384
	ds_read_b128 v[198:201], v157 offset:17408
	ds_read_b128 v[202:205], v158 offset:16384
	ds_read_b128 v[206:209], v158 offset:17408
	global_load_lds_dwordx4 v[238:239], off
	v_lshl_add_u64 v[238:239], v[136:137], 0, s[24:25]
	v_lshl_add_u64 v[240:241], v[238:239], 0, s[0:1]
	s_mov_b32 m0, s9
	s_nop 0
	global_load_lds_dwordx4 v[240:241], off
	s_barrier
	s_waitcnt lgkmcnt(0)
	v_mfma_f32_16x16x32_bf16 v[40:43], v[178:181], v[162:165], v[40:43]
	v_mfma_f32_16x16x32_bf16 v[36:39], v[178:181], v[170:173], v[36:39]
	v_mfma_f32_16x16x32_bf16 v[48:51], v[186:189], v[162:165], v[48:51]
	v_mfma_f32_16x16x32_bf16 v[44:47], v[186:189], v[170:173], v[44:47]
	v_mfma_f32_16x16x32_bf16 v[56:59], v[194:197], v[162:165], v[56:59]
	v_mfma_f32_16x16x32_bf16 v[52:55], v[194:197], v[170:173], v[52:55]
	v_mfma_f32_16x16x32_bf16 v[64:67], v[202:205], v[162:165], v[64:67]
	v_mfma_f32_16x16x32_bf16 v[60:63], v[202:205], v[170:173], v[60:63]
	v_mfma_f32_16x16x32_bf16 v[40:43], v[182:185], v[166:169], v[40:43]
	v_mfma_f32_16x16x32_bf16 v[36:39], v[182:185], v[174:177], v[36:39]
	v_mfma_f32_16x16x32_bf16 v[48:51], v[190:193], v[166:169], v[48:51]
	v_mfma_f32_16x16x32_bf16 v[44:47], v[190:193], v[174:177], v[44:47]
	v_mfma_f32_16x16x32_bf16 v[56:59], v[198:201], v[166:169], v[56:59]
	v_mfma_f32_16x16x32_bf16 v[52:55], v[198:201], v[174:177], v[52:55]
	v_mfma_f32_16x16x32_bf16 v[64:67], v[206:209], v[166:169], v[64:67]
	v_mfma_f32_16x16x32_bf16 v[60:63], v[206:209], v[174:177], v[60:63]
	s_barrier
; #define STAGE(P, BASE, br, kt) do { const char* _gb = (const char*)((BASE) + ((long)(br) * K + (long)(kt) * BK)); \
;     __builtin_amdgcn_global_load_lds((const unsigned*)(_gb + (size_t)so0), (unsigned*)((char*)(P) + wv1k), 16, 0, 0); \
;     __builtin_amdgcn_global_load_lds((const unsigned*)(_gb + (size_t)so1), (unsigned*)((char*)(P) + wv1k + 8192), 16, 0, 0); } while (0)
; #define LDA(dst, b, h) _Pragma("unroll") for (int m = 0; m < 4; ++m) _Pragma("unroll") for (int k = 0; k < 2; ++k) \
;     dst[m][k] = *reinterpret_cast<const bf16x8*>((char*)SA(b, h) + lds_byte(wr * 64 + m * 16 + fr, k * 32 + fq * 8))
; #define LDB(dst, b, h) _Pragma("unroll") for (int n = 0; n < 2; ++n) _Pragma("unroll") for (int k = 0; k < 2; ++k) \
;     dst[n][k] = *reinterpret_cast<const bf16x8*>((char*)SB(b, h) + lds_byte(wc * 32 + n * 16 + fr, k * 32 + fq * 8))
; #define MMA(ai, bj, At_, Bt_) do { __builtin_amdgcn_s_setprio(1); \
;     _Pragma("unroll") for (int m = 0; m < 4; ++m) _Pragma("unroll") for (int n = 0; n < 2; ++n) _Pragma("unroll") for (int k = 0; k < 2; ++k) \
;       acc[ai][bj][m][n] = __builtin_amdgcn_mfma_f32_16x16x32_bf16(At_[m][k], Bt_[n][k], acc[ai][bj][m][n], 0, 0, 0); \
;     __builtin_amdgcn_s_setprio(0); } while (0)
; #define WAIT_V(n) asm volatile("s_waitcnt vmcnt(" #n ")" ::: "memory")
; #define WAIT_L(n) asm volatile("s_waitcnt lgkmcnt(" #n ")" ::: "memory")
; #define BAR __builtin_amdgcn_s_barrier()
; #define SCHED __builtin_amdgcn_sched_barrier(0)
; template <class Epi> ...
;     ...
;     STAGE(SB(0, 1), Bt, bcol + HALF, t + 2);
;     WAIT_V(6); BAR; MMA(1, 1, At, B1); BAR;
;     LDB(B0, 1, 0); SCHED; LDA(At, 1, 0); STAGE(SA(0, 1), A, brow + HALF, t + 2);
;     WAIT_L(8); BAR; WAIT_L(0); MMA(0, 0, At, B0); BAR; SCHED;
;     LDB(B1, 1, 1); STAGE(SB(1, 0), Bt, bcol, t + 3);
;     BAR; WAIT_L(0); MMA(0, 1, At, B1); BAR;
;     LDA(At, 1, 1); STAGE(SA(1, 0), A, brow, t + 3);
;     BAR; WAIT_L(0); MMA(1, 0, At, B0); BAR; SCHED;
	v_lshl_add_u64 v[240:241], v[134:135], 0, s[24:25]
	s_mov_b32 m0, s57
	v_lshl_add_u64 v[162:163], v[240:241], 0, s[0:1]
	v_lshl_add_u64 v[242:243], v[132:133], 0, s[24:25]
	global_load_lds_dwordx4 v[162:163], off
	v_lshl_add_u64 v[162:163], v[242:243], 0, s[0:1]
	s_mov_b32 m0, s58
	s_nop 0
	global_load_lds_dwordx4 v[162:163], off
	s_waitcnt vmcnt(6)
	s_barrier
	v_mfma_f32_16x16x32_bf16 v[8:11], v[178:181], v[210:213], v[8:11]
	v_mfma_f32_16x16x32_bf16 v[4:7], v[178:181], v[218:221], v[4:7]
	v_mfma_f32_16x16x32_bf16 v[16:19], v[186:189], v[210:213], v[16:19]
	v_mfma_f32_16x16x32_bf16 v[12:15], v[186:189], v[218:221], v[12:15]
	v_mfma_f32_16x16x32_bf16 v[24:27], v[194:197], v[210:213], v[24:27]
	v_mfma_f32_16x16x32_bf16 v[20:23], v[194:197], v[218:221], v[20:23]
	v_mfma_f32_16x16x32_bf16 v[32:35], v[202:205], v[210:213], v[32:35]
	v_mfma_f32_16x16x32_bf16 v[28:31], v[202:205], v[218:221], v[28:31]
	v_mfma_f32_16x16x32_bf16 v[8:11], v[182:185], v[214:217], v[8:11]
	v_mfma_f32_16x16x32_bf16 v[4:7], v[182:185], v[222:225], v[4:7]
	v_mfma_f32_16x16x32_bf16 v[16:19], v[190:193], v[214:217], v[16:19]
	v_mfma_f32_16x16x32_bf16 v[12:15], v[190:193], v[222:225], v[12:15]
	v_mfma_f32_16x16x32_bf16 v[24:27], v[198:201], v[214:217], v[24:27]
	v_mfma_f32_16x16x32_bf16 v[20:23], v[198:201], v[222:225], v[20:23]
	v_mfma_f32_16x16x32_bf16 v[32:35], v[206:209], v[214:217], v[32:35]
	v_mfma_f32_16x16x32_bf16 v[28:31], v[206:209], v[222:225], v[28:31]
	s_barrier
	ds_read_b128 v[162:165], v160
	ds_read_b128 v[166:169], v160 offset:1024
	ds_read_b128 v[170:173], v160 offset:2048
	ds_read_b128 v[174:177], v160 offset:3072
	s_mov_b32 m0, s59
	v_lshl_add_u64 v[210:211], v[226:227], 0, s[0:1]
	ds_read_b128 v[178:181], v155 offset:32768
	ds_read_b128 v[182:185], v155 offset:33792
	ds_read_b128 v[186:189], v156 offset:32768
	ds_read_b128 v[190:193], v156 offset:33792
	ds_read_b128 v[194:197], v157 offset:32768
	ds_read_b128 v[198:201], v157 offset:33792
	ds_read_b128 v[202:205], v158 offset:32768
	ds_read_b128 v[206:209], v158 offset:33792
	global_load_lds_dwordx4 v[210:211], off
	v_lshl_add_u64 v[210:211], v[228:229], 0, s[0:1]
	s_mov_b32 m0, s60
	s_nop 0
	global_load_lds_dwordx4 v[210:211], off
	s_waitcnt lgkmcnt(8)
	s_barrier
	s_waitcnt lgkmcnt(0)
	v_mfma_f32_16x16x32_bf16 v[104:107], v[178:181], v[162:165], v[104:107]
	v_mfma_f32_16x16x32_bf16 v[100:103], v[178:181], v[170:173], v[100:103]
	v_mfma_f32_16x16x32_bf16 v[112:115], v[186:189], v[162:165], v[112:115]
	v_mfma_f32_16x16x32_bf16 v[108:111], v[186:189], v[170:173], v[108:111]
	v_mfma_f32_16x16x32_bf16 v[120:123], v[194:197], v[162:165], v[120:123]
	v_mfma_f32_16x16x32_bf16 v[116:119], v[194:197], v[170:173], v[116:119]
	v_mfma_f32_16x16x32_bf16 v[128:131], v[202:205], v[162:165], v[128:131]
	v_mfma_f32_16x16x32_bf16 v[124:127], v[202:205], v[170:173], v[124:127]
	v_mfma_f32_16x16x32_bf16 v[104:107], v[182:185], v[166:169], v[104:107]
	v_mfma_f32_16x16x32_bf16 v[100:103], v[182:185], v[174:177], v[100:103]
	v_mfma_f32_16x16x32_bf16 v[112:115], v[190:193], v[166:169], v[112:115]
	v_mfma_f32_16x16x32_bf16 v[108:111], v[190:193], v[174:177], v[108:111]
	v_mfma_f32_16x16x32_bf16 v[120:123], v[198:201], v[166:169], v[120:123]
	v_mfma_f32_16x16x32_bf16 v[116:119], v[198:201], v[174:177], v[116:119]
	v_mfma_f32_16x16x32_bf16 v[128:131], v[206:209], v[166:169], v[128:131]
	v_mfma_f32_16x16x32_bf16 v[124:127], v[206:209], v[174:177], v[124:127]
	s_barrier
	s_mov_b32 m0, s29
	v_lshl_add_u64 v[226:227], v[230:231], 0, s[90:91]
	ds_read_b128 v[210:213], v161
	ds_read_b128 v[214:217], v161 offset:1024
	ds_read_b128 v[218:221], v161 offset:2048
	ds_read_b128 v[222:225], v161 offset:3072
	global_load_lds_dwordx4 v[226:227], off
	v_lshl_add_u64 v[226:227], v[232:233], 0, s[90:91]
	s_mov_b32 m0, s40
	s_nop 0
	global_load_lds_dwordx4 v[226:227], off
	s_barrier
	s_waitcnt lgkmcnt(0)
	v_mfma_f32_16x16x32_bf16 v[72:75], v[178:181], v[210:213], v[72:75]
	v_mfma_f32_16x16x32_bf16 v[68:71], v[178:181], v[218:221], v[68:71]
	v_mfma_f32_16x16x32_bf16 v[80:83], v[186:189], v[210:213], v[80:83]
	v_mfma_f32_16x16x32_bf16 v[76:79], v[186:189], v[218:221], v[76:79]
	v_mfma_f32_16x16x32_bf16 v[88:91], v[194:197], v[210:213], v[88:91]
	v_mfma_f32_16x16x32_bf16 v[84:87], v[194:197], v[218:221], v[84:87]
	v_mfma_f32_16x16x32_bf16 v[96:99], v[202:205], v[210:213], v[96:99]
	v_mfma_f32_16x16x32_bf16 v[92:95], v[202:205], v[218:221], v[92:95]
	v_mfma_f32_16x16x32_bf16 v[72:75], v[182:185], v[214:217], v[72:75]
	v_mfma_f32_16x16x32_bf16 v[68:71], v[182:185], v[222:225], v[68:71]
	v_mfma_f32_16x16x32_bf16 v[80:83], v[190:193], v[214:217], v[80:83]
	v_mfma_f32_16x16x32_bf16 v[76:79], v[190:193], v[222:225], v[76:79]
	v_mfma_f32_16x16x32_bf16 v[88:91], v[198:201], v[214:217], v[88:91]
	v_mfma_f32_16x16x32_bf16 v[84:87], v[198:201], v[222:225], v[84:87]
	v_mfma_f32_16x16x32_bf16 v[96:99], v[206:209], v[214:217], v[96:99]
	v_mfma_f32_16x16x32_bf16 v[92:95], v[206:209], v[222:225], v[92:95]
	s_mov_b32 m0, s41
	v_lshl_add_u64 v[226:227], v[236:237], 0, s[90:91]
	s_barrier
	ds_read_b128 v[178:181], v155 offset:49152
	ds_read_b128 v[182:185], v155 offset:50176
	ds_read_b128 v[186:189], v156 offset:49152
	ds_read_b128 v[190:193], v156 offset:50176
	ds_read_b128 v[194:197], v157 offset:49152
	ds_read_b128 v[198:201], v157 offset:50176
	ds_read_b128 v[202:205], v158 offset:49152
	ds_read_b128 v[206:209], v158 offset:50176
	global_load_lds_dwordx4 v[226:227], off
	v_lshl_add_u64 v[226:227], v[238:239], 0, s[90:91]
	s_mov_b32 m0, s42
	s_nop 0
	global_load_lds_dwordx4 v[226:227], off
	s_barrier
; #define STAGE(P, BASE, br, kt) do { const char* _gb = (const char*)((BASE) + ((long)(br) * K + (long)(kt) * BK)); \
;     __builtin_amdgcn_global_load_lds((const unsigned*)(_gb + (size_t)so0), (unsigned*)((char*)(P) + wv1k), 16, 0, 0); \
;     __builtin_amdgcn_global_load_lds((const unsigned*)(_gb + (size_t)so1), (unsigned*)((char*)(P) + wv1k + 8192), 16, 0, 0); } while (0)
; #define LDA(dst, b, h) _Pragma("unroll") for (int m = 0; m < 4; ++m) _Pragma("unroll") for (int k = 0; k < 2; ++k) \
;     dst[m][k] = *reinterpret_cast<const bf16x8*>((char*)SA(b, h) + lds_byte(wr * 64 + m * 16 + fr, k * 32 + fq * 8))
; #define LDB(dst, b, h) _Pragma("unroll") for (int n = 0; n < 2; ++n) _Pragma("unroll") for (int k = 0; k < 2; ++k) \
;     dst[n][k] = *reinterpret_cast<const bf16x8*>((char*)SB(b, h) + lds_byte(wc * 32 + n * 16 + fr, k * 32 + fq * 8))
; #define MMA(ai, bj, At_, Bt_) do { __builtin_amdgcn_s_setprio(1); \
;     _Pragma("unroll") for (int m = 0; m < 4; ++m) _Pragma("unroll") for (int n = 0; n < 2; ++n) _Pragma("unroll") for (int k = 0; k < 2; ++k) \
;       acc[ai][bj][m][n] = __builtin_amdgcn_mfma_f32_16x16x32_bf16(At_[m][k], Bt_[n][k], acc[ai][bj][m][n], 0, 0, 0); \
;     __builtin_amdgcn_s_setprio(0); } while (0)
; #define WAIT_V(n) asm volatile("s_waitcnt vmcnt(" #n ")" ::: "memory")
; #define WAIT_L(n) asm volatile("s_waitcnt lgkmcnt(" #n ")" ::: "memory")
; #define BAR __builtin_amdgcn_s_barrier()
; #define SCHED __builtin_amdgcn_sched_barrier(0)
; template <class Epi> ...
;     ...
;     BAR; WAIT_L(0); MMA(1, 0, At, B0); BAR; SCHED;
;     STAGE(SB(1, 1), Bt, bcol + HALF, t + 3);
;     WAIT_V(6); BAR; MMA(1, 1, At, B1); BAR;
;   }
;   { LDB(B0, 0, 0); LDA(At, 0, 0); STAGE(SA(1, 1), A, brow + HALF, nt - 1);
;     BAR; WAIT_L(0); MMA(0, 0, At, B0); BAR;
;     LDB(B1, 0, 1); BAR; WAIT_L(0); MMA(0, 1, At, B1); BAR;
	s_waitcnt lgkmcnt(0)
	v_mfma_f32_16x16x32_bf16 v[40:43], v[178:181], v[162:165], v[40:43]
	v_mfma_f32_16x16x32_bf16 v[36:39], v[178:181], v[170:173], v[36:39]
	v_mfma_f32_16x16x32_bf16 v[48:51], v[186:189], v[162:165], v[48:51]
	v_mfma_f32_16x16x32_bf16 v[44:47], v[186:189], v[170:173], v[44:47]
	v_mfma_f32_16x16x32_bf16 v[56:59], v[194:197], v[162:165], v[56:59]
	v_mfma_f32_16x16x32_bf16 v[52:55], v[194:197], v[170:173], v[52:55]
	v_mfma_f32_16x16x32_bf16 v[64:67], v[202:205], v[162:165], v[64:67]
	v_mfma_f32_16x16x32_bf16 v[60:63], v[202:205], v[170:173], v[60:63]
	v_mfma_f32_16x16x32_bf16 v[40:43], v[182:185], v[166:169], v[40:43]
	v_mfma_f32_16x16x32_bf16 v[36:39], v[182:185], v[174:177], v[36:39]
	v_mfma_f32_16x16x32_bf16 v[48:51], v[190:193], v[166:169], v[48:51]
	v_mfma_f32_16x16x32_bf16 v[44:47], v[190:193], v[174:177], v[44:47]
	v_mfma_f32_16x16x32_bf16 v[56:59], v[198:201], v[166:169], v[56:59]
	v_mfma_f32_16x16x32_bf16 v[52:55], v[198:201], v[174:177], v[52:55]
	v_mfma_f32_16x16x32_bf16 v[64:67], v[206:209], v[166:169], v[64:67]
	v_mfma_f32_16x16x32_bf16 v[60:63], v[206:209], v[174:177], v[60:63]
	s_barrier
	s_mov_b32 m0, s43
	v_lshl_add_u64 v[162:163], v[240:241], 0, s[90:91]
	global_load_lds_dwordx4 v[162:163], off
	v_lshl_add_u64 v[162:163], v[242:243], 0, s[90:91]
	s_mov_b32 m0, s44
	s_nop 0
	global_load_lds_dwordx4 v[162:163], off
	s_waitcnt vmcnt(6)
	s_barrier
	v_mfma_f32_16x16x32_bf16 v[8:11], v[178:181], v[210:213], v[8:11]
	v_mfma_f32_16x16x32_bf16 v[4:7], v[178:181], v[218:221], v[4:7]
	v_mfma_f32_16x16x32_bf16 v[16:19], v[186:189], v[210:213], v[16:19]
	v_mfma_f32_16x16x32_bf16 v[12:15], v[186:189], v[218:221], v[12:15]
	v_mfma_f32_16x16x32_bf16 v[24:27], v[194:197], v[210:213], v[24:27]
	v_mfma_f32_16x16x32_bf16 v[20:23], v[194:197], v[218:221], v[20:23]
	v_mfma_f32_16x16x32_bf16 v[32:35], v[202:205], v[210:213], v[32:35]
	v_mfma_f32_16x16x32_bf16 v[28:31], v[202:205], v[218:221], v[28:31]
	v_mfma_f32_16x16x32_bf16 v[8:11], v[182:185], v[214:217], v[8:11]
	v_mfma_f32_16x16x32_bf16 v[4:7], v[182:185], v[222:225], v[4:7]
	v_mfma_f32_16x16x32_bf16 v[16:19], v[190:193], v[214:217], v[16:19]
	v_mfma_f32_16x16x32_bf16 v[12:15], v[190:193], v[222:225], v[12:15]
	v_mfma_f32_16x16x32_bf16 v[24:27], v[198:201], v[214:217], v[24:27]
	v_mfma_f32_16x16x32_bf16 v[20:23], v[198:201], v[222:225], v[20:23]
	v_mfma_f32_16x16x32_bf16 v[32:35], v[206:209], v[214:217], v[32:35]
	v_mfma_f32_16x16x32_bf16 v[28:31], v[206:209], v[222:225], v[28:31]
	s_add_u32 s24, s24, 0x100
	s_addc_u32 s25, s25, 0
	s_cmp_lt_u32 s26, s45
	s_barrier
	s_cbranch_scc1 .LBB0_133
	s_add_i32 s96, s28, -1
	s_lshl_b64 s[24:25], s[96:97], 7
	s_add_u32 s22, s22, s24
	s_addc_u32 s23, s23, s25
	s_mov_b32 m0, s30
	v_lshl_add_u64 v[194:195], s[22:23], 0, v[0:1]
	ds_read_b128 v[132:135], v154
	ds_read_b128 v[136:139], v154 offset:1024
	ds_read_b128 v[140:143], v154 offset:2048
	ds_read_b128 v[144:147], v154 offset:3072
	ds_read_b128 v[162:165], v155
	ds_read_b128 v[166:169], v155 offset:1024
	ds_read_b128 v[170:173], v156
	ds_read_b128 v[174:177], v156 offset:1024
	ds_read_b128 v[178:181], v157
	ds_read_b128 v[182:185], v157 offset:1024
	ds_read_b128 v[186:189], v158
	ds_read_b128 v[190:193], v158 offset:1024
	global_load_lds_dwordx4 v[194:195], off
	v_lshl_add_u64 v[2:3], s[22:23], 0, v[2:3]
	s_mov_b32 m0, s27
	s_nop 0
	global_load_lds_dwordx4 v[2:3], off
	s_barrier
	s_waitcnt lgkmcnt(0)
	v_mfma_f32_16x16x32_bf16 v[104:107], v[162:165], v[132:135], v[104:107]
	v_mfma_f32_16x16x32_bf16 v[100:103], v[162:165], v[140:143], v[100:103]
	v_mfma_f32_16x16x32_bf16 v[112:115], v[170:173], v[132:135], v[112:115]
	v_mfma_f32_16x16x32_bf16 v[108:111], v[170:173], v[140:143], v[108:111]
	v_mfma_f32_16x16x32_bf16 v[120:123], v[178:181], v[132:135], v[120:123]
	v_mfma_f32_16x16x32_bf16 v[116:119], v[178:181], v[140:143], v[116:119]
	v_mfma_f32_16x16x32_bf16 v[128:131], v[186:189], v[132:135], v[128:131]
	v_mfma_f32_16x16x32_bf16 v[124:127], v[186:189], v[140:143], v[124:127]
	v_mfma_f32_16x16x32_bf16 v[104:107], v[166:169], v[136:139], v[104:107]
	v_mfma_f32_16x16x32_bf16 v[100:103], v[166:169], v[144:147], v[100:103]
	v_mfma_f32_16x16x32_bf16 v[112:115], v[174:177], v[136:139], v[112:115]
	v_mfma_f32_16x16x32_bf16 v[108:111], v[174:177], v[144:147], v[108:111]
	v_mfma_f32_16x16x32_bf16 v[120:123], v[182:185], v[136:139], v[120:123]
	v_mfma_f32_16x16x32_bf16 v[116:119], v[182:185], v[144:147], v[116:119]
	v_mfma_f32_16x16x32_bf16 v[128:131], v[190:193], v[136:139], v[128:131]
	v_mfma_f32_16x16x32_bf16 v[124:127], v[190:193], v[144:147], v[124:127]
	s_barrier
	ds_read_b128 v[194:197], v159
	ds_read_b128 v[198:201], v159 offset:1024
	ds_read_b128 v[202:205], v159 offset:2048
	ds_read_b128 v[206:209], v159 offset:3072
	s_barrier
	s_waitcnt lgkmcnt(0)
	v_mfma_f32_16x16x32_bf16 v[72:75], v[162:165], v[194:197], v[72:75]
	v_mfma_f32_16x16x32_bf16 v[68:71], v[162:165], v[202:205], v[68:71]
	v_mfma_f32_16x16x32_bf16 v[80:83], v[170:173], v[194:197], v[80:83]
	v_mfma_f32_16x16x32_bf16 v[76:79], v[170:173], v[202:205], v[76:79]
	v_mfma_f32_16x16x32_bf16 v[88:91], v[178:181], v[194:197], v[88:91]
	v_mfma_f32_16x16x32_bf16 v[84:87], v[178:181], v[202:205], v[84:87]
	v_mfma_f32_16x16x32_bf16 v[96:99], v[186:189], v[194:197], v[96:99]
	v_mfma_f32_16x16x32_bf16 v[92:95], v[186:189], v[202:205], v[92:95]
	v_mfma_f32_16x16x32_bf16 v[72:75], v[166:169], v[198:201], v[72:75]
	v_mfma_f32_16x16x32_bf16 v[68:71], v[166:169], v[206:209], v[68:71]
	v_mfma_f32_16x16x32_bf16 v[80:83], v[174:177], v[198:201], v[80:83]
	v_mfma_f32_16x16x32_bf16 v[76:79], v[174:177], v[206:209], v[76:79]
	v_mfma_f32_16x16x32_bf16 v[88:91], v[182:185], v[198:201], v[88:91]
	v_mfma_f32_16x16x32_bf16 v[84:87], v[182:185], v[206:209], v[84:87]
	v_mfma_f32_16x16x32_bf16 v[96:99], v[190:193], v[198:201], v[96:99]
	v_mfma_f32_16x16x32_bf16 v[92:95], v[190:193], v[206:209], v[92:95]
	s_barrier
; #define LDA(dst, b, h) _Pragma("unroll") for (int m = 0; m < 4; ++m) _Pragma("unroll") for (int k = 0; k < 2; ++k) \
;     dst[m][k] = *reinterpret_cast<const bf16x8*>((char*)SA(b, h) + lds_byte(wr * 64 + m * 16 + fr, k * 32 + fq * 8))
; #define LDB(dst, b, h) _Pragma("unroll") for (int n = 0; n < 2; ++n) _Pragma("unroll") for (int k = 0; k < 2; ++k) \
;     dst[n][k] = *reinterpret_cast<const bf16x8*>((char*)SB(b, h) + lds_byte(wc * 32 + n * 16 + fr, k * 32 + fq * 8))
; #define MMA(ai, bj, At_, Bt_) do { __builtin_amdgcn_s_setprio(1); \
;     _Pragma("unroll") for (int m = 0; m < 4; ++m) _Pragma("unroll") for (int n = 0; n < 2; ++n) _Pragma("unroll") for (int k = 0; k < 2; ++k) \
;       acc[ai][bj][m][n] = __builtin_amdgcn_mfma_f32_16x16x32_bf16(At_[m][k], Bt_[n][k], acc[ai][bj][m][n], 0, 0, 0); \
;     __builtin_amdgcn_s_setprio(0); } while (0)
; #define WAIT_V(n) asm volatile("s_waitcnt vmcnt(" #n ")" ::: "memory")
; #define WAIT_L(n) asm volatile("s_waitcnt lgkmcnt(" #n ")" ::: "memory")
; #define BAR __builtin_amdgcn_s_barrier()
; template <class Epi> ...
;     ...
;     LDA(At, 0, 1); WAIT_V(4); BAR; WAIT_L(0); MMA(1, 0, At, B0); MMA(1, 1, At, B1); BAR; }
;   { LDB(B0, 1, 0); LDA(At, 1, 0); WAIT_V(2); BAR; WAIT_L(0); MMA(0, 0, At, B0); BAR;
	ds_read_b128 v[162:165], v155 offset:16384
	ds_read_b128 v[166:169], v155 offset:17408
	ds_read_b128 v[170:173], v156 offset:16384
	ds_read_b128 v[174:177], v156 offset:17408
	ds_read_b128 v[178:181], v157 offset:16384
	ds_read_b128 v[182:185], v157 offset:17408
	ds_read_b128 v[186:189], v158 offset:16384
	ds_read_b128 v[190:193], v158 offset:17408
	s_waitcnt vmcnt(4)
	s_barrier
	s_waitcnt lgkmcnt(0)
	v_mfma_f32_16x16x32_bf16 v[40:43], v[162:165], v[132:135], v[40:43]
	v_mfma_f32_16x16x32_bf16 v[36:39], v[162:165], v[140:143], v[36:39]
	v_mfma_f32_16x16x32_bf16 v[48:51], v[170:173], v[132:135], v[48:51]
	v_mfma_f32_16x16x32_bf16 v[44:47], v[170:173], v[140:143], v[44:47]
	v_mfma_f32_16x16x32_bf16 v[56:59], v[178:181], v[132:135], v[56:59]
	v_mfma_f32_16x16x32_bf16 v[52:55], v[178:181], v[140:143], v[52:55]
	v_mfma_f32_16x16x32_bf16 v[64:67], v[186:189], v[132:135], v[64:67]
	v_mfma_f32_16x16x32_bf16 v[60:63], v[186:189], v[140:143], v[60:63]
	v_mfma_f32_16x16x32_bf16 v[40:43], v[166:169], v[136:139], v[40:43]
	v_mfma_f32_16x16x32_bf16 v[36:39], v[166:169], v[144:147], v[36:39]
	v_mfma_f32_16x16x32_bf16 v[48:51], v[174:177], v[136:139], v[48:51]
	v_mfma_f32_16x16x32_bf16 v[44:47], v[174:177], v[144:147], v[44:47]
	v_mfma_f32_16x16x32_bf16 v[56:59], v[182:185], v[136:139], v[56:59]
	v_mfma_f32_16x16x32_bf16 v[52:55], v[182:185], v[144:147], v[52:55]
	v_mfma_f32_16x16x32_bf16 v[64:67], v[190:193], v[136:139], v[64:67]
	v_mfma_f32_16x16x32_bf16 v[60:63], v[190:193], v[144:147], v[60:63]
	v_mfma_f32_16x16x32_bf16 v[8:11], v[162:165], v[194:197], v[8:11]
	v_mfma_f32_16x16x32_bf16 v[2:5], v[162:165], v[202:205], v[4:7]
	v_mfma_f32_16x16x32_bf16 v[16:19], v[170:173], v[194:197], v[16:19]
	v_mfma_f32_16x16x32_bf16 v[12:15], v[170:173], v[202:205], v[12:15]
	v_mfma_f32_16x16x32_bf16 v[24:27], v[178:181], v[194:197], v[24:27]
	v_mfma_f32_16x16x32_bf16 v[20:23], v[178:181], v[202:205], v[20:23]
	v_mfma_f32_16x16x32_bf16 v[32:35], v[186:189], v[194:197], v[32:35]
	v_mfma_f32_16x16x32_bf16 v[28:31], v[186:189], v[202:205], v[28:31]
	v_mfma_f32_16x16x32_bf16 v[8:11], v[166:169], v[198:201], v[8:11]
	v_mfma_f32_16x16x32_bf16 v[2:5], v[166:169], v[206:209], v[2:5]
	v_mfma_f32_16x16x32_bf16 v[16:19], v[174:177], v[198:201], v[16:19]
	v_mfma_f32_16x16x32_bf16 v[12:15], v[174:177], v[206:209], v[12:15]
	v_mfma_f32_16x16x32_bf16 v[24:27], v[182:185], v[198:201], v[24:27]
	v_mfma_f32_16x16x32_bf16 v[20:23], v[182:185], v[206:209], v[20:23]
	v_mfma_f32_16x16x32_bf16 v[32:35], v[190:193], v[198:201], v[32:35]
	v_mfma_f32_16x16x32_bf16 v[28:31], v[190:193], v[206:209], v[28:31]
	s_barrier
	ds_read_b128 v[132:135], v160
	ds_read_b128 v[136:139], v160 offset:1024
	ds_read_b128 v[140:143], v160 offset:2048
	ds_read_b128 v[144:147], v160 offset:3072
	ds_read_b128 v[162:165], v155 offset:32768
	ds_read_b128 v[166:169], v155 offset:33792
	ds_read_b128 v[170:173], v156 offset:32768
	ds_read_b128 v[174:177], v156 offset:33792
	ds_read_b128 v[178:181], v157 offset:32768
	ds_read_b128 v[182:185], v157 offset:33792
	ds_read_b128 v[186:189], v158 offset:32768
	ds_read_b128 v[190:193], v158 offset:33792
	s_waitcnt vmcnt(2)
	s_barrier
	s_waitcnt lgkmcnt(0)
	v_mfma_f32_16x16x32_bf16 v[104:107], v[162:165], v[132:135], v[104:107]
	v_mfma_f32_16x16x32_bf16 v[100:103], v[162:165], v[140:143], v[100:103]
	v_mfma_f32_16x16x32_bf16 v[112:115], v[170:173], v[132:135], v[112:115]
	v_mfma_f32_16x16x32_bf16 v[108:111], v[170:173], v[140:143], v[108:111]
	v_mfma_f32_16x16x32_bf16 v[120:123], v[178:181], v[132:135], v[120:123]
	v_mfma_f32_16x16x32_bf16 v[116:119], v[178:181], v[140:143], v[116:119]
	v_mfma_f32_16x16x32_bf16 v[128:131], v[186:189], v[132:135], v[128:131]
	v_mfma_f32_16x16x32_bf16 v[124:127], v[186:189], v[140:143], v[124:127]
	v_mfma_f32_16x16x32_bf16 v[104:107], v[166:169], v[136:139], v[104:107]
	v_mfma_f32_16x16x32_bf16 v[100:103], v[166:169], v[144:147], v[100:103]
	v_mfma_f32_16x16x32_bf16 v[112:115], v[174:177], v[136:139], v[112:115]
	v_mfma_f32_16x16x32_bf16 v[108:111], v[174:177], v[144:147], v[108:111]
	v_mfma_f32_16x16x32_bf16 v[120:123], v[182:185], v[136:139], v[120:123]
	v_mfma_f32_16x16x32_bf16 v[116:119], v[182:185], v[144:147], v[116:119]
	v_mfma_f32_16x16x32_bf16 v[128:131], v[190:193], v[136:139], v[128:131]
	v_mfma_f32_16x16x32_bf16 v[124:127], v[190:193], v[144:147], v[124:127]
	s_barrier
; #define LDA(dst, b, h) _Pragma("unroll") for (int m = 0; m < 4; ++m) _Pragma("unroll") for (int k = 0; k < 2; ++k) \
;     dst[m][k] = *reinterpret_cast<const bf16x8*>((char*)SA(b, h) + lds_byte(wr * 64 + m * 16 + fr, k * 32 + fq * 8))
; #define LDB(dst, b, h) _Pragma("unroll") for (int n = 0; n < 2; ++n) _Pragma("unroll") for (int k = 0; k < 2; ++k) \
;     dst[n][k] = *reinterpret_cast<const bf16x8*>((char*)SB(b, h) + lds_byte(wc * 32 + n * 16 + fr, k * 32 + fq * 8))
; #define MMA(ai, bj, At_, Bt_) do { __builtin_amdgcn_s_setprio(1); \
;     _Pragma("unroll") for (int m = 0; m < 4; ++m) _Pragma("unroll") for (int n = 0; n < 2; ++n) _Pragma("unroll") for (int k = 0; k < 2; ++k) \
;       acc[ai][bj][m][n] = __builtin_amdgcn_mfma_f32_16x16x32_bf16(At_[m][k], Bt_[n][k], acc[ai][bj][m][n], 0, 0, 0); \
;     __builtin_amdgcn_s_setprio(0); } while (0)
; #define WAIT_V(n) asm volatile("s_waitcnt vmcnt(" #n ")" ::: "memory")
; #define WAIT_L(n) asm volatile("s_waitcnt lgkmcnt(" #n ")" ::: "memory")
; #define BAR __builtin_amdgcn_s_barrier()
; template <class Epi> ...
;     ...
;     LDB(B1, 1, 1); WAIT_V(0); BAR; WAIT_L(0); MMA(0, 1, At, B1); BAR;
;     LDA(At, 1, 1); BAR; WAIT_L(0); MMA(1, 0, At, B0); MMA(1, 1, At, B1); BAR; }
;   if (wr == 0) BAR;
	ds_read_b128 v[194:197], v161
	ds_read_b128 v[198:201], v161 offset:1024
	ds_read_b128 v[202:205], v161 offset:2048
	ds_read_b128 v[206:209], v161 offset:3072
	s_waitcnt vmcnt(0)
	s_barrier
	s_waitcnt lgkmcnt(0)
	v_mfma_f32_16x16x32_bf16 v[72:75], v[162:165], v[194:197], v[72:75]
	v_mfma_f32_16x16x32_bf16 v[68:71], v[162:165], v[202:205], v[68:71]
	v_mfma_f32_16x16x32_bf16 v[80:83], v[170:173], v[194:197], v[80:83]
	v_mfma_f32_16x16x32_bf16 v[76:79], v[170:173], v[202:205], v[76:79]
	v_mfma_f32_16x16x32_bf16 v[88:91], v[178:181], v[194:197], v[88:91]
	v_mfma_f32_16x16x32_bf16 v[84:87], v[178:181], v[202:205], v[84:87]
	v_mfma_f32_16x16x32_bf16 v[96:99], v[186:189], v[194:197], v[96:99]
	v_mfma_f32_16x16x32_bf16 v[92:95], v[186:189], v[202:205], v[92:95]
	v_mfma_f32_16x16x32_bf16 v[72:75], v[166:169], v[198:201], v[72:75]
	v_mfma_f32_16x16x32_bf16 v[68:71], v[166:169], v[206:209], v[68:71]
	v_mfma_f32_16x16x32_bf16 v[80:83], v[174:177], v[198:201], v[80:83]
	v_mfma_f32_16x16x32_bf16 v[76:79], v[174:177], v[206:209], v[76:79]
	v_mfma_f32_16x16x32_bf16 v[88:91], v[182:185], v[198:201], v[88:91]
	v_mfma_f32_16x16x32_bf16 v[84:87], v[182:185], v[206:209], v[84:87]
	v_mfma_f32_16x16x32_bf16 v[96:99], v[190:193], v[198:201], v[96:99]
	v_mfma_f32_16x16x32_bf16 v[92:95], v[190:193], v[206:209], v[92:95]
	s_barrier
	ds_read_b128 v[162:165], v155 offset:49152
	ds_read_b128 v[166:169], v155 offset:50176
	ds_read_b128 v[170:173], v156 offset:49152
	ds_read_b128 v[174:177], v156 offset:50176
	ds_read_b128 v[178:181], v157 offset:49152
	ds_read_b128 v[182:185], v157 offset:50176
	ds_read_b128 v[186:189], v158 offset:49152
	ds_read_b128 v[190:193], v158 offset:50176
	s_barrier
	s_waitcnt lgkmcnt(0)
	v_mfma_f32_16x16x32_bf16 v[40:43], v[162:165], v[132:135], v[40:43]
	v_mfma_f32_16x16x32_bf16 v[36:39], v[162:165], v[140:143], v[36:39]
	v_mfma_f32_16x16x32_bf16 v[48:51], v[170:173], v[132:135], v[48:51]
	v_mfma_f32_16x16x32_bf16 v[44:47], v[170:173], v[140:143], v[44:47]
	v_mfma_f32_16x16x32_bf16 v[56:59], v[178:181], v[132:135], v[56:59]
	v_mfma_f32_16x16x32_bf16 v[52:55], v[178:181], v[140:143], v[52:55]
	v_mfma_f32_16x16x32_bf16 v[64:67], v[186:189], v[132:135], v[64:67]
	v_mfma_f32_16x16x32_bf16 v[60:63], v[186:189], v[140:143], v[60:63]
	v_mfma_f32_16x16x32_bf16 v[40:43], v[166:169], v[136:139], v[40:43]
	v_mfma_f32_16x16x32_bf16 v[36:39], v[166:169], v[144:147], v[36:39]
	v_mfma_f32_16x16x32_bf16 v[48:51], v[174:177], v[136:139], v[48:51]
	v_mfma_f32_16x16x32_bf16 v[44:47], v[174:177], v[144:147], v[44:47]
	v_mfma_f32_16x16x32_bf16 v[56:59], v[182:185], v[136:139], v[56:59]
	v_mfma_f32_16x16x32_bf16 v[52:55], v[182:185], v[144:147], v[52:55]
	v_mfma_f32_16x16x32_bf16 v[64:67], v[190:193], v[136:139], v[64:67]
	v_mfma_f32_16x16x32_bf16 v[60:63], v[190:193], v[144:147], v[60:63]
	v_mfma_f32_16x16x32_bf16 v[6:9], v[162:165], v[194:197], v[8:11]
	v_mfma_f32_16x16x32_bf16 v[2:5], v[162:165], v[202:205], v[2:5]
	v_mfma_f32_16x16x32_bf16 v[16:19], v[170:173], v[194:197], v[16:19]
	v_mfma_f32_16x16x32_bf16 v[12:15], v[170:173], v[202:205], v[12:15]
	v_mfma_f32_16x16x32_bf16 v[24:27], v[178:181], v[194:197], v[24:27]
	v_mfma_f32_16x16x32_bf16 v[20:23], v[178:181], v[202:205], v[20:23]
	v_mfma_f32_16x16x32_bf16 v[32:35], v[186:189], v[194:197], v[32:35]
	v_mfma_f32_16x16x32_bf16 v[28:31], v[186:189], v[202:205], v[28:31]
	v_mfma_f32_16x16x32_bf16 v[8:11], v[166:169], v[198:201], v[6:9]
	v_mfma_f32_16x16x32_bf16 v[4:7], v[166:169], v[206:209], v[2:5]
	v_mfma_f32_16x16x32_bf16 v[16:19], v[174:177], v[198:201], v[16:19]
	v_mfma_f32_16x16x32_bf16 v[12:15], v[174:177], v[206:209], v[12:15]
	v_mfma_f32_16x16x32_bf16 v[24:27], v[182:185], v[198:201], v[24:27]
	v_mfma_f32_16x16x32_bf16 v[20:23], v[182:185], v[206:209], v[20:23]
	v_mfma_f32_16x16x32_bf16 v[32:35], v[190:193], v[198:201], v[32:35]
	v_mfma_f32_16x16x32_bf16 v[28:31], v[190:193], v[206:209], v[28:31]
	s_barrier
	s_and_saveexec_b64 s[22:23], s[6:7]
	s_cbranch_execz .LBB0_136
	s_barrier

; #define STAGE(P, BASE, br, kt) do { const char* _gb = (const char*)((BASE) + ((long)(br) * K + (long)(kt) * BK)); \
;     __builtin_amdgcn_global_load_lds((const unsigned*)(_gb + (size_t)so0), (unsigned*)((char*)(P) + wv1k), 16, 0, 0); \
;     __builtin_amdgcn_global_load_lds((const unsigned*)(_gb + (size_t)so1), (unsigned*)((char*)(P) + wv1k + 8192), 16, 0, 0); } while (0)
; #define LDA(dst, b, h) _Pragma("unroll") for (int m = 0; m < 4; ++m) _Pragma("unroll") for (int k = 0; k < 2; ++k) \
;     dst[m][k] = *reinterpret_cast<const bf16x8*>((char*)SA(b, h) + lds_byte(wr * 64 + m * 16 + fr, k * 32 + fq * 8))
; #define LDB(dst, b, h) _Pragma("unroll") for (int n = 0; n < 2; ++n) _Pragma("unroll") for (int k = 0; k < 2; ++k) \
;     dst[n][k] = *reinterpret_cast<const bf16x8*>((char*)SB(b, h) + lds_byte(wc * 32 + n * 16 + fr, k * 32 + fq * 8))
; #define MMA(ai, bj, At_, Bt_) do { __builtin_amdgcn_s_setprio(1); \
;     _Pragma("unroll") for (int m = 0; m < 4; ++m) _Pragma("unroll") for (int n = 0; n < 2; ++n) _Pragma("unroll") for (int k = 0; k < 2; ++k) \
;       acc[ai][bj][m][n] = __builtin_amdgcn_mfma_f32_16x16x32_bf16(At_[m][k], Bt_[n][k], acc[ai][bj][m][n], 0, 0, 0); \
;     __builtin_amdgcn_s_setprio(0); } while (0)
; #define WAIT_V(n) asm volatile("s_waitcnt vmcnt(" #n ")" ::: "memory")
; #define WAIT_L(n) asm volatile("s_waitcnt lgkmcnt(" #n ")" ::: "memory")
; #define BAR __builtin_amdgcn_s_barrier()
; #define SCHED __builtin_amdgcn_sched_barrier(0)
; template <class Epi> ...
;     ...
;     LDB(B0, 0, 0); SCHED; LDA(At, 0, 0); STAGE(SA(1, 1), A, brow + HALF, t + 1);
;     WAIT_L(8); BAR; WAIT_L(0); MMA(0, 0, At, B0); BAR; SCHED;
;     LDB(B1, 0, 1); STAGE(SB(0, 0), Bt, bcol, t + 2);
;     BAR; WAIT_L(0); MMA(0, 1, At, B1); BAR;
;     LDA(At, 0, 1); STAGE(SA(0, 0), A, brow, t + 2);
;     BAR; WAIT_L(0); MMA(1, 0, At, B0); BAR; SCHED;
;     STAGE(SB(0, 1), Bt, bcol + HALF, t + 2);
;     WAIT_V(6); BAR; MMA(1, 1, At, B1); BAR;
.LBB0_449:
	ds_read_b128 v[156:159], v175
	ds_read_b128 v[160:163], v175 offset:1024
	ds_read_b128 v[164:167], v175 offset:2048
	ds_read_b128 v[168:171], v175 offset:3072
	v_lshl_add_u64 v[172:173], v[148:149], 0, s[8:9]
	s_add_i32 s40, s20, 0xc000
	v_lshl_add_u64 v[216:217], v[172:173], 0, s[42:43]
	s_mov_b32 m0, s40
	v_lshl_add_u64 v[232:233], v[146:147], 0, s[8:9]
	s_add_i32 s11, s20, 0xe000
	ds_read_b128 v[184:187], v176
	ds_read_b128 v[188:191], v176 offset:1024
	ds_read_b128 v[192:195], v177
	ds_read_b128 v[196:199], v177 offset:1024
	ds_read_b128 v[200:203], v178
	ds_read_b128 v[204:207], v178 offset:1024
	ds_read_b128 v[208:211], v179
	ds_read_b128 v[212:215], v179 offset:1024
	global_load_lds_dwordx4 v[216:217], off
	v_lshl_add_u64 v[216:217], v[232:233], 0, s[42:43]
	s_mov_b32 m0, s11
	s_nop 0
	global_load_lds_dwordx4 v[216:217], off
	s_waitcnt lgkmcnt(8)
	s_barrier
	s_waitcnt lgkmcnt(0)
	v_mfma_f32_16x16x32_bf16 v[126:129], v[184:187], v[156:159], v[126:129]
	v_mfma_f32_16x16x32_bf16 v[122:125], v[184:187], v[164:167], v[122:125]
	v_mfma_f32_16x16x32_bf16 v[118:121], v[192:195], v[156:159], v[118:121]
	v_mfma_f32_16x16x32_bf16 v[114:117], v[192:195], v[164:167], v[114:117]
	v_mfma_f32_16x16x32_bf16 v[110:113], v[200:203], v[156:159], v[110:113]
	v_mfma_f32_16x16x32_bf16 v[106:109], v[200:203], v[164:167], v[106:109]
	v_mfma_f32_16x16x32_bf16 v[102:105], v[208:211], v[156:159], v[102:105]
	v_mfma_f32_16x16x32_bf16 v[98:101], v[208:211], v[164:167], v[98:101]
	v_mfma_f32_16x16x32_bf16 v[126:129], v[188:191], v[160:163], v[126:129]
	v_mfma_f32_16x16x32_bf16 v[122:125], v[188:191], v[168:171], v[122:125]
	v_mfma_f32_16x16x32_bf16 v[118:121], v[196:199], v[160:163], v[118:121]
	v_mfma_f32_16x16x32_bf16 v[114:117], v[196:199], v[168:171], v[114:117]
	v_mfma_f32_16x16x32_bf16 v[110:113], v[204:207], v[160:163], v[110:113]
	v_mfma_f32_16x16x32_bf16 v[106:109], v[204:207], v[168:171], v[106:109]
	v_mfma_f32_16x16x32_bf16 v[102:105], v[212:215], v[160:163], v[102:105]
	v_mfma_f32_16x16x32_bf16 v[98:101], v[212:215], v[168:171], v[98:101]
	s_barrier
	v_lshl_add_u64 v[236:237], v[154:155], 0, s[8:9]
	s_mov_b32 m0, s21
	v_lshl_add_u64 v[238:239], v[236:237], 0, s[0:1]
	ds_read_b128 v[216:219], v180
	ds_read_b128 v[220:223], v180 offset:1024
	ds_read_b128 v[224:227], v180 offset:2048
	ds_read_b128 v[228:231], v180 offset:3072
	global_load_lds_dwordx4 v[238:239], off
	v_lshl_add_u64 v[238:239], v[152:153], 0, s[8:9]
	v_lshl_add_u64 v[240:241], v[238:239], 0, s[0:1]
	s_mov_b32 m0, s23
	s_nop 0
	global_load_lds_dwordx4 v[240:241], off
	s_barrier
	s_waitcnt lgkmcnt(0)
	v_mfma_f32_16x16x32_bf16 v[94:97], v[184:187], v[216:219], v[94:97]
	v_mfma_f32_16x16x32_bf16 v[90:93], v[184:187], v[224:227], v[90:93]
	v_mfma_f32_16x16x32_bf16 v[86:89], v[192:195], v[216:219], v[86:89]
	v_mfma_f32_16x16x32_bf16 v[82:85], v[192:195], v[224:227], v[82:85]
	v_mfma_f32_16x16x32_bf16 v[78:81], v[200:203], v[216:219], v[78:81]
	v_mfma_f32_16x16x32_bf16 v[74:77], v[200:203], v[224:227], v[74:77]
	v_mfma_f32_16x16x32_bf16 v[70:73], v[208:211], v[216:219], v[70:73]
	v_mfma_f32_16x16x32_bf16 v[66:69], v[208:211], v[224:227], v[66:69]
	v_mfma_f32_16x16x32_bf16 v[94:97], v[188:191], v[220:223], v[94:97]
	v_mfma_f32_16x16x32_bf16 v[90:93], v[188:191], v[228:231], v[90:93]
	v_mfma_f32_16x16x32_bf16 v[86:89], v[196:199], v[220:223], v[86:89]
	v_mfma_f32_16x16x32_bf16 v[82:85], v[196:199], v[228:231], v[82:85]
	v_mfma_f32_16x16x32_bf16 v[78:81], v[204:207], v[220:223], v[78:81]
	v_mfma_f32_16x16x32_bf16 v[74:77], v[204:207], v[228:231], v[74:77]
	v_mfma_f32_16x16x32_bf16 v[70:73], v[212:215], v[220:223], v[70:73]
	v_mfma_f32_16x16x32_bf16 v[66:69], v[212:215], v[228:231], v[66:69]
	s_mov_b32 m0, s20
	v_lshl_add_u64 v[240:241], v[172:173], 0, s[0:1]
	s_barrier
	ds_read_b128 v[184:187], v176 offset:16384
	ds_read_b128 v[188:191], v176 offset:17408
	ds_read_b128 v[192:195], v177 offset:16384
	ds_read_b128 v[196:199], v177 offset:17408
	ds_read_b128 v[200:203], v178 offset:16384
	ds_read_b128 v[204:207], v178 offset:17408
	ds_read_b128 v[208:211], v179 offset:16384
	ds_read_b128 v[212:215], v179 offset:17408
	global_load_lds_dwordx4 v[240:241], off
	v_lshl_add_u64 v[240:241], v[232:233], 0, s[0:1]
	s_mov_b32 m0, s13
	s_nop 0
	global_load_lds_dwordx4 v[240:241], off
	s_barrier
	s_waitcnt lgkmcnt(0)
	v_mfma_f32_16x16x32_bf16 v[62:65], v[184:187], v[156:159], v[62:65]
	v_mfma_f32_16x16x32_bf16 v[58:61], v[184:187], v[164:167], v[58:61]
	v_mfma_f32_16x16x32_bf16 v[54:57], v[192:195], v[156:159], v[54:57]
	v_mfma_f32_16x16x32_bf16 v[50:53], v[192:195], v[164:167], v[50:53]
	v_mfma_f32_16x16x32_bf16 v[46:49], v[200:203], v[156:159], v[46:49]
	v_mfma_f32_16x16x32_bf16 v[42:45], v[200:203], v[164:167], v[42:45]
	v_mfma_f32_16x16x32_bf16 v[38:41], v[208:211], v[156:159], v[38:41]
	v_mfma_f32_16x16x32_bf16 v[34:37], v[208:211], v[164:167], v[34:37]
	v_mfma_f32_16x16x32_bf16 v[62:65], v[188:191], v[160:163], v[62:65]
	v_mfma_f32_16x16x32_bf16 v[58:61], v[188:191], v[168:171], v[58:61]
	v_mfma_f32_16x16x32_bf16 v[54:57], v[196:199], v[160:163], v[54:57]
	v_mfma_f32_16x16x32_bf16 v[50:53], v[196:199], v[168:171], v[50:53]
	v_mfma_f32_16x16x32_bf16 v[46:49], v[204:207], v[160:163], v[46:49]
	v_mfma_f32_16x16x32_bf16 v[42:45], v[204:207], v[168:171], v[42:45]
	v_mfma_f32_16x16x32_bf16 v[38:41], v[212:215], v[160:163], v[38:41]
	v_mfma_f32_16x16x32_bf16 v[34:37], v[212:215], v[168:171], v[34:37]
	s_barrier
	s_mov_b32 m0, s24
	v_lshl_add_u64 v[156:157], v[236:237], 0, s[44:45]
	global_load_lds_dwordx4 v[156:157], off
	v_lshl_add_u64 v[156:157], v[238:239], 0, s[44:45]
	s_mov_b32 m0, s25
	s_nop 0
	global_load_lds_dwordx4 v[156:157], off
	s_waitcnt vmcnt(6)
	s_barrier
; #define STAGE(P, BASE, br, kt) do { const char* _gb = (const char*)((BASE) + ((long)(br) * K + (long)(kt) * BK)); \
;     __builtin_amdgcn_global_load_lds((const unsigned*)(_gb + (size_t)so0), (unsigned*)((char*)(P) + wv1k), 16, 0, 0); \
;     __builtin_amdgcn_global_load_lds((const unsigned*)(_gb + (size_t)so1), (unsigned*)((char*)(P) + wv1k + 8192), 16, 0, 0); } while (0)
; #define LDA(dst, b, h) _Pragma("unroll") for (int m = 0; m < 4; ++m) _Pragma("unroll") for (int k = 0; k < 2; ++k) \
;     dst[m][k] = *reinterpret_cast<const bf16x8*>((char*)SA(b, h) + lds_byte(wr * 64 + m * 16 + fr, k * 32 + fq * 8))
; #define LDB(dst, b, h) _Pragma("unroll") for (int n = 0; n < 2; ++n) _Pragma("unroll") for (int k = 0; k < 2; ++k) \
;     dst[n][k] = *reinterpret_cast<const bf16x8*>((char*)SB(b, h) + lds_byte(wc * 32 + n * 16 + fr, k * 32 + fq * 8))
; #define MMA(ai, bj, At_, Bt_) do { __builtin_amdgcn_s_setprio(1); \
;     _Pragma("unroll") for (int m = 0; m < 4; ++m) _Pragma("unroll") for (int n = 0; n < 2; ++n) _Pragma("unroll") for (int k = 0; k < 2; ++k) \
;       acc[ai][bj][m][n] = __builtin_amdgcn_mfma_f32_16x16x32_bf16(At_[m][k], Bt_[n][k], acc[ai][bj][m][n], 0, 0, 0); \
;     __builtin_amdgcn_s_setprio(0); } while (0)
; #define WAIT_V(n) asm volatile("s_waitcnt vmcnt(" #n ")" ::: "memory")
; #define WAIT_L(n) asm volatile("s_waitcnt lgkmcnt(" #n ")" ::: "memory")
; #define BAR __builtin_amdgcn_s_barrier()
; #define SCHED __builtin_amdgcn_sched_barrier(0)
; template <class Epi> ...
;     ...
;     WAIT_V(6); BAR; MMA(1, 1, At, B1); BAR;
;     LDB(B0, 1, 0); SCHED; LDA(At, 1, 0); STAGE(SA(0, 1), A, brow + HALF, t + 2);
;     WAIT_L(8); BAR; WAIT_L(0); MMA(0, 0, At, B0); BAR; SCHED;
;     LDB(B1, 1, 1); STAGE(SB(1, 0), Bt, bcol, t + 3);
;     BAR; WAIT_L(0); MMA(0, 1, At, B1); BAR;
;     LDA(At, 1, 1); STAGE(SA(1, 0), A, brow, t + 3);
	v_mfma_f32_16x16x32_bf16 v[30:33], v[184:187], v[216:219], v[30:33]
	v_mfma_f32_16x16x32_bf16 v[26:29], v[184:187], v[224:227], v[26:29]
	v_mfma_f32_16x16x32_bf16 v[22:25], v[192:195], v[216:219], v[22:25]
	v_mfma_f32_16x16x32_bf16 v[18:21], v[192:195], v[224:227], v[18:21]
	v_mfma_f32_16x16x32_bf16 v[14:17], v[200:203], v[216:219], v[14:17]
	v_mfma_f32_16x16x32_bf16 v[10:13], v[200:203], v[224:227], v[10:13]
	v_mfma_f32_16x16x32_bf16 v[6:9], v[208:211], v[216:219], v[6:9]
	v_mfma_f32_16x16x32_bf16 v[2:5], v[208:211], v[224:227], v[2:5]
	v_mfma_f32_16x16x32_bf16 v[30:33], v[188:191], v[220:223], v[30:33]
	v_mfma_f32_16x16x32_bf16 v[26:29], v[188:191], v[228:231], v[26:29]
	v_mfma_f32_16x16x32_bf16 v[22:25], v[196:199], v[220:223], v[22:25]
	v_mfma_f32_16x16x32_bf16 v[18:21], v[196:199], v[228:231], v[18:21]
	v_mfma_f32_16x16x32_bf16 v[14:17], v[204:207], v[220:223], v[14:17]
	v_mfma_f32_16x16x32_bf16 v[10:13], v[204:207], v[228:231], v[10:13]
	v_mfma_f32_16x16x32_bf16 v[6:9], v[212:215], v[220:223], v[6:9]
	v_mfma_f32_16x16x32_bf16 v[2:5], v[212:215], v[228:231], v[2:5]
	s_barrier
	ds_read_b128 v[156:159], v181
	ds_read_b128 v[160:163], v181 offset:1024
	ds_read_b128 v[164:167], v181 offset:2048
	ds_read_b128 v[168:171], v181 offset:3072
	s_mov_b32 m0, s26
	v_lshl_add_u64 v[216:217], v[172:173], 0, s[44:45]
	ds_read_b128 v[184:187], v176 offset:32768
	ds_read_b128 v[188:191], v176 offset:33792
	ds_read_b128 v[192:195], v177 offset:32768
	ds_read_b128 v[196:199], v177 offset:33792
	ds_read_b128 v[200:203], v178 offset:32768
	ds_read_b128 v[204:207], v178 offset:33792
	ds_read_b128 v[208:211], v179 offset:32768
	ds_read_b128 v[212:215], v179 offset:33792
	global_load_lds_dwordx4 v[216:217], off
	v_lshl_add_u64 v[216:217], v[232:233], 0, s[44:45]
	s_mov_b32 m0, s27
	s_nop 0
	global_load_lds_dwordx4 v[216:217], off
	s_waitcnt lgkmcnt(8)
	s_barrier
	s_waitcnt lgkmcnt(0)
	v_mfma_f32_16x16x32_bf16 v[126:129], v[184:187], v[156:159], v[126:129]
	v_mfma_f32_16x16x32_bf16 v[122:125], v[184:187], v[164:167], v[122:125]
	v_mfma_f32_16x16x32_bf16 v[118:121], v[192:195], v[156:159], v[118:121]
	v_mfma_f32_16x16x32_bf16 v[114:117], v[192:195], v[164:167], v[114:117]
	v_mfma_f32_16x16x32_bf16 v[110:113], v[200:203], v[156:159], v[110:113]
	v_mfma_f32_16x16x32_bf16 v[106:109], v[200:203], v[164:167], v[106:109]
	v_mfma_f32_16x16x32_bf16 v[102:105], v[208:211], v[156:159], v[102:105]
	v_mfma_f32_16x16x32_bf16 v[98:101], v[208:211], v[164:167], v[98:101]
	v_mfma_f32_16x16x32_bf16 v[126:129], v[188:191], v[160:163], v[126:129]
	v_mfma_f32_16x16x32_bf16 v[122:125], v[188:191], v[168:171], v[122:125]
	v_mfma_f32_16x16x32_bf16 v[118:121], v[196:199], v[160:163], v[118:121]
	v_mfma_f32_16x16x32_bf16 v[114:117], v[196:199], v[168:171], v[114:117]
	v_mfma_f32_16x16x32_bf16 v[110:113], v[204:207], v[160:163], v[110:113]
	v_mfma_f32_16x16x32_bf16 v[106:109], v[204:207], v[168:171], v[106:109]
	v_mfma_f32_16x16x32_bf16 v[102:105], v[212:215], v[160:163], v[102:105]
	v_mfma_f32_16x16x32_bf16 v[98:101], v[212:215], v[168:171], v[98:101]
	s_barrier
	s_mov_b32 m0, s14
	v_lshl_add_u64 v[240:241], v[236:237], 0, s[90:91]
	ds_read_b128 v[216:219], v182
	ds_read_b128 v[220:223], v182 offset:1024
	ds_read_b128 v[224:227], v182 offset:2048
	ds_read_b128 v[228:231], v182 offset:3072
	global_load_lds_dwordx4 v[240:241], off
	v_lshl_add_u64 v[240:241], v[238:239], 0, s[90:91]
	s_mov_b32 m0, s15
	s_nop 0
	global_load_lds_dwordx4 v[240:241], off
	s_barrier
	s_waitcnt lgkmcnt(0)
	v_mfma_f32_16x16x32_bf16 v[94:97], v[184:187], v[216:219], v[94:97]
	v_mfma_f32_16x16x32_bf16 v[90:93], v[184:187], v[224:227], v[90:93]
	v_mfma_f32_16x16x32_bf16 v[86:89], v[192:195], v[216:219], v[86:89]
	v_mfma_f32_16x16x32_bf16 v[82:85], v[192:195], v[224:227], v[82:85]
	v_mfma_f32_16x16x32_bf16 v[78:81], v[200:203], v[216:219], v[78:81]
	v_mfma_f32_16x16x32_bf16 v[74:77], v[200:203], v[224:227], v[74:77]
	v_mfma_f32_16x16x32_bf16 v[70:73], v[208:211], v[216:219], v[70:73]
	v_mfma_f32_16x16x32_bf16 v[66:69], v[208:211], v[224:227], v[66:69]
	v_mfma_f32_16x16x32_bf16 v[94:97], v[188:191], v[220:223], v[94:97]
	v_mfma_f32_16x16x32_bf16 v[90:93], v[188:191], v[228:231], v[90:93]
	v_mfma_f32_16x16x32_bf16 v[86:89], v[196:199], v[220:223], v[86:89]
	v_mfma_f32_16x16x32_bf16 v[82:85], v[196:199], v[228:231], v[82:85]
	v_mfma_f32_16x16x32_bf16 v[78:81], v[204:207], v[220:223], v[78:81]
	v_mfma_f32_16x16x32_bf16 v[74:77], v[204:207], v[228:231], v[74:77]
	v_mfma_f32_16x16x32_bf16 v[70:73], v[212:215], v[220:223], v[70:73]
	v_mfma_f32_16x16x32_bf16 v[66:69], v[212:215], v[228:231], v[66:69]
	s_mov_b32 m0, s28
	v_lshl_add_u64 v[172:173], v[172:173], 0, s[90:91]
	s_barrier
	ds_read_b128 v[184:187], v176 offset:49152
	ds_read_b128 v[188:191], v176 offset:50176
	ds_read_b128 v[192:195], v177 offset:49152
	ds_read_b128 v[196:199], v177 offset:50176
	ds_read_b128 v[200:203], v178 offset:49152
	ds_read_b128 v[204:207], v178 offset:50176
	ds_read_b128 v[208:211], v179 offset:49152
	ds_read_b128 v[212:215], v179 offset:50176
	global_load_lds_dwordx4 v[172:173], off
	v_lshl_add_u64 v[172:173], v[232:233], 0, s[90:91]
	s_mov_b32 m0, s29
	s_nop 0
	global_load_lds_dwordx4 v[172:173], off
	s_barrier
; #define STAGE(P, BASE, br, kt) do { const char* _gb = (const char*)((BASE) + ((long)(br) * K + (long)(kt) * BK)); \
;     __builtin_amdgcn_global_load_lds((const unsigned*)(_gb + (size_t)so0), (unsigned*)((char*)(P) + wv1k), 16, 0, 0); \
;     __builtin_amdgcn_global_load_lds((const unsigned*)(_gb + (size_t)so1), (unsigned*)((char*)(P) + wv1k + 8192), 16, 0, 0); } while (0)
; #define LDA(dst, b, h) _Pragma("unroll") for (int m = 0; m < 4; ++m) _Pragma("unroll") for (int k = 0; k < 2; ++k) \
;     dst[m][k] = *reinterpret_cast<const bf16x8*>((char*)SA(b, h) + lds_byte(wr * 64 + m * 16 + fr, k * 32 + fq * 8))
; #define LDB(dst, b, h) _Pragma("unroll") for (int n = 0; n < 2; ++n) _Pragma("unroll") for (int k = 0; k < 2; ++k) \
;     dst[n][k] = *reinterpret_cast<const bf16x8*>((char*)SB(b, h) + lds_byte(wc * 32 + n * 16 + fr, k * 32 + fq * 8))
; #define MMA(ai, bj, At_, Bt_) do { __builtin_amdgcn_s_setprio(1); \
;     _Pragma("unroll") for (int m = 0; m < 4; ++m) _Pragma("unroll") for (int n = 0; n < 2; ++n) _Pragma("unroll") for (int k = 0; k < 2; ++k) \
;       acc[ai][bj][m][n] = __builtin_amdgcn_mfma_f32_16x16x32_bf16(At_[m][k], Bt_[n][k], acc[ai][bj][m][n], 0, 0, 0); \
;     __builtin_amdgcn_s_setprio(0); } while (0)
; #define WAIT_V(n) asm volatile("s_waitcnt vmcnt(" #n ")" ::: "memory")
; #define WAIT_L(n) asm volatile("s_waitcnt lgkmcnt(" #n ")" ::: "memory")
; #define BAR __builtin_amdgcn_s_barrier()
; #define SCHED __builtin_amdgcn_sched_barrier(0)
; template <class Epi> ...
;     ...
;     BAR; WAIT_L(0); MMA(1, 0, At, B0); BAR; SCHED;
;     STAGE(SB(1, 1), Bt, bcol + HALF, t + 3);
;     WAIT_V(6); BAR; MMA(1, 1, At, B1); BAR;
;   }
;   { LDB(B0, 0, 0); LDA(At, 0, 0); STAGE(SA(1, 1), A, brow + HALF, nt - 1);
;     BAR; WAIT_L(0); MMA(0, 0, At, B0); BAR;
;     LDB(B1, 0, 1); BAR; WAIT_L(0); MMA(0, 1, At, B1); BAR;
	s_waitcnt lgkmcnt(0)
	v_mfma_f32_16x16x32_bf16 v[62:65], v[184:187], v[156:159], v[62:65]
	v_mfma_f32_16x16x32_bf16 v[58:61], v[184:187], v[164:167], v[58:61]
	v_mfma_f32_16x16x32_bf16 v[54:57], v[192:195], v[156:159], v[54:57]
	v_mfma_f32_16x16x32_bf16 v[50:53], v[192:195], v[164:167], v[50:53]
	v_mfma_f32_16x16x32_bf16 v[46:49], v[200:203], v[156:159], v[46:49]
	v_mfma_f32_16x16x32_bf16 v[42:45], v[200:203], v[164:167], v[42:45]
	v_mfma_f32_16x16x32_bf16 v[38:41], v[208:211], v[156:159], v[38:41]
	v_mfma_f32_16x16x32_bf16 v[34:37], v[208:211], v[164:167], v[34:37]
	v_mfma_f32_16x16x32_bf16 v[62:65], v[188:191], v[160:163], v[62:65]
	v_mfma_f32_16x16x32_bf16 v[58:61], v[188:191], v[168:171], v[58:61]
	v_mfma_f32_16x16x32_bf16 v[54:57], v[196:199], v[160:163], v[54:57]
	v_mfma_f32_16x16x32_bf16 v[50:53], v[196:199], v[168:171], v[50:53]
	v_mfma_f32_16x16x32_bf16 v[46:49], v[204:207], v[160:163], v[46:49]
	v_mfma_f32_16x16x32_bf16 v[42:45], v[204:207], v[168:171], v[42:45]
	v_mfma_f32_16x16x32_bf16 v[38:41], v[212:215], v[160:163], v[38:41]
	v_mfma_f32_16x16x32_bf16 v[34:37], v[212:215], v[168:171], v[34:37]
	s_barrier
	s_mov_b32 m0, s38
	v_lshl_add_u64 v[156:157], v[236:237], 0, s[46:47]
	global_load_lds_dwordx4 v[156:157], off
	v_lshl_add_u64 v[156:157], v[238:239], 0, s[46:47]
	s_mov_b32 m0, s39
	s_nop 0
	global_load_lds_dwordx4 v[156:157], off
	s_waitcnt vmcnt(6)
	s_barrier
	v_mfma_f32_16x16x32_bf16 v[30:33], v[184:187], v[216:219], v[30:33]
	v_mfma_f32_16x16x32_bf16 v[26:29], v[184:187], v[224:227], v[26:29]
	v_mfma_f32_16x16x32_bf16 v[22:25], v[192:195], v[216:219], v[22:25]
	v_mfma_f32_16x16x32_bf16 v[18:21], v[192:195], v[224:227], v[18:21]
	v_mfma_f32_16x16x32_bf16 v[14:17], v[200:203], v[216:219], v[14:17]
	v_mfma_f32_16x16x32_bf16 v[10:13], v[200:203], v[224:227], v[10:13]
	v_mfma_f32_16x16x32_bf16 v[6:9], v[208:211], v[216:219], v[6:9]
	v_mfma_f32_16x16x32_bf16 v[2:5], v[208:211], v[224:227], v[2:5]
	v_mfma_f32_16x16x32_bf16 v[30:33], v[188:191], v[220:223], v[30:33]
	v_mfma_f32_16x16x32_bf16 v[26:29], v[188:191], v[228:231], v[26:29]
	v_mfma_f32_16x16x32_bf16 v[22:25], v[196:199], v[220:223], v[22:25]
	v_mfma_f32_16x16x32_bf16 v[18:21], v[196:199], v[228:231], v[18:21]
	v_mfma_f32_16x16x32_bf16 v[14:17], v[204:207], v[220:223], v[14:17]
	v_mfma_f32_16x16x32_bf16 v[10:13], v[204:207], v[228:231], v[10:13]
	v_mfma_f32_16x16x32_bf16 v[6:9], v[212:215], v[220:223], v[6:9]
	v_mfma_f32_16x16x32_bf16 v[2:5], v[212:215], v[228:231], v[2:5]
	s_add_i32 s10, s10, 2
	s_add_u32 s8, s8, 0x100
	s_addc_u32 s9, s9, 0
	s_cmp_lt_u32 s10, 12
	s_barrier
	s_cbranch_scc1 .LBB0_449
	s_mov_b64 s[8:9], 0x780
	s_mov_b32 m0, s40
	v_lshl_add_u64 v[142:143], v[142:143], 0, s[8:9]
	ds_read_b128 v[146:149], v175
	ds_read_b128 v[152:155], v175 offset:1024
	ds_read_b128 v[156:159], v175 offset:2048
	ds_read_b128 v[160:163], v175 offset:3072
	ds_read_b128 v[164:167], v176
	ds_read_b128 v[168:171], v176 offset:1024
	ds_read_b128 v[184:187], v177
	ds_read_b128 v[188:191], v177 offset:1024
	ds_read_b128 v[192:195], v178
	ds_read_b128 v[196:199], v178 offset:1024
	ds_read_b128 v[200:203], v179
	ds_read_b128 v[204:207], v179 offset:1024
	global_load_lds_dwordx4 v[142:143], off
	v_lshl_add_u64 v[142:143], v[144:145], 0, s[8:9]
	s_mov_b32 m0, s11
	s_nop 0
	global_load_lds_dwordx4 v[142:143], off
	s_barrier
	s_waitcnt lgkmcnt(0)
	v_mfma_f32_16x16x32_bf16 v[126:129], v[164:167], v[146:149], v[126:129]
	v_mfma_f32_16x16x32_bf16 v[122:125], v[164:167], v[156:159], v[122:125]
	v_mfma_f32_16x16x32_bf16 v[110:113], v[192:195], v[146:149], v[110:113]
	v_mfma_f32_16x16x32_bf16 v[106:109], v[192:195], v[156:159], v[106:109]
	v_mfma_f32_16x16x32_bf16 v[126:129], v[168:171], v[152:155], v[126:129]
	v_mfma_f32_16x16x32_bf16 v[122:125], v[168:171], v[160:163], v[122:125]
	v_mfma_f32_16x16x32_bf16 v[118:121], v[184:187], v[146:149], v[118:121]
	v_mfma_f32_16x16x32_bf16 v[114:117], v[184:187], v[156:159], v[114:117]
	v_mfma_f32_16x16x32_bf16 v[110:113], v[196:199], v[152:155], v[110:113]
	v_mfma_f32_16x16x32_bf16 v[106:109], v[196:199], v[160:163], v[106:109]
	v_mfma_f32_16x16x32_bf16 v[102:105], v[200:203], v[146:149], v[102:105]
	v_mfma_f32_16x16x32_bf16 v[98:101], v[200:203], v[156:159], v[98:101]
	v_mfma_f32_16x16x32_bf16 v[142:145], v[188:191], v[152:155], v[118:121]
	v_mfma_f32_16x16x32_bf16 v[208:211], v[188:191], v[160:163], v[114:117]
	v_mfma_f32_16x16x32_bf16 v[212:215], v[204:207], v[152:155], v[102:105]
	v_mfma_f32_16x16x32_bf16 v[216:219], v[204:207], v[160:163], v[98:101]
	s_barrier
	s_nop 1
	ds_read_b128 v[98:101], v180
	ds_read_b128 v[102:105], v180 offset:1024
	ds_read_b128 v[114:117], v180 offset:2048
	ds_read_b128 v[118:121], v180 offset:3072
	s_barrier
	s_waitcnt lgkmcnt(0)
	v_mfma_f32_16x16x32_bf16 v[94:97], v[164:167], v[98:101], v[94:97]
	v_mfma_f32_16x16x32_bf16 v[90:93], v[164:167], v[114:117], v[90:93]
	v_mfma_f32_16x16x32_bf16 v[78:81], v[192:195], v[98:101], v[78:81]
	v_mfma_f32_16x16x32_bf16 v[74:77], v[192:195], v[114:117], v[74:77]
	v_mfma_f32_16x16x32_bf16 v[94:97], v[168:171], v[102:105], v[94:97]
	v_mfma_f32_16x16x32_bf16 v[90:93], v[168:171], v[118:121], v[90:93]
	v_mfma_f32_16x16x32_bf16 v[86:89], v[184:187], v[98:101], v[86:89]
	v_mfma_f32_16x16x32_bf16 v[82:85], v[184:187], v[114:117], v[82:85]
	v_mfma_f32_16x16x32_bf16 v[78:81], v[196:199], v[102:105], v[78:81]
	v_mfma_f32_16x16x32_bf16 v[74:77], v[196:199], v[118:121], v[74:77]
	v_mfma_f32_16x16x32_bf16 v[70:73], v[200:203], v[98:101], v[70:73]
	v_mfma_f32_16x16x32_bf16 v[66:69], v[200:203], v[114:117], v[66:69]
	v_mfma_f32_16x16x32_bf16 v[164:167], v[188:191], v[102:105], v[86:89]
	v_mfma_f32_16x16x32_bf16 v[168:171], v[188:191], v[118:121], v[82:85]
	v_mfma_f32_16x16x32_bf16 v[184:187], v[204:207], v[102:105], v[70:73]
	v_mfma_f32_16x16x32_bf16 v[188:191], v[204:207], v[118:121], v[66:69]
	s_barrier
; #define LDA(dst, b, h) _Pragma("unroll") for (int m = 0; m < 4; ++m) _Pragma("unroll") for (int k = 0; k < 2; ++k) \
;     dst[m][k] = *reinterpret_cast<const bf16x8*>((char*)SA(b, h) + lds_byte(wr * 64 + m * 16 + fr, k * 32 + fq * 8))
; #define LDB(dst, b, h) _Pragma("unroll") for (int n = 0; n < 2; ++n) _Pragma("unroll") for (int k = 0; k < 2; ++k) \
;     dst[n][k] = *reinterpret_cast<const bf16x8*>((char*)SB(b, h) + lds_byte(wc * 32 + n * 16 + fr, k * 32 + fq * 8))
; #define MMA(ai, bj, At_, Bt_) do { __builtin_amdgcn_s_setprio(1); \
;     _Pragma("unroll") for (int m = 0; m < 4; ++m) _Pragma("unroll") for (int n = 0; n < 2; ++n) _Pragma("unroll") for (int k = 0; k < 2; ++k) \
;       acc[ai][bj][m][n] = __builtin_amdgcn_mfma_f32_16x16x32_bf16(At_[m][k], Bt_[n][k], acc[ai][bj][m][n], 0, 0, 0); \
;     __builtin_amdgcn_s_setprio(0); } while (0)
; #define WAIT_V(n) asm volatile("s_waitcnt vmcnt(" #n ")" ::: "memory")
; #define WAIT_L(n) asm volatile("s_waitcnt lgkmcnt(" #n ")" ::: "memory")
; #define BAR __builtin_amdgcn_s_barrier()
; template <class Epi> ...
;     ...
;     LDA(At, 0, 1); WAIT_V(4); BAR; WAIT_L(0); MMA(1, 0, At, B0); MMA(1, 1, At, B1); BAR; }
;   { LDB(B0, 1, 0); LDA(At, 1, 0); WAIT_V(2); BAR; WAIT_L(0); MMA(0, 0, At, B0); BAR;
	s_nop 1
	ds_read_b128 v[66:69], v176 offset:16384
	ds_read_b128 v[70:73], v176 offset:17408
	ds_read_b128 v[82:85], v177 offset:16384
	ds_read_b128 v[86:89], v177 offset:17408
	ds_read_b128 v[192:195], v178 offset:16384
	ds_read_b128 v[196:199], v178 offset:17408
	ds_read_b128 v[200:203], v179 offset:16384
	ds_read_b128 v[204:207], v179 offset:17408
	s_waitcnt vmcnt(4)
	s_barrier
	s_waitcnt lgkmcnt(0)
	v_mfma_f32_16x16x32_bf16 v[62:65], v[66:69], v[146:149], v[62:65]
	v_mfma_f32_16x16x32_bf16 v[58:61], v[66:69], v[156:159], v[58:61]
	v_mfma_f32_16x16x32_bf16 v[46:49], v[192:195], v[146:149], v[46:49]
	v_mfma_f32_16x16x32_bf16 v[42:45], v[192:195], v[156:159], v[42:45]
	v_mfma_f32_16x16x32_bf16 v[62:65], v[70:73], v[152:155], v[62:65]
	v_mfma_f32_16x16x32_bf16 v[58:61], v[70:73], v[160:163], v[58:61]
	v_mfma_f32_16x16x32_bf16 v[54:57], v[82:85], v[146:149], v[54:57]
	v_mfma_f32_16x16x32_bf16 v[50:53], v[82:85], v[156:159], v[50:53]
	v_mfma_f32_16x16x32_bf16 v[46:49], v[196:199], v[152:155], v[46:49]
	v_mfma_f32_16x16x32_bf16 v[42:45], v[196:199], v[160:163], v[42:45]
	v_mfma_f32_16x16x32_bf16 v[38:41], v[200:203], v[146:149], v[38:41]
	v_mfma_f32_16x16x32_bf16 v[34:37], v[200:203], v[156:159], v[34:37]
	v_mfma_f32_16x16x32_bf16 v[220:223], v[86:89], v[152:155], v[54:57]
	v_mfma_f32_16x16x32_bf16 v[224:227], v[86:89], v[160:163], v[50:53]
	v_mfma_f32_16x16x32_bf16 v[146:149], v[204:207], v[152:155], v[38:41]
	v_mfma_f32_16x16x32_bf16 v[152:155], v[204:207], v[160:163], v[34:37]
	v_mfma_f32_16x16x32_bf16 v[30:33], v[66:69], v[98:101], v[30:33]
	v_mfma_f32_16x16x32_bf16 v[26:29], v[66:69], v[114:117], v[26:29]
	v_mfma_f32_16x16x32_bf16 v[14:17], v[192:195], v[98:101], v[14:17]
	v_mfma_f32_16x16x32_bf16 v[10:13], v[192:195], v[114:117], v[10:13]
	v_mfma_f32_16x16x32_bf16 v[30:33], v[70:73], v[102:105], v[30:33]
	v_mfma_f32_16x16x32_bf16 v[26:29], v[70:73], v[118:121], v[26:29]
	v_mfma_f32_16x16x32_bf16 v[22:25], v[82:85], v[98:101], v[22:25]
	v_mfma_f32_16x16x32_bf16 v[18:21], v[82:85], v[114:117], v[18:21]
	v_mfma_f32_16x16x32_bf16 v[14:17], v[196:199], v[102:105], v[14:17]
	v_mfma_f32_16x16x32_bf16 v[10:13], v[196:199], v[118:121], v[10:13]
	v_mfma_f32_16x16x32_bf16 v[6:9], v[200:203], v[98:101], v[6:9]
	v_mfma_f32_16x16x32_bf16 v[2:5], v[200:203], v[114:117], v[2:5]
	v_mfma_f32_16x16x32_bf16 v[156:159], v[86:89], v[102:105], v[22:25]
	v_mfma_f32_16x16x32_bf16 v[160:163], v[86:89], v[118:121], v[18:21]
	v_mfma_f32_16x16x32_bf16 v[192:195], v[204:207], v[102:105], v[6:9]
	v_mfma_f32_16x16x32_bf16 v[196:199], v[204:207], v[118:121], v[2:5]
	s_barrier
	s_nop 1
	ds_read_b128 v[2:5], v181
	ds_read_b128 v[6:9], v181 offset:1024
	ds_read_b128 v[200:203], v181 offset:2048
	ds_read_b128 v[204:207], v181 offset:3072
	ds_read_b128 v[18:21], v176 offset:32768
	ds_read_b128 v[22:25], v176 offset:33792
	ds_read_b128 v[34:37], v177 offset:32768
	ds_read_b128 v[38:41], v177 offset:33792
	ds_read_b128 v[50:53], v178 offset:32768
	ds_read_b128 v[54:57], v178 offset:33792
	ds_read_b128 v[228:231], v179 offset:32768
	ds_read_b128 v[236:239], v179 offset:33792
	s_waitcnt vmcnt(2)
	s_barrier
	s_waitcnt lgkmcnt(0)
	v_mfma_f32_16x16x32_bf16 v[66:69], v[18:21], v[2:5], v[126:129]
	v_mfma_f32_16x16x32_bf16 v[118:121], v[22:25], v[6:9], v[66:69]
	v_mfma_f32_16x16x32_bf16 v[66:69], v[18:21], v[200:203], v[122:125]
	v_mfma_f32_16x16x32_bf16 v[114:117], v[22:25], v[204:207], v[66:69]
	v_mfma_f32_16x16x32_bf16 v[66:69], v[34:37], v[2:5], v[142:145]
	v_mfma_f32_16x16x32_bf16 v[102:105], v[38:41], v[6:9], v[66:69]
	v_mfma_f32_16x16x32_bf16 v[66:69], v[34:37], v[200:203], v[208:211]
	v_mfma_f32_16x16x32_bf16 v[98:101], v[38:41], v[204:207], v[66:69]
	v_mfma_f32_16x16x32_bf16 v[66:69], v[50:53], v[2:5], v[110:113]
	v_mfma_f32_16x16x32_bf16 v[86:89], v[54:57], v[6:9], v[66:69]
	v_mfma_f32_16x16x32_bf16 v[66:69], v[50:53], v[200:203], v[106:109]
	v_mfma_f32_16x16x32_bf16 v[82:85], v[54:57], v[204:207], v[66:69]
	v_mfma_f32_16x16x32_bf16 v[66:69], v[228:231], v[2:5], v[212:215]
	v_mfma_f32_16x16x32_bf16 v[70:73], v[236:239], v[6:9], v[66:69]
	v_mfma_f32_16x16x32_bf16 v[66:69], v[228:231], v[200:203], v[216:219]
	v_mfma_f32_16x16x32_bf16 v[66:69], v[236:239], v[204:207], v[66:69]
	s_barrier
; #define LDA(dst, b, h) _Pragma("unroll") for (int m = 0; m < 4; ++m) _Pragma("unroll") for (int k = 0; k < 2; ++k) \
;     dst[m][k] = *reinterpret_cast<const bf16x8*>((char*)SA(b, h) + lds_byte(wr * 64 + m * 16 + fr, k * 32 + fq * 8))
; #define LDB(dst, b, h) _Pragma("unroll") for (int n = 0; n < 2; ++n) _Pragma("unroll") for (int k = 0; k < 2; ++k) \
;     dst[n][k] = *reinterpret_cast<const bf16x8*>((char*)SB(b, h) + lds_byte(wc * 32 + n * 16 + fr, k * 32 + fq * 8))
; #define MMA(ai, bj, At_, Bt_) do { __builtin_amdgcn_s_setprio(1); \
;     _Pragma("unroll") for (int m = 0; m < 4; ++m) _Pragma("unroll") for (int n = 0; n < 2; ++n) _Pragma("unroll") for (int k = 0; k < 2; ++k) \
;       acc[ai][bj][m][n] = __builtin_amdgcn_mfma_f32_16x16x32_bf16(At_[m][k], Bt_[n][k], acc[ai][bj][m][n], 0, 0, 0); \
;     __builtin_amdgcn_s_setprio(0); } while (0)
; #define WAIT_V(n) asm volatile("s_waitcnt vmcnt(" #n ")" ::: "memory")
; #define WAIT_L(n) asm volatile("s_waitcnt lgkmcnt(" #n ")" ::: "memory")
; #define BAR __builtin_amdgcn_s_barrier()
; template <class Epi> ...
;     ...
;     LDB(B1, 1, 1); WAIT_V(0); BAR; WAIT_L(0); MMA(0, 1, At, B1); BAR;
;     LDA(At, 1, 1); BAR; WAIT_L(0); MMA(1, 0, At, B0); MMA(1, 1, At, B1); BAR; }
;   if (wr == 0) BAR;
	ds_read_b128 v[142:145], v182
	ds_read_b128 v[208:211], v182 offset:1024
	ds_read_b128 v[212:215], v182 offset:2048
	ds_read_b128 v[216:219], v182 offset:3072
	s_waitcnt vmcnt(0)
	s_barrier
	s_waitcnt lgkmcnt(0)
	v_mfma_f32_16x16x32_bf16 v[94:97], v[18:21], v[142:145], v[94:97]
	v_mfma_f32_16x16x32_bf16 v[18:21], v[18:21], v[212:215], v[90:93]
	v_mfma_f32_16x16x32_bf16 v[122:125], v[22:25], v[216:219], v[18:21]
	v_mfma_f32_16x16x32_bf16 v[18:21], v[34:37], v[142:145], v[164:167]
	v_mfma_f32_16x16x32_bf16 v[110:113], v[38:41], v[208:211], v[18:21]
	v_mfma_f32_16x16x32_bf16 v[18:21], v[34:37], v[212:215], v[168:171]
	v_mfma_f32_16x16x32_bf16 v[106:109], v[38:41], v[216:219], v[18:21]
	v_mfma_f32_16x16x32_bf16 v[18:21], v[50:53], v[142:145], v[78:81]
	v_mfma_f32_16x16x32_bf16 v[126:129], v[22:25], v[208:211], v[94:97]
	v_mfma_f32_16x16x32_bf16 v[94:97], v[54:57], v[208:211], v[18:21]
	v_mfma_f32_16x16x32_bf16 v[18:21], v[50:53], v[212:215], v[74:77]
	v_mfma_f32_16x16x32_bf16 v[90:93], v[54:57], v[216:219], v[18:21]
	v_mfma_f32_16x16x32_bf16 v[18:21], v[228:231], v[142:145], v[184:187]
	v_mfma_f32_16x16x32_bf16 v[78:81], v[236:239], v[208:211], v[18:21]
	v_mfma_f32_16x16x32_bf16 v[18:21], v[228:231], v[212:215], v[188:191]
	v_mfma_f32_16x16x32_bf16 v[74:77], v[236:239], v[216:219], v[18:21]
	s_barrier
	ds_read_b128 v[164:167], v176 offset:49152
	ds_read_b128 v[168:171], v176 offset:50176
	ds_read_b128 v[184:187], v177 offset:49152
	ds_read_b128 v[188:191], v177 offset:50176
	ds_read_b128 v[228:231], v178 offset:49152
	ds_read_b128 v[236:239], v178 offset:50176
	ds_read_b128 v[240:243], v179 offset:49152
	ds_read_b128 v[244:247], v179 offset:50176
	s_barrier
	s_waitcnt lgkmcnt(0)
	v_mfma_f32_16x16x32_bf16 v[18:21], v[164:167], v[2:5], v[62:65]
	v_mfma_f32_16x16x32_bf16 v[54:57], v[168:171], v[6:9], v[18:21]
	v_mfma_f32_16x16x32_bf16 v[18:21], v[164:167], v[200:203], v[58:61]
	v_mfma_f32_16x16x32_bf16 v[50:53], v[168:171], v[204:207], v[18:21]
	v_mfma_f32_16x16x32_bf16 v[18:21], v[184:187], v[2:5], v[220:223]
	v_mfma_f32_16x16x32_bf16 v[38:41], v[188:191], v[6:9], v[18:21]
	v_mfma_f32_16x16x32_bf16 v[18:21], v[184:187], v[200:203], v[224:227]
	v_mfma_f32_16x16x32_bf16 v[34:37], v[188:191], v[204:207], v[18:21]
	v_mfma_f32_16x16x32_bf16 v[18:21], v[228:231], v[2:5], v[46:49]
	v_mfma_f32_16x16x32_bf16 v[2:5], v[240:243], v[2:5], v[146:149]
	v_mfma_f32_16x16x32_bf16 v[22:25], v[236:239], v[6:9], v[18:21]
	v_mfma_f32_16x16x32_bf16 v[18:21], v[228:231], v[200:203], v[42:45]
	v_mfma_f32_16x16x32_bf16 v[6:9], v[244:247], v[6:9], v[2:5]
	v_mfma_f32_16x16x32_bf16 v[2:5], v[240:243], v[200:203], v[152:155]
	v_mfma_f32_16x16x32_bf16 v[18:21], v[236:239], v[204:207], v[18:21]
	v_mfma_f32_16x16x32_bf16 v[2:5], v[244:247], v[204:207], v[2:5]
	v_mfma_f32_16x16x32_bf16 v[26:29], v[164:167], v[212:215], v[26:29]
	v_mfma_f32_16x16x32_bf16 v[58:61], v[168:171], v[216:219], v[26:29]
	v_mfma_f32_16x16x32_bf16 v[26:29], v[184:187], v[142:145], v[156:159]
	v_mfma_f32_16x16x32_bf16 v[46:49], v[188:191], v[208:211], v[26:29]
	v_mfma_f32_16x16x32_bf16 v[26:29], v[184:187], v[212:215], v[160:163]
	v_mfma_f32_16x16x32_bf16 v[10:13], v[228:231], v[212:215], v[10:13]
	v_mfma_f32_16x16x32_bf16 v[30:33], v[164:167], v[142:145], v[30:33]
	v_mfma_f32_16x16x32_bf16 v[42:45], v[188:191], v[216:219], v[26:29]
	v_mfma_f32_16x16x32_bf16 v[14:17], v[228:231], v[142:145], v[14:17]
	v_mfma_f32_16x16x32_bf16 v[26:29], v[236:239], v[216:219], v[10:13]
	v_mfma_f32_16x16x32_bf16 v[10:13], v[240:243], v[142:145], v[192:195]
	v_mfma_f32_16x16x32_bf16 v[62:65], v[168:171], v[208:211], v[30:33]
	v_mfma_f32_16x16x32_bf16 v[30:33], v[236:239], v[208:211], v[14:17]
	v_mfma_f32_16x16x32_bf16 v[14:17], v[244:247], v[208:211], v[10:13]
	v_mfma_f32_16x16x32_bf16 v[10:13], v[240:243], v[212:215], v[196:199]
	v_mfma_f32_16x16x32_bf16 v[10:13], v[244:247], v[216:219], v[10:13]
	s_barrier
	s_and_saveexec_b64 s[8:9], s[6:7]
	s_cbranch_execz .LBB0_452
	s_barrier
